# v40 stack + first K-iteration of each GEMM unit peeled with inline-zero SrcC (accumulator zeroing removed)
# baseline (speedup 1.0000x reference)
; #define PG8_LDA(dst, b, h) do { if constexpr (FP8) { _Pragma("unroll") for (int m = 0; m < 4; ++m) dst##8[m] = PG8_LD8(PG8_SA(b, h), aoff, aoff1, m); } \
;         else { _Pragma("unroll") for (int m = 0; m < 4; ++m) _Pragma("unroll") for (int k = 0; k < 2; ++k) dst[m][k] = *(const LAS bf16x8*)(lds + PG8_SA(b, h) + (k ? aoff1 : aoff) + m * 2048); } } while (0)
; #define PG8_LDB(dst, b, h) do { if constexpr (FP8) { dst##8[0] = PG8_LD8(PG8_SB(b, h), boff, boff1, 0); dst##8[1] = PG8_LD8(PG8_SB(b, h), boff, boff1, 1); } \
;         else { _Pragma("unroll") for (int n = 0; n < 2; ++n) _Pragma("unroll") for (int k = 0; k < 2; ++k) dst[n][k] = *(const LAS bf16x8*)(lds + PG8_SB(b, h) + (k ? boff1 : boff) + n * 2048); } } while (0)
; #define PG8_WAIT_V(n) asm volatile("s_waitcnt vmcnt(" #n ")" ::: "memory")
; #define PG8_WAIT_L(n) asm volatile("s_waitcnt lgkmcnt(" #n ")" ::: "memory")
; #define PG8_BAR __builtin_amdgcn_s_barrier()
; #define PG8_SCHED __builtin_amdgcn_sched_barrier(0)
; #define PG8_S1 PG8_STAGE(PG8_SA(1, 1), a1 + hstepA, voffA)
; #define PG8_S2 do { PG8_STAGE(PG8_SB(0, 0), b2, voffB); PG8_STAGE(PG8_SB(0, 1), b2 + hstepB, voffB); PG8_STAGE(PG8_SA(0, 0), a2, voffA); } while (0)
; template <class Epi, class SchedT, bool ALIGN_EPI, bool SP2, bool FP8 = false>
; __device__ __forceinline__ void gemm_phase(LAS unsigned char* lds, const Gemm g, const SchedT& S, const Epi& E, const int wid) {
;     ...
;             PG8_LDB(B0, 0, 0); PG8_LDB(B1, 0, 1); PG8_SCHED; PG8_LDA(At, 0, 0); PG8_S1;
;             PG8_WAIT_V(8); PG8_WAIT_L(0); PG8_BAR; PG8_MMAP(0, 0, 0); PG8_BAR; PG8_SCHED;
;             PG8_LDA(At, 0, 1); PG8_S2;
;             PG8_WAIT_V(8); PG8_WAIT_L(0); PG8_BAR; PG8_MMAP(1, 0, 1); PG8_BAR; PG8_SCHED;
.LBB0_237:
	s_ashr_i32 s47, s46, 31
	s_lshl_b64 s[8:9], s[46:47], 18
	s_add_u32 s50, s4, s8
	s_addc_u32 s51, s5, s9
	s_cmp_lt_i32 s22, 1
	s_cbranch_scc1 .LBB0_245
	s_and_b64 s[8:9], s[68:69], exec
	s_cselect_b32 s8, s51, s67
	s_cselect_b32 s9, s50, s66
	s_add_i32 s20, s22, -2
	s_add_u32 s52, s52, 0x90080
	s_addc_u32 s53, s53, 0
	s_add_u32 s21, s66, 0x100
	s_addc_u32 s24, s67, 0
	s_mov_b32 s31, 0
	ds_read_b128 v[130:133], v143
	ds_read_b128 v[134:137], v143 offset:16
	ds_read_b128 v[148:151], v143 offset:2048
	ds_read_b128 v[152:155], v143 offset:2064
	ds_read_b128 v[156:159], v144
	ds_read_b128 v[160:163], v144 offset:16
	ds_read_b128 v[164:167], v144 offset:2048
	ds_read_b128 v[168:171], v144 offset:2064
	s_add_i32 s30, s31, 2
	s_add_u32 s6, s52, 0xfff70080
	s_addc_u32 s7, s53, -1
	s_cmp_eq_u32 s20, s31
	s_cselect_b32 s67, s49, s7
	s_cselect_b32 s66, s48, s6
	v_mov_b32_e32 v128, v138
	ds_read_b128 v[172:175], v145
	ds_read_b128 v[176:179], v145 offset:16
	ds_read_b128 v[180:183], v145 offset:2048
	ds_read_b128 v[184:187], v145 offset:2064
	ds_read_b128 v[188:191], v145 offset:4096
	ds_read_b128 v[192:195], v145 offset:4112
	ds_read_b128 v[196:199], v145 offset:6144
	ds_read_b128 v[200:203], v145 offset:6160
	s_cselect_b32 s69, s8, s24
	s_cselect_b32 s68, s9, s21
	s_add_i32 m0, s87, 0xc000
	s_nop 0
	global_load_lds_dwordx4 v128, s[52:53]
	v_mov_b32_e32 v128, v140
	s_add_i32 m0, s87, 0xe000
	s_nop 0
	global_load_lds_dwordx4 v128, s[52:53]
	s_waitcnt vmcnt(8)
	s_waitcnt lgkmcnt(0)
	s_barrier
	s_setprio 1
	s_waitcnt lgkmcnt(0)
	v_mfma_scale_f32_16x16x128_f8f6f4 v[124:127], v[130:137], v[172:179], 0, v146, v146 op_sel_hi:[0,0,0]
	v_mfma_scale_f32_16x16x128_f8f6f4 v[108:111], v[156:163], v[172:179], 0, v146, v146 op_sel_hi:[0,0,0]
	v_mfma_scale_f32_16x16x128_f8f6f4 v[120:123], v[148:155], v[172:179], 0, v146, v146 op_sel_hi:[0,0,0]
	v_mfma_scale_f32_16x16x128_f8f6f4 v[100:103], v[164:171], v[172:179], 0, v146, v146 op_sel_hi:[0,0,0]
	v_mfma_scale_f32_16x16x128_f8f6f4 v[116:119], v[130:137], v[180:187], 0, v146, v146 op_sel_hi:[0,0,0]
	v_mfma_scale_f32_16x16x128_f8f6f4 v[112:115], v[148:155], v[180:187], 0, v146, v146 op_sel_hi:[0,0,0]
	v_mfma_scale_f32_16x16x128_f8f6f4 v[104:107], v[130:137], v[188:195], 0, v146, v146 op_sel_hi:[0,0,0]
	v_mfma_scale_f32_16x16x128_f8f6f4 v[60:63], v[164:171], v[196:203], 0, v146, v146 op_sel_hi:[0,0,0]
	v_mfma_scale_f32_16x16x128_f8f6f4 v[172:175], v[156:163], v[180:187], 0, v146, v146 op_sel_hi:[0,0,0]
	v_mfma_scale_f32_16x16x128_f8f6f4 v[176:179], v[164:171], v[180:187], 0, v146, v146 op_sel_hi:[0,0,0]
	v_mfma_scale_f32_16x16x128_f8f6f4 v[180:183], v[156:163], v[188:195], 0, v146, v146 op_sel_hi:[0,0,0]
	v_mfma_scale_f32_16x16x128_f8f6f4 v[184:187], v[148:155], v[188:195], 0, v146, v146 op_sel_hi:[0,0,0]
	v_mfma_scale_f32_16x16x128_f8f6f4 v[188:191], v[164:171], v[188:195], 0, v146, v146 op_sel_hi:[0,0,0]
	v_mfma_scale_f32_16x16x128_f8f6f4 v[192:195], v[130:137], v[196:203], 0, v146, v146 op_sel_hi:[0,0,0]
	v_mfma_scale_f32_16x16x128_f8f6f4 v[204:207], v[156:163], v[196:203], 0, v146, v146 op_sel_hi:[0,0,0]
	v_mfma_scale_f32_16x16x128_f8f6f4 v[208:211], v[148:155], v[196:203], 0, v146, v146 op_sel_hi:[0,0,0]
	s_setprio 0
	s_barrier
	v_mov_b32_e32 v128, v139
	s_add_i32 s6, s94, s86
	s_nop 1
	ds_read_b128 v[68:71], v145 offset:16384
	ds_read_b128 v[72:75], v145 offset:16400
	ds_read_b128 v[76:79], v145 offset:18432
	ds_read_b128 v[80:83], v145 offset:18448
	ds_read_b128 v[84:87], v145 offset:20480
	ds_read_b128 v[88:91], v145 offset:20496
	ds_read_b128 v[92:95], v145 offset:22528
	ds_read_b128 v[96:99], v145 offset:22544
	s_mov_b32 m0, s6
	s_nop 0
	global_load_lds_dwordx4 v128, s[68:69]
	v_mov_b32_e32 v128, v141
	s_add_i32 m0, s6, 0x2000
	s_add_u32 s38, s68, 0x20000
	global_load_lds_dwordx4 v128, s[68:69]
	s_addc_u32 s39, s69, 0
	v_mov_b32_e32 v128, v139
	s_add_i32 s6, s95, s86
	s_mov_b32 m0, s6
	s_nop 0
	global_load_lds_dwordx4 v128, s[38:39]
	v_mov_b32_e32 v128, v141
	s_add_i32 m0, s6, 0x2000
	s_nop 0
	global_load_lds_dwordx4 v128, s[38:39]
	v_mov_b32_e32 v128, v138
	s_mov_b32 m0, s87
	s_nop 0
	global_load_lds_dwordx4 v128, s[66:67]
	v_mov_b32_e32 v128, v140
	s_mov_b32 m0, s88
	s_nop 0
	global_load_lds_dwordx4 v128, s[66:67]
	s_waitcnt vmcnt(8)
	s_waitcnt lgkmcnt(0)
	s_barrier
	s_setprio 1
	s_waitcnt lgkmcnt(0)
	v_mfma_scale_f32_16x16x128_f8f6f4 v[64:67], v[130:137], v[68:75], 0, v146, v146 op_sel_hi:[0,0,0]
	v_mfma_scale_f32_16x16x128_f8f6f4 v[44:47], v[156:163], v[68:75], 0, v146, v146 op_sel_hi:[0,0,0]
	v_mfma_scale_f32_16x16x128_f8f6f4 v[56:59], v[148:155], v[68:75], 0, v146, v146 op_sel_hi:[0,0,0]
	v_mfma_scale_f32_16x16x128_f8f6f4 v[52:55], v[130:137], v[76:83], 0, v146, v146 op_sel_hi:[0,0,0]
	v_mfma_scale_f32_16x16x128_f8f6f4 v[48:51], v[148:155], v[76:83], 0, v146, v146 op_sel_hi:[0,0,0]
	v_mfma_scale_f32_16x16x128_f8f6f4 v[40:43], v[130:137], v[84:91], 0, v146, v146 op_sel_hi:[0,0,0]
	v_mfma_scale_f32_16x16x128_f8f6f4 v[196:199], v[164:171], v[68:75], 0, v146, v146 op_sel_hi:[0,0,0]
	v_mfma_scale_f32_16x16x128_f8f6f4 v[200:203], v[156:163], v[76:83], 0, v146, v146 op_sel_hi:[0,0,0]
	v_mfma_scale_f32_16x16x128_f8f6f4 v[212:215], v[164:171], v[76:83], 0, v146, v146 op_sel_hi:[0,0,0]
	v_mfma_scale_f32_16x16x128_f8f6f4 v[216:219], v[156:163], v[84:91], 0, v146, v146 op_sel_hi:[0,0,0]
	v_mfma_scale_f32_16x16x128_f8f6f4 v[220:223], v[148:155], v[84:91], 0, v146, v146 op_sel_hi:[0,0,0]
	v_mfma_scale_f32_16x16x128_f8f6f4 v[224:227], v[164:171], v[84:91], 0, v146, v146 op_sel_hi:[0,0,0]
	v_mfma_scale_f32_16x16x128_f8f6f4 v[228:231], v[130:137], v[92:99], 0, v146, v146 op_sel_hi:[0,0,0]
	v_mfma_scale_f32_16x16x128_f8f6f4 v[232:235], v[156:163], v[92:99], 0, v146, v146 op_sel_hi:[0,0,0]
	v_mfma_scale_f32_16x16x128_f8f6f4 v[236:239], v[148:155], v[92:99], 0, v146, v146 op_sel_hi:[0,0,0]
	v_mfma_scale_f32_16x16x128_f8f6f4 v[240:243], v[164:171], v[92:99], 0, v146, v146 op_sel_hi:[0,0,0]
	s_setprio 0
	s_barrier
; #define PG8_LDA(dst, b, h) do { if constexpr (FP8) { _Pragma("unroll") for (int m = 0; m < 4; ++m) dst##8[m] = PG8_LD8(PG8_SA(b, h), aoff, aoff1, m); } \
;         else { _Pragma("unroll") for (int m = 0; m < 4; ++m) _Pragma("unroll") for (int k = 0; k < 2; ++k) dst[m][k] = *(const LAS bf16x8*)(lds + PG8_SA(b, h) + (k ? aoff1 : aoff) + m * 2048); } } while (0)
; #define PG8_LDB(dst, b, h) do { if constexpr (FP8) { dst##8[0] = PG8_LD8(PG8_SB(b, h), boff, boff1, 0); dst##8[1] = PG8_LD8(PG8_SB(b, h), boff, boff1, 1); } \
;         else { _Pragma("unroll") for (int n = 0; n < 2; ++n) _Pragma("unroll") for (int k = 0; k < 2; ++k) dst[n][k] = *(const LAS bf16x8*)(lds + PG8_SB(b, h) + (k ? boff1 : boff) + n * 2048); } } while (0)
; #define PG8_WAIT_V(n) asm volatile("s_waitcnt vmcnt(" #n ")" ::: "memory")
; #define PG8_WAIT_L(n) asm volatile("s_waitcnt lgkmcnt(" #n ")" ::: "memory")
; #define PG8_BAR __builtin_amdgcn_s_barrier()
; #define PG8_SCHED __builtin_amdgcn_sched_barrier(0)
; #define PG8_S3 PG8_STAGE(PG8_SA(0, 1), a2 + hstepA, voffA)
; #define PG8_S4 do { PG8_STAGE(PG8_SB(1, 0), b3, voffB); PG8_STAGE(PG8_SB(1, 1), b3 + hstepB, voffB); PG8_STAGE(PG8_SA(1, 0), a3, voffA); } while (0)
; template <class Epi, class SchedT, bool ALIGN_EPI, bool SP2, bool FP8 = false>
; __device__ __forceinline__ void gemm_phase(LAS unsigned char* lds, const Gemm g, const SchedT& S, const Epi& E, const int wid) {
;     ...
;         for (int t = 0; t < nt; t += 2) {
;             const bool last = (t == nt - 2);
;             const char* a1 = cA + (size_t)(t + 1) * kstep;
;             const char* a2 = last ? nA : cA + (size_t)(t + 2) * kstep; const char* b2 = last ? nB : cB + (size_t)(t + 2) * kstep;
;             const char* a3 = a2 + kstep; const char* b3 = b2 + kstep;
;     ...
;             PG8_LDB(B0, 1, 0); PG8_LDB(B1, 1, 1); PG8_SCHED; PG8_LDA(At, 1, 0); PG8_S3;
;             PG8_WAIT_V(8); PG8_WAIT_L(0); PG8_BAR; PG8_MMAP(0, 1, 0); PG8_BAR; PG8_SCHED;
;             PG8_LDA(At, 1, 1); PG8_S4;
;             PG8_WAIT_V(8); PG8_WAIT_L(0); PG8_BAR; PG8_MMAP(1, 1, 1); PG8_BAR; PG8_SCHED;
	s_add_i32 s6, 0, 0x18000
	v_add_u32_e32 v8, s6, v142
	s_add_i32 s7, 0, 0x1c000
	s_nop 1
	ds_read_b128 v[0:3], v8
	ds_read_b128 v[4:7], v8 offset:16
	ds_read_b128 v[130:133], v8 offset:2048
	ds_read_b128 v[134:137], v8 offset:2064
	v_add_u32_e32 v8, s7, v142
	ds_read_b128 v[148:151], v8
	ds_read_b128 v[152:155], v8 offset:16
	ds_read_b128 v[156:159], v8 offset:2048
	ds_read_b128 v[160:163], v8 offset:2064
	s_add_u32 s38, s66, 0x90000
	v_mov_b32_e32 v68, v138
	s_mov_b32 m0, s89
	ds_read_b128 v[8:11], v145 offset:32768
	ds_read_b128 v[12:15], v145 offset:32784
	ds_read_b128 v[16:19], v145 offset:34816
	ds_read_b128 v[20:23], v145 offset:34832
	ds_read_b128 v[24:27], v145 offset:36864
	ds_read_b128 v[28:31], v145 offset:36880
	ds_read_b128 v[32:35], v145 offset:38912
	ds_read_b128 v[36:39], v145 offset:38928
	s_addc_u32 s39, s67, 0
	s_nop 0
	global_load_lds_dwordx4 v68, s[38:39]
	v_mov_b32_e32 v68, v140
	s_mov_b32 m0, s90
	s_nop 0
	global_load_lds_dwordx4 v68, s[38:39]
	s_waitcnt vmcnt(8)
	s_waitcnt lgkmcnt(0)
	s_barrier
	s_setprio 1
	s_waitcnt lgkmcnt(0)
	v_mfma_scale_f32_16x16x128_f8f6f4 v[124:127], v[0:7], v[8:15], v[124:127], v146, v146 op_sel_hi:[0,0,0]
	v_mfma_scale_f32_16x16x128_f8f6f4 v[108:111], v[148:155], v[8:15], v[108:111], v146, v146 op_sel_hi:[0,0,0]
	v_mfma_scale_f32_16x16x128_f8f6f4 v[120:123], v[130:137], v[8:15], v[120:123], v146, v146 op_sel_hi:[0,0,0]
	v_mfma_scale_f32_16x16x128_f8f6f4 v[100:103], v[156:163], v[8:15], v[100:103], v146, v146 op_sel_hi:[0,0,0]
	v_mfma_scale_f32_16x16x128_f8f6f4 v[116:119], v[0:7], v[16:23], v[116:119], v146, v146 op_sel_hi:[0,0,0]
	v_mfma_scale_f32_16x16x128_f8f6f4 v[92:95], v[148:155], v[16:23], v[172:175], v146, v146 op_sel_hi:[0,0,0]
	v_mfma_scale_f32_16x16x128_f8f6f4 v[112:115], v[130:137], v[16:23], v[112:115], v146, v146 op_sel_hi:[0,0,0]
	v_mfma_scale_f32_16x16x128_f8f6f4 v[84:87], v[156:163], v[16:23], v[176:179], v146, v146 op_sel_hi:[0,0,0]
	v_mfma_scale_f32_16x16x128_f8f6f4 v[104:107], v[0:7], v[24:31], v[104:107], v146, v146 op_sel_hi:[0,0,0]
	v_mfma_scale_f32_16x16x128_f8f6f4 v[76:79], v[148:155], v[24:31], v[180:183], v146, v146 op_sel_hi:[0,0,0]
	v_mfma_scale_f32_16x16x128_f8f6f4 v[96:99], v[130:137], v[24:31], v[184:187], v146, v146 op_sel_hi:[0,0,0]
	v_mfma_scale_f32_16x16x128_f8f6f4 v[72:75], v[156:163], v[24:31], v[188:191], v146, v146 op_sel_hi:[0,0,0]
	v_mfma_scale_f32_16x16x128_f8f6f4 v[88:91], v[0:7], v[32:39], v[192:195], v146, v146 op_sel_hi:[0,0,0]
	v_mfma_scale_f32_16x16x128_f8f6f4 v[68:71], v[148:155], v[32:39], v[204:207], v146, v146 op_sel_hi:[0,0,0]
	v_mfma_scale_f32_16x16x128_f8f6f4 v[80:83], v[130:137], v[32:39], v[208:211], v146, v146 op_sel_hi:[0,0,0]
	v_mfma_scale_f32_16x16x128_f8f6f4 v[60:63], v[156:163], v[32:39], v[60:63], v146, v146 op_sel_hi:[0,0,0]
	s_setprio 0
	s_barrier
	v_mov_b32_e32 v128, v139
	ds_read_b128 v[8:11], v145 offset:49152
	ds_read_b128 v[12:15], v145 offset:49168
	ds_read_b128 v[16:19], v145 offset:51200
	ds_read_b128 v[20:23], v145 offset:51216
	ds_read_b128 v[164:167], v145 offset:53248
	ds_read_b128 v[168:171], v145 offset:53264
	ds_read_b128 v[172:175], v145 offset:55296
	ds_read_b128 v[176:179], v145 offset:55312
	s_add_i32 s6, s6, s86
	v_lshl_add_u64 v[24:25], s[68:69], 0, v[128:129]
	v_lshl_add_u64 v[24:25], v[24:25], 0, s[40:41]
	s_mov_b32 m0, s6
	v_mov_b32_e32 v128, v141
	global_load_lds_dwordx4 v[24:25], off
	s_add_i32 m0, s6, 0x2000
	v_lshl_add_u64 v[24:25], s[68:69], 0, v[128:129]
	v_lshl_add_u64 v[24:25], v[24:25], 0, s[40:41]
	s_add_u32 s38, s68, 0x20080
	global_load_lds_dwordx4 v[24:25], off
	s_addc_u32 s39, s69, 0
	v_mov_b32_e32 v24, v139
	s_add_i32 s6, s7, s86
	s_mov_b32 m0, s6
	v_mov_b32_e32 v128, v138
	global_load_lds_dwordx4 v24, s[38:39]
	v_mov_b32_e32 v24, v141
	s_add_i32 m0, s6, 0x2000
	s_nop 0
	global_load_lds_dwordx4 v24, s[38:39]
	s_mov_b32 m0, s92
	v_lshl_add_u64 v[24:25], s[66:67], 0, v[128:129]
	v_lshl_add_u64 v[24:25], v[24:25], 0, s[40:41]
	v_mov_b32_e32 v128, v140
	global_load_lds_dwordx4 v[24:25], off
	s_mov_b32 m0, s93
	v_lshl_add_u64 v[24:25], s[66:67], 0, v[128:129]
	v_lshl_add_u64 v[24:25], v[24:25], 0, s[40:41]
	global_load_lds_dwordx4 v[24:25], off
	s_waitcnt vmcnt(8)
	s_waitcnt lgkmcnt(0)
	s_barrier
	s_setprio 1
	s_waitcnt lgkmcnt(0)
	v_mfma_scale_f32_16x16x128_f8f6f4 v[64:67], v[0:7], v[8:15], v[64:67], v146, v146 op_sel_hi:[0,0,0]
	v_mfma_scale_f32_16x16x128_f8f6f4 v[44:47], v[148:155], v[8:15], v[44:47], v146, v146 op_sel_hi:[0,0,0]
	v_mfma_scale_f32_16x16x128_f8f6f4 v[56:59], v[130:137], v[8:15], v[56:59], v146, v146 op_sel_hi:[0,0,0]
	v_mfma_scale_f32_16x16x128_f8f6f4 v[36:39], v[156:163], v[8:15], v[196:199], v146, v146 op_sel_hi:[0,0,0]
	v_mfma_scale_f32_16x16x128_f8f6f4 v[52:55], v[0:7], v[16:23], v[52:55], v146, v146 op_sel_hi:[0,0,0]
	v_mfma_scale_f32_16x16x128_f8f6f4 v[28:31], v[148:155], v[16:23], v[200:203], v146, v146 op_sel_hi:[0,0,0]
	v_mfma_scale_f32_16x16x128_f8f6f4 v[48:51], v[130:137], v[16:23], v[48:51], v146, v146 op_sel_hi:[0,0,0]
	v_mfma_scale_f32_16x16x128_f8f6f4 v[20:23], v[156:163], v[16:23], v[212:215], v146, v146 op_sel_hi:[0,0,0]
	v_mfma_scale_f32_16x16x128_f8f6f4 v[40:43], v[0:7], v[164:171], v[40:43], v146, v146 op_sel_hi:[0,0,0]
	v_mfma_scale_f32_16x16x128_f8f6f4 v[12:15], v[148:155], v[164:171], v[216:219], v146, v146 op_sel_hi:[0,0,0]
	v_mfma_scale_f32_16x16x128_f8f6f4 v[32:35], v[130:137], v[164:171], v[220:223], v146, v146 op_sel_hi:[0,0,0]
	v_mfma_scale_f32_16x16x128_f8f6f4 v[8:11], v[156:163], v[164:171], v[224:227], v146, v146 op_sel_hi:[0,0,0]
	v_mfma_scale_f32_16x16x128_f8f6f4 v[24:27], v[0:7], v[172:179], v[228:231], v146, v146 op_sel_hi:[0,0,0]
	v_mfma_scale_f32_16x16x128_f8f6f4 v[4:7], v[148:155], v[172:179], v[232:235], v146, v146 op_sel_hi:[0,0,0]
	v_mfma_scale_f32_16x16x128_f8f6f4 v[16:19], v[130:137], v[172:179], v[236:239], v146, v146 op_sel_hi:[0,0,0]
	v_mfma_scale_f32_16x16x128_f8f6f4 v[0:3], v[156:163], v[172:179], v[240:243], v146, v146 op_sel_hi:[0,0,0]
	s_setprio 0
	s_barrier
	s_add_u32 s52, s52, 0x100
	s_addc_u32 s53, s53, 0
	s_add_u32 s21, s21, 0x100
	s_addc_u32 s24, s24, 0
	s_cmp_ge_i32 s30, s22
	s_mov_b32 s31, s30
	s_cbranch_scc1 .Lpeel_exit_lbb0_239

; __device__ __forceinline__ unsigned pk2(float lo, float hi) { f32x2_t v = {lo, hi}; bf16x2_t b = __builtin_convertvector(v, bf16x2_t); return __builtin_bit_cast(unsigned, b); }
;     __device__ __forceinline__ void operator()(const f32x4 (&acc)[2][2][4][2], const Unit& u, int wr, int wc, int fr, int fq) const {
;     ...
;             for (int m = 0; m < 4; ++m) { bf16_t* rowp = O + (size_t)(row0 + ai * HALF + m * 16) * ldc + col0;
; #pragma unroll
;                 for (int bj = 0; bj < 2; ++bj) { const f32x4 v0 = acc[ai][bj][m][0] * sc, v1 = acc[ai][bj][m][1] * sc;
;                     u32x4 w; w.x = pk2(v0[0], v0[1]); w.y = pk2(v0[2], v0[3]); w.z = pk2(v1[0], v1[1]); w.w = pk2(v1[2], v1[3]);
;                     *(u32x4*)(rowp + bj * HALF) = w; } }
.Lpeel_exit_lbb0_239:
	v_pk_mul_f32 v[126:127], v[126:127], s[42:43] op_sel_hi:[1,0]
	v_pk_mul_f32 v[124:125], v[124:125], s[42:43] op_sel_hi:[1,0]
	v_pk_mul_f32 v[122:123], v[122:123], s[42:43] op_sel_hi:[1,0]
	v_pk_mul_f32 v[120:121], v[120:121], s[42:43] op_sel_hi:[1,0]
	v_pk_mul_f32 v[130:131], v[110:111], s[42:43] op_sel_hi:[1,0]
	v_pk_mul_f32 v[132:133], v[108:109], s[42:43] op_sel_hi:[1,0]
	v_pk_mul_f32 v[134:135], v[102:103], s[42:43] op_sel_hi:[1,0]
	v_pk_mul_f32 v[136:137], v[100:101], s[42:43] op_sel_hi:[1,0]
	v_pk_mul_f32 v[100:101], v[118:119], s[42:43] op_sel_hi:[1,0]
	v_pk_mul_f32 v[102:103], v[116:117], s[42:43] op_sel_hi:[1,0]
	v_pk_mul_f32 v[108:109], v[114:115], s[42:43] op_sel_hi:[1,0]
	v_pk_mul_f32 v[110:111], v[112:113], s[42:43] op_sel_hi:[1,0]
	v_pk_mul_f32 v[112:113], v[94:95], s[42:43] op_sel_hi:[1,0]
	v_pk_mul_f32 v[114:115], v[92:93], s[42:43] op_sel_hi:[1,0]
	v_pk_mul_f32 v[116:117], v[86:87], s[42:43] op_sel_hi:[1,0]
	v_pk_mul_f32 v[118:119], v[84:85], s[42:43] op_sel_hi:[1,0]
	v_pk_mul_f32 v[84:85], v[106:107], s[42:43] op_sel_hi:[1,0]
	v_pk_mul_f32 v[86:87], v[104:105], s[42:43] op_sel_hi:[1,0]
	v_pk_mul_f32 v[92:93], v[98:99], s[42:43] op_sel_hi:[1,0]
	v_pk_mul_f32 v[94:95], v[96:97], s[42:43] op_sel_hi:[1,0]
	v_pk_mul_f32 v[96:97], v[78:79], s[42:43] op_sel_hi:[1,0]
	v_pk_mul_f32 v[98:99], v[76:77], s[42:43] op_sel_hi:[1,0]
	v_pk_mul_f32 v[104:105], v[74:75], s[42:43] op_sel_hi:[1,0]
	v_pk_mul_f32 v[106:107], v[72:73], s[42:43] op_sel_hi:[1,0]
	v_pk_mul_f32 v[72:73], v[90:91], s[42:43] op_sel_hi:[1,0]
	v_pk_mul_f32 v[74:75], v[88:89], s[42:43] op_sel_hi:[1,0]
	v_pk_mul_f32 v[76:77], v[82:83], s[42:43] op_sel_hi:[1,0]
	v_pk_mul_f32 v[78:79], v[80:81], s[42:43] op_sel_hi:[1,0]
	v_pk_mul_f32 v[70:71], v[70:71], s[42:43] op_sel_hi:[1,0]
	v_pk_mul_f32 v[68:69], v[68:69], s[42:43] op_sel_hi:[1,0]
	v_pk_mul_f32 v[62:63], v[62:63], s[42:43] op_sel_hi:[1,0]
	v_pk_mul_f32 v[80:81], v[60:61], s[42:43] op_sel_hi:[1,0]
	v_pk_mul_f32 v[60:61], v[66:67], s[42:43] op_sel_hi:[1,0]
	v_pk_mul_f32 v[64:65], v[64:65], s[42:43] op_sel_hi:[1,0]
	v_pk_mul_f32 v[58:59], v[58:59], s[42:43] op_sel_hi:[1,0]
	v_pk_mul_f32 v[56:57], v[56:57], s[42:43] op_sel_hi:[1,0]
	v_pk_mul_f32 v[66:67], v[46:47], s[42:43] op_sel_hi:[1,0]
	v_pk_mul_f32 v[82:83], v[44:45], s[42:43] op_sel_hi:[1,0]
	v_pk_mul_f32 v[88:89], v[38:39], s[42:43] op_sel_hi:[1,0]
	v_pk_mul_f32 v[90:91], v[36:37], s[42:43] op_sel_hi:[1,0]
	v_pk_mul_f32 v[36:37], v[54:55], s[42:43] op_sel_hi:[1,0]
	v_pk_mul_f32 v[38:39], v[52:53], s[42:43] op_sel_hi:[1,0]
	v_pk_mul_f32 v[44:45], v[50:51], s[42:43] op_sel_hi:[1,0]
	v_pk_mul_f32 v[46:47], v[48:49], s[42:43] op_sel_hi:[1,0]
	v_pk_mul_f32 v[48:49], v[30:31], s[42:43] op_sel_hi:[1,0]
	v_pk_mul_f32 v[50:51], v[28:29], s[42:43] op_sel_hi:[1,0]
	v_pk_mul_f32 v[52:53], v[22:23], s[42:43] op_sel_hi:[1,0]
	v_pk_mul_f32 v[54:55], v[20:21], s[42:43] op_sel_hi:[1,0]
	v_pk_mul_f32 v[20:21], v[42:43], s[42:43] op_sel_hi:[1,0]
	v_pk_mul_f32 v[22:23], v[40:41], s[42:43] op_sel_hi:[1,0]
	v_pk_mul_f32 v[28:29], v[34:35], s[42:43] op_sel_hi:[1,0]
	v_pk_mul_f32 v[30:31], v[32:33], s[42:43] op_sel_hi:[1,0]
	v_pk_mul_f32 v[32:33], v[14:15], s[42:43] op_sel_hi:[1,0]
	v_pk_mul_f32 v[34:35], v[12:13], s[42:43] op_sel_hi:[1,0]
	v_pk_mul_f32 v[40:41], v[10:11], s[42:43] op_sel_hi:[1,0]
	v_pk_mul_f32 v[42:43], v[8:9], s[42:43] op_sel_hi:[1,0]
	v_pk_mul_f32 v[8:9], v[26:27], s[42:43] op_sel_hi:[1,0]
	v_pk_mul_f32 v[10:11], v[24:25], s[42:43] op_sel_hi:[1,0]
	v_pk_mul_f32 v[12:13], v[18:19], s[42:43] op_sel_hi:[1,0]
	v_pk_mul_f32 v[14:15], v[16:17], s[42:43] op_sel_hi:[1,0]
	v_pk_mul_f32 v[6:7], v[6:7], s[42:43] op_sel_hi:[1,0]
	v_pk_mul_f32 v[4:5], v[4:5], s[42:43] op_sel_hi:[1,0]
	v_pk_mul_f32 v[2:3], v[2:3], s[42:43] op_sel_hi:[1,0]
	v_pk_mul_f32 v[0:1], v[0:1], s[42:43] op_sel_hi:[1,0]
	s_and_b64 vcc, exec, s[96:97]
	s_cbranch_vccz .LBB0_242

; #define PG8_LDA(dst, b, h) do { if constexpr (FP8) { _Pragma("unroll") for (int m = 0; m < 4; ++m) dst##8[m] = PG8_LD8(PG8_SA(b, h), aoff, aoff1, m); } \
;         else { _Pragma("unroll") for (int m = 0; m < 4; ++m) _Pragma("unroll") for (int k = 0; k < 2; ++k) dst[m][k] = *(const LAS bf16x8*)(lds + PG8_SA(b, h) + (k ? aoff1 : aoff) + m * 2048); } } while (0)
; #define PG8_LDB(dst, b, h) do { if constexpr (FP8) { dst##8[0] = PG8_LD8(PG8_SB(b, h), boff, boff1, 0); dst##8[1] = PG8_LD8(PG8_SB(b, h), boff, boff1, 1); } \
;         else { _Pragma("unroll") for (int n = 0; n < 2; ++n) _Pragma("unroll") for (int k = 0; k < 2; ++k) dst[n][k] = *(const LAS bf16x8*)(lds + PG8_SB(b, h) + (k ? boff1 : boff) + n * 2048); } } while (0)
; #define PG8_WAIT_V(n) asm volatile("s_waitcnt vmcnt(" #n ")" ::: "memory")
; #define PG8_WAIT_L(n) asm volatile("s_waitcnt lgkmcnt(" #n ")" ::: "memory")
; #define PG8_BAR __builtin_amdgcn_s_barrier()
; #define PG8_SCHED __builtin_amdgcn_sched_barrier(0)
; #define PG8_S1 PG8_STAGE(PG8_SA(1, 1), a1 + hstepA, voffA)
; #define PG8_S2 do { PG8_STAGE(PG8_SB(0, 0), b2, voffB); PG8_STAGE(PG8_SB(0, 1), b2 + hstepB, voffB); PG8_STAGE(PG8_SA(0, 0), a2, voffA); } while (0)
; template <class Epi, class SchedT, bool ALIGN_EPI, bool SP2, bool FP8 = false>
; __device__ __forceinline__ void gemm_phase(LAS unsigned char* lds, const Gemm g, const SchedT& S, const Epi& E, const int wid) {
;     ...
;         const bool has_next = S.next(ui + 1, nxt);
;         const char* nA = has_next ? (const char*)g.A + (size_t)nxt.pm * tstepA + (size_t)nxt.aoff * 2 : cA; const char* nB = has_next ? (const char*)g.Bt + (size_t)nxt.pn * tstepB + (size_t)nxt.boff * 2 : cB;
;         const int nt = cur.nt;
;         for (int t = 0; t < nt; t += 2) {
;             const bool last = (t == nt - 2);
;             const char* a1 = cA + (size_t)(t + 1) * kstep;
;             const char* a2 = last ? nA : cA + (size_t)(t + 2) * kstep; const char* b2 = last ? nB : cB + (size_t)(t + 2) * kstep;
;             const char* a3 = a2 + kstep; const char* b3 = b2 + kstep;
;             if constexpr (SP2) {
;     ...
;             PG8_LDB(B0, 0, 0); PG8_LDB(B1, 0, 1); PG8_SCHED; PG8_LDA(At, 0, 0); PG8_S1;
;             PG8_WAIT_V(8); PG8_WAIT_L(0); PG8_BAR; PG8_MMAP(0, 0, 0); PG8_BAR; PG8_SCHED;
;             PG8_LDA(At, 0, 1); PG8_S2;
.LBB0_254:
	s_ashr_i32 s45, s44, 31
	s_lshl_b64 s[20:21], s[44:45], 19
	s_add_u32 s46, s23, s20
	s_addc_u32 s47, s34, s21
	s_ashr_i32 s43, s42, 31
	s_lshl_b64 s[20:21], s[42:43], 19
	s_add_u32 s48, s64, s20
	s_addc_u32 s49, s65, s21
	s_cmp_lt_i32 s8, 1
	s_cbranch_scc1 .LBB0_262
	s_and_b64 s[20:21], s[4:5], exec
	s_cselect_b32 s9, s47, s51
	s_cselect_b32 s20, s46, s50
	s_cselect_b32 s21, s49, s53
	s_cselect_b32 s24, s48, s52
	s_add_i32 s30, s8, -2
	s_add_u32 s50, s50, 0x40080
	s_addc_u32 s51, s51, 0
	s_add_u32 s31, s52, 0x100
	s_addc_u32 s38, s53, 0
	s_mov_b32 s39, 0
	ds_read_b128 v[146:149], v139
	ds_read_b128 v[150:153], v139 offset:1024
	ds_read_b128 v[154:157], v140
	ds_read_b128 v[158:161], v140 offset:1024
	ds_read_b128 v[162:165], v141
	ds_read_b128 v[166:169], v141 offset:1024
	ds_read_b128 v[170:173], v142
	ds_read_b128 v[174:177], v142 offset:1024
	s_add_i32 s43, s39, 2
	s_add_u32 s6, s50, 0xfffc0080
	s_addc_u32 s7, s51, -1
	s_cmp_eq_u32 s30, s39
	s_cselect_b32 s53, s9, s7
	s_cselect_b32 s52, s20, s6
	s_cselect_b32 s67, s21, s38
	s_cselect_b32 s66, s24, s31
	v_mov_b32_e32 v128, v134
	ds_read_b128 v[178:181], v143
	ds_read_b128 v[182:185], v143 offset:1024
	ds_read_b128 v[186:189], v143 offset:2048
	ds_read_b128 v[190:193], v143 offset:3072
	ds_read_b128 v[194:197], v143 offset:4096
	ds_read_b128 v[198:201], v143 offset:5120
	ds_read_b128 v[202:205], v143 offset:6144
	ds_read_b128 v[206:209], v143 offset:7168
	s_add_i32 m0, s87, 0xc000
	s_nop 0
	global_load_lds_dwordx4 v128, s[50:51]
	v_mov_b32_e32 v128, v136
	s_add_i32 m0, s87, 0xe000
	s_nop 0
	global_load_lds_dwordx4 v128, s[50:51]
	s_waitcnt vmcnt(8)
	s_waitcnt lgkmcnt(0)
	s_barrier
	s_setprio 1
	s_waitcnt lgkmcnt(0)
	v_mfma_f32_16x16x32_bf16 v[124:127], v[146:149], v[178:181], 0
	v_mfma_f32_16x16x32_bf16 v[120:123], v[154:157], v[178:181], 0
	v_mfma_f32_16x16x32_bf16 v[104:107], v[154:157], v[186:189], 0
	v_mfma_f32_16x16x32_bf16 v[108:111], v[146:149], v[186:189], 0
	v_mfma_f32_16x16x32_bf16 v[92:95], v[146:149], v[194:197], 0
	v_mfma_f32_16x16x32_bf16 v[88:91], v[154:157], v[194:197], 0
	v_mfma_f32_16x16x32_bf16 v[72:75], v[154:157], v[202:205], 0
	v_mfma_f32_16x16x32_bf16 v[76:79], v[146:149], v[202:205], 0
	v_mfma_f32_16x16x32_bf16 v[124:127], v[150:153], v[182:185], v[124:127]
	v_mfma_f32_16x16x32_bf16 v[120:123], v[158:161], v[182:185], v[120:123]
	v_mfma_f32_16x16x32_bf16 v[104:107], v[158:161], v[190:193], v[104:107]
	v_mfma_f32_16x16x32_bf16 v[108:111], v[150:153], v[190:193], v[108:111]
	v_mfma_f32_16x16x32_bf16 v[92:95], v[150:153], v[198:201], v[92:95]
	v_mfma_f32_16x16x32_bf16 v[88:91], v[158:161], v[198:201], v[88:91]
	v_mfma_f32_16x16x32_bf16 v[72:75], v[158:161], v[206:209], v[72:75]
	v_mfma_f32_16x16x32_bf16 v[76:79], v[150:153], v[206:209], v[76:79]
	s_setprio 0
	s_setprio 1
	v_mfma_f32_16x16x32_bf16 v[116:119], v[162:165], v[178:181], 0
	v_mfma_f32_16x16x32_bf16 v[112:115], v[170:173], v[178:181], 0
	v_mfma_f32_16x16x32_bf16 v[96:99], v[170:173], v[186:189], 0
	v_mfma_f32_16x16x32_bf16 v[100:103], v[162:165], v[186:189], 0
	v_mfma_f32_16x16x32_bf16 v[84:87], v[162:165], v[194:197], 0
	v_mfma_f32_16x16x32_bf16 v[80:83], v[170:173], v[194:197], 0
	v_mfma_f32_16x16x32_bf16 v[56:59], v[170:173], v[202:205], 0
	v_mfma_f32_16x16x32_bf16 v[60:63], v[162:165], v[202:205], 0
	v_mfma_f32_16x16x32_bf16 v[116:119], v[166:169], v[182:185], v[116:119]
	v_mfma_f32_16x16x32_bf16 v[112:115], v[174:177], v[182:185], v[112:115]
	v_mfma_f32_16x16x32_bf16 v[96:99], v[174:177], v[190:193], v[96:99]
	v_mfma_f32_16x16x32_bf16 v[100:103], v[166:169], v[190:193], v[100:103]
	v_mfma_f32_16x16x32_bf16 v[84:87], v[166:169], v[198:201], v[84:87]
	v_mfma_f32_16x16x32_bf16 v[80:83], v[174:177], v[198:201], v[80:83]
	v_mfma_f32_16x16x32_bf16 v[56:59], v[174:177], v[206:209], v[56:59]
	v_mfma_f32_16x16x32_bf16 v[60:63], v[166:169], v[206:209], v[60:63]
	s_setprio 0
	s_barrier
	v_mov_b32_e32 v128, v135
	s_add_i32 s6, s94, s86
	ds_read_b128 v[178:181], v143 offset:16384
	ds_read_b128 v[182:185], v143 offset:17408
	ds_read_b128 v[186:189], v143 offset:18432
	ds_read_b128 v[190:193], v143 offset:19456
	ds_read_b128 v[194:197], v143 offset:20480
	ds_read_b128 v[198:201], v143 offset:21504
	ds_read_b128 v[202:205], v143 offset:22528
	ds_read_b128 v[206:209], v143 offset:23552
	s_mov_b32 m0, s6
	s_nop 0
	global_load_lds_dwordx4 v128, s[66:67]
	v_mov_b32_e32 v128, v137
	s_add_i32 m0, s6, 0x2000
	s_add_u32 s60, s66, 0x40000
	global_load_lds_dwordx4 v128, s[66:67]
	s_addc_u32 s61, s67, 0
	v_mov_b32_e32 v128, v135
	s_add_i32 s6, s95, s86
	s_mov_b32 m0, s6
	s_nop 0
	global_load_lds_dwordx4 v128, s[60:61]
	v_mov_b32_e32 v128, v137
	s_add_i32 m0, s6, 0x2000
	s_nop 0
	global_load_lds_dwordx4 v128, s[60:61]
	v_mov_b32_e32 v128, v134
	s_mov_b32 m0, s87
	s_nop 0
	global_load_lds_dwordx4 v128, s[52:53]
	v_mov_b32_e32 v128, v136
	s_mov_b32 m0, s88
	s_nop 0
	global_load_lds_dwordx4 v128, s[52:53]
	s_waitcnt vmcnt(8)
	s_waitcnt lgkmcnt(0)
	s_barrier
; #define PG8_LDA(dst, b, h) do { if constexpr (FP8) { _Pragma("unroll") for (int m = 0; m < 4; ++m) dst##8[m] = PG8_LD8(PG8_SA(b, h), aoff, aoff1, m); } \
;         else { _Pragma("unroll") for (int m = 0; m < 4; ++m) _Pragma("unroll") for (int k = 0; k < 2; ++k) dst[m][k] = *(const LAS bf16x8*)(lds + PG8_SA(b, h) + (k ? aoff1 : aoff) + m * 2048); } } while (0)
; #define PG8_LDB(dst, b, h) do { if constexpr (FP8) { dst##8[0] = PG8_LD8(PG8_SB(b, h), boff, boff1, 0); dst##8[1] = PG8_LD8(PG8_SB(b, h), boff, boff1, 1); } \
;         else { _Pragma("unroll") for (int n = 0; n < 2; ++n) _Pragma("unroll") for (int k = 0; k < 2; ++k) dst[n][k] = *(const LAS bf16x8*)(lds + PG8_SB(b, h) + (k ? boff1 : boff) + n * 2048); } } while (0)
; #define PG8_WAIT_V(n) asm volatile("s_waitcnt vmcnt(" #n ")" ::: "memory")
; #define PG8_WAIT_L(n) asm volatile("s_waitcnt lgkmcnt(" #n ")" ::: "memory")
; #define PG8_BAR __builtin_amdgcn_s_barrier()
; #define PG8_SCHED __builtin_amdgcn_sched_barrier(0)
; #define PG8_S1 PG8_STAGE(PG8_SA(1, 1), a1 + hstepA, voffA)
; #define PG8_S2 do { PG8_STAGE(PG8_SB(0, 0), b2, voffB); PG8_STAGE(PG8_SB(0, 1), b2 + hstepB, voffB); PG8_STAGE(PG8_SA(0, 0), a2, voffA); } while (0)
; #define PG8_S3 PG8_STAGE(PG8_SA(0, 1), a2 + hstepA, voffA)
; template <class Epi, class SchedT, bool ALIGN_EPI, bool SP2, bool FP8 = false>
; __device__ __forceinline__ void gemm_phase(LAS unsigned char* lds, const Gemm g, const SchedT& S, const Epi& E, const int wid) {
;     ...
;         for (int t = 0; t < nt; t += 2) {
;             const bool last = (t == nt - 2);
;             const char* a1 = cA + (size_t)(t + 1) * kstep;
;             const char* a2 = last ? nA : cA + (size_t)(t + 2) * kstep; const char* b2 = last ? nB : cB + (size_t)(t + 2) * kstep;
;             const char* a3 = a2 + kstep; const char* b3 = b2 + kstep;
;             if constexpr (SP2) {
;     ...
;             PG8_LDB(B0, 0, 0); PG8_LDB(B1, 0, 1); PG8_SCHED; PG8_LDA(At, 0, 0); PG8_S1;
;             PG8_WAIT_V(8); PG8_WAIT_L(0); PG8_BAR; PG8_MMAP(0, 0, 0); PG8_BAR; PG8_SCHED;
;             PG8_LDA(At, 0, 1); PG8_S2;
;             PG8_WAIT_V(8); PG8_WAIT_L(0); PG8_BAR; PG8_MMAP(1, 0, 1); PG8_BAR; PG8_SCHED;
;             PG8_LDB(B0, 1, 0); PG8_LDB(B1, 1, 1); PG8_SCHED; PG8_LDA(At, 1, 0); PG8_S3;
;             PG8_WAIT_V(8); PG8_WAIT_L(0); PG8_BAR; PG8_MMAP(0, 1, 0); PG8_BAR; PG8_SCHED;
	s_setprio 1
	s_waitcnt lgkmcnt(0)
	v_mfma_f32_16x16x32_bf16 v[68:71], v[146:149], v[178:181], 0
	v_mfma_f32_16x16x32_bf16 v[64:67], v[154:157], v[178:181], 0
	v_mfma_f32_16x16x32_bf16 v[40:43], v[154:157], v[186:189], 0
	v_mfma_f32_16x16x32_bf16 v[44:47], v[146:149], v[186:189], 0
	v_mfma_f32_16x16x32_bf16 v[28:31], v[146:149], v[194:197], 0
	v_mfma_f32_16x16x32_bf16 v[24:27], v[154:157], v[194:197], 0
	v_mfma_f32_16x16x32_bf16 v[8:11], v[154:157], v[202:205], 0
	v_mfma_f32_16x16x32_bf16 v[12:15], v[146:149], v[202:205], 0
	v_mfma_f32_16x16x32_bf16 v[68:71], v[150:153], v[182:185], v[68:71]
	v_mfma_f32_16x16x32_bf16 v[64:67], v[158:161], v[182:185], v[64:67]
	v_mfma_f32_16x16x32_bf16 v[40:43], v[158:161], v[190:193], v[40:43]
	v_mfma_f32_16x16x32_bf16 v[44:47], v[150:153], v[190:193], v[44:47]
	v_mfma_f32_16x16x32_bf16 v[28:31], v[150:153], v[198:201], v[28:31]
	v_mfma_f32_16x16x32_bf16 v[24:27], v[158:161], v[198:201], v[24:27]
	v_mfma_f32_16x16x32_bf16 v[8:11], v[158:161], v[206:209], v[8:11]
	v_mfma_f32_16x16x32_bf16 v[12:15], v[150:153], v[206:209], v[12:15]
	s_setprio 0
	s_setprio 1
	v_mfma_f32_16x16x32_bf16 v[52:55], v[162:165], v[178:181], 0
	v_mfma_f32_16x16x32_bf16 v[48:51], v[170:173], v[178:181], 0
	v_mfma_f32_16x16x32_bf16 v[32:35], v[170:173], v[186:189], 0
	v_mfma_f32_16x16x32_bf16 v[36:39], v[162:165], v[186:189], 0
	v_mfma_f32_16x16x32_bf16 v[20:23], v[162:165], v[194:197], 0
	v_mfma_f32_16x16x32_bf16 v[16:19], v[170:173], v[194:197], 0
	v_mfma_f32_16x16x32_bf16 v[0:3], v[170:173], v[202:205], 0
	v_mfma_f32_16x16x32_bf16 v[4:7], v[162:165], v[202:205], 0
	v_mfma_f32_16x16x32_bf16 v[52:55], v[166:169], v[182:185], v[52:55]
	v_mfma_f32_16x16x32_bf16 v[48:51], v[174:177], v[182:185], v[48:51]
	v_mfma_f32_16x16x32_bf16 v[32:35], v[174:177], v[190:193], v[32:35]
	v_mfma_f32_16x16x32_bf16 v[36:39], v[166:169], v[190:193], v[36:39]
	v_mfma_f32_16x16x32_bf16 v[20:23], v[166:169], v[198:201], v[20:23]
	v_mfma_f32_16x16x32_bf16 v[16:19], v[174:177], v[198:201], v[16:19]
	v_mfma_f32_16x16x32_bf16 v[0:3], v[174:177], v[206:209], v[0:3]
	v_mfma_f32_16x16x32_bf16 v[4:7], v[166:169], v[206:209], v[4:7]
	s_setprio 0
	s_barrier
	s_add_i32 s6, 0, 0x18000
	v_add_u32_e32 v128, s6, v138
	s_add_i32 s7, 0, 0x1c000
	ds_read_b128 v[146:149], v128
	ds_read_b128 v[150:153], v128 offset:1024
	ds_read_b128 v[154:157], v144
	ds_read_b128 v[158:161], v144 offset:1024
	v_add_u32_e32 v128, s7, v138
	ds_read_b128 v[162:165], v128
	ds_read_b128 v[166:169], v128 offset:1024
	ds_read_b128 v[170:173], v145
	ds_read_b128 v[174:177], v145 offset:1024
	s_add_u32 s60, s52, 0x40000
	v_mov_b32_e32 v128, v134
	s_mov_b32 m0, s89
	ds_read_b128 v[178:181], v143 offset:32768
	ds_read_b128 v[182:185], v143 offset:33792
	ds_read_b128 v[186:189], v143 offset:34816
	ds_read_b128 v[190:193], v143 offset:35840
	ds_read_b128 v[194:197], v143 offset:36864
	ds_read_b128 v[198:201], v143 offset:37888
	ds_read_b128 v[202:205], v143 offset:38912
	ds_read_b128 v[206:209], v143 offset:39936
	s_addc_u32 s61, s53, 0
	s_nop 0
	global_load_lds_dwordx4 v128, s[60:61]
	v_mov_b32_e32 v128, v136
	s_mov_b32 m0, s90
	s_nop 0
	global_load_lds_dwordx4 v128, s[60:61]
	s_waitcnt vmcnt(8)
	s_waitcnt lgkmcnt(0)
	s_barrier
	s_setprio 1
	s_waitcnt lgkmcnt(0)
	v_mfma_f32_16x16x32_bf16 v[124:127], v[146:149], v[178:181], v[124:127]
	v_mfma_f32_16x16x32_bf16 v[120:123], v[154:157], v[178:181], v[120:123]
	v_mfma_f32_16x16x32_bf16 v[104:107], v[154:157], v[186:189], v[104:107]
	v_mfma_f32_16x16x32_bf16 v[108:111], v[146:149], v[186:189], v[108:111]
	v_mfma_f32_16x16x32_bf16 v[92:95], v[146:149], v[194:197], v[92:95]
	v_mfma_f32_16x16x32_bf16 v[88:91], v[154:157], v[194:197], v[88:91]
	v_mfma_f32_16x16x32_bf16 v[72:75], v[154:157], v[202:205], v[72:75]
	v_mfma_f32_16x16x32_bf16 v[76:79], v[146:149], v[202:205], v[76:79]
	v_mfma_f32_16x16x32_bf16 v[124:127], v[150:153], v[182:185], v[124:127]
	v_mfma_f32_16x16x32_bf16 v[120:123], v[158:161], v[182:185], v[120:123]
	v_mfma_f32_16x16x32_bf16 v[104:107], v[158:161], v[190:193], v[104:107]
	v_mfma_f32_16x16x32_bf16 v[108:111], v[150:153], v[190:193], v[108:111]
	v_mfma_f32_16x16x32_bf16 v[92:95], v[150:153], v[198:201], v[92:95]
	v_mfma_f32_16x16x32_bf16 v[88:91], v[158:161], v[198:201], v[88:91]
	v_mfma_f32_16x16x32_bf16 v[72:75], v[158:161], v[206:209], v[72:75]
	v_mfma_f32_16x16x32_bf16 v[76:79], v[150:153], v[206:209], v[76:79]
	s_setprio 0
	s_setprio 1
	v_mfma_f32_16x16x32_bf16 v[116:119], v[162:165], v[178:181], v[116:119]
	v_mfma_f32_16x16x32_bf16 v[112:115], v[170:173], v[178:181], v[112:115]
	v_mfma_f32_16x16x32_bf16 v[96:99], v[170:173], v[186:189], v[96:99]
	v_mfma_f32_16x16x32_bf16 v[100:103], v[162:165], v[186:189], v[100:103]
	v_mfma_f32_16x16x32_bf16 v[84:87], v[162:165], v[194:197], v[84:87]
	v_mfma_f32_16x16x32_bf16 v[80:83], v[170:173], v[194:197], v[80:83]
	v_mfma_f32_16x16x32_bf16 v[56:59], v[170:173], v[202:205], v[56:59]
	v_mfma_f32_16x16x32_bf16 v[60:63], v[162:165], v[202:205], v[60:63]
	v_mfma_f32_16x16x32_bf16 v[116:119], v[166:169], v[182:185], v[116:119]
	v_mfma_f32_16x16x32_bf16 v[112:115], v[174:177], v[182:185], v[112:115]
	v_mfma_f32_16x16x32_bf16 v[96:99], v[174:177], v[190:193], v[96:99]
	v_mfma_f32_16x16x32_bf16 v[100:103], v[166:169], v[190:193], v[100:103]
	v_mfma_f32_16x16x32_bf16 v[84:87], v[166:169], v[198:201], v[84:87]
	v_mfma_f32_16x16x32_bf16 v[80:83], v[174:177], v[198:201], v[80:83]
	v_mfma_f32_16x16x32_bf16 v[56:59], v[174:177], v[206:209], v[56:59]
	v_mfma_f32_16x16x32_bf16 v[60:63], v[166:169], v[206:209], v[60:63]
	s_setprio 0
	s_barrier
; #define PG8_LDA(dst, b, h) do { if constexpr (FP8) { _Pragma("unroll") for (int m = 0; m < 4; ++m) dst##8[m] = PG8_LD8(PG8_SA(b, h), aoff, aoff1, m); } \
;         else { _Pragma("unroll") for (int m = 0; m < 4; ++m) _Pragma("unroll") for (int k = 0; k < 2; ++k) dst[m][k] = *(const LAS bf16x8*)(lds + PG8_SA(b, h) + (k ? aoff1 : aoff) + m * 2048); } } while (0)
; #define PG8_LDB(dst, b, h) do { if constexpr (FP8) { dst##8[0] = PG8_LD8(PG8_SB(b, h), boff, boff1, 0); dst##8[1] = PG8_LD8(PG8_SB(b, h), boff, boff1, 1); } \
;         else { _Pragma("unroll") for (int n = 0; n < 2; ++n) _Pragma("unroll") for (int k = 0; k < 2; ++k) dst[n][k] = *(const LAS bf16x8*)(lds + PG8_SB(b, h) + (k ? boff1 : boff) + n * 2048); } } while (0)
; #define PG8_WAIT_V(n) asm volatile("s_waitcnt vmcnt(" #n ")" ::: "memory")
; #define PG8_WAIT_L(n) asm volatile("s_waitcnt lgkmcnt(" #n ")" ::: "memory")
; #define PG8_BAR __builtin_amdgcn_s_barrier()
; #define PG8_SCHED __builtin_amdgcn_sched_barrier(0)
; #define PG8_S1 PG8_STAGE(PG8_SA(1, 1), a1 + hstepA, voffA)
; #define PG8_S4 do { PG8_STAGE(PG8_SB(1, 0), b3, voffB); PG8_STAGE(PG8_SB(1, 1), b3 + hstepB, voffB); PG8_STAGE(PG8_SA(1, 0), a3, voffA); } while (0)
; template <class Epi, class SchedT, bool ALIGN_EPI, bool SP2, bool FP8 = false>
; __device__ __forceinline__ void gemm_phase(LAS unsigned char* lds, const Gemm g, const SchedT& S, const Epi& E, const int wid) {
;     ...
;         for (int t = 0; t < nt; t += 2) {
;             const bool last = (t == nt - 2);
;             const char* a1 = cA + (size_t)(t + 1) * kstep;
;             const char* a2 = last ? nA : cA + (size_t)(t + 2) * kstep; const char* b2 = last ? nB : cB + (size_t)(t + 2) * kstep;
;             const char* a3 = a2 + kstep; const char* b3 = b2 + kstep;
;             if constexpr (SP2) {
;     ...
;             PG8_LDB(B0, 0, 0); PG8_LDB(B1, 0, 1); PG8_SCHED; PG8_LDA(At, 0, 0); PG8_S1;
;             PG8_WAIT_V(8); PG8_WAIT_L(0); PG8_BAR; PG8_MMAP(0, 0, 0); PG8_BAR; PG8_SCHED;
;     ...
;             PG8_LDA(At, 1, 1); PG8_S4;
;             PG8_WAIT_V(8); PG8_WAIT_L(0); PG8_BAR; PG8_MMAP(1, 1, 1); PG8_BAR; PG8_SCHED;
	v_mov_b32_e32 v128, v135
	ds_read_b128 v[178:181], v143 offset:49152
	ds_read_b128 v[182:185], v143 offset:50176
	ds_read_b128 v[186:189], v143 offset:51200
	ds_read_b128 v[190:193], v143 offset:52224
	ds_read_b128 v[194:197], v143 offset:53248
	ds_read_b128 v[198:201], v143 offset:54272
	ds_read_b128 v[202:205], v143 offset:55296
	ds_read_b128 v[206:209], v143 offset:56320
	s_add_i32 s6, s6, s86
	v_lshl_add_u64 v[210:211], s[66:67], 0, v[128:129]
	v_lshl_add_u64 v[210:211], v[210:211], 0, s[36:37]
	s_mov_b32 m0, s6
	v_mov_b32_e32 v128, v137
	global_load_lds_dwordx4 v[210:211], off
	s_add_i32 m0, s6, 0x2000
	s_add_u32 s60, s66, 0x40080
	v_lshl_add_u64 v[210:211], s[66:67], 0, v[128:129]
	v_lshl_add_u64 v[210:211], v[210:211], 0, s[36:37]
	s_addc_u32 s61, s67, 0
	v_mov_b32_e32 v128, v135
	s_add_i32 s6, s7, s86
	global_load_lds_dwordx4 v[210:211], off
	s_mov_b32 m0, s6
	s_nop 0
	global_load_lds_dwordx4 v128, s[60:61]
	v_mov_b32_e32 v128, v137
	s_add_i32 m0, s6, 0x2000
	s_nop 0
	global_load_lds_dwordx4 v128, s[60:61]
	v_mov_b32_e32 v128, v134
	s_mov_b32 m0, s92
	v_lshl_add_u64 v[210:211], s[52:53], 0, v[128:129]
	v_lshl_add_u64 v[210:211], v[210:211], 0, s[36:37]
	v_mov_b32_e32 v128, v136
	global_load_lds_dwordx4 v[210:211], off
	s_mov_b32 m0, s93
	v_lshl_add_u64 v[210:211], s[52:53], 0, v[128:129]
	v_lshl_add_u64 v[210:211], v[210:211], 0, s[36:37]
	global_load_lds_dwordx4 v[210:211], off
	s_waitcnt vmcnt(8)
	s_waitcnt lgkmcnt(0)
	s_barrier
	s_setprio 1
	s_waitcnt lgkmcnt(0)
	v_mfma_f32_16x16x32_bf16 v[68:71], v[146:149], v[178:181], v[68:71]
	v_mfma_f32_16x16x32_bf16 v[64:67], v[154:157], v[178:181], v[64:67]
	v_mfma_f32_16x16x32_bf16 v[40:43], v[154:157], v[186:189], v[40:43]
	v_mfma_f32_16x16x32_bf16 v[44:47], v[146:149], v[186:189], v[44:47]
	v_mfma_f32_16x16x32_bf16 v[28:31], v[146:149], v[194:197], v[28:31]
	v_mfma_f32_16x16x32_bf16 v[24:27], v[154:157], v[194:197], v[24:27]
	v_mfma_f32_16x16x32_bf16 v[8:11], v[154:157], v[202:205], v[8:11]
	v_mfma_f32_16x16x32_bf16 v[12:15], v[146:149], v[202:205], v[12:15]
	v_mfma_f32_16x16x32_bf16 v[68:71], v[150:153], v[182:185], v[68:71]
	v_mfma_f32_16x16x32_bf16 v[64:67], v[158:161], v[182:185], v[64:67]
	v_mfma_f32_16x16x32_bf16 v[40:43], v[158:161], v[190:193], v[40:43]
	v_mfma_f32_16x16x32_bf16 v[44:47], v[150:153], v[190:193], v[44:47]
	v_mfma_f32_16x16x32_bf16 v[28:31], v[150:153], v[198:201], v[28:31]
	v_mfma_f32_16x16x32_bf16 v[24:27], v[158:161], v[198:201], v[24:27]
	v_mfma_f32_16x16x32_bf16 v[8:11], v[158:161], v[206:209], v[8:11]
	v_mfma_f32_16x16x32_bf16 v[12:15], v[150:153], v[206:209], v[12:15]
	s_setprio 0
	s_setprio 1
	v_mfma_f32_16x16x32_bf16 v[52:55], v[162:165], v[178:181], v[52:55]
	v_mfma_f32_16x16x32_bf16 v[48:51], v[170:173], v[178:181], v[48:51]
	v_mfma_f32_16x16x32_bf16 v[32:35], v[170:173], v[186:189], v[32:35]
	v_mfma_f32_16x16x32_bf16 v[36:39], v[162:165], v[186:189], v[36:39]
	v_mfma_f32_16x16x32_bf16 v[20:23], v[162:165], v[194:197], v[20:23]
	v_mfma_f32_16x16x32_bf16 v[16:19], v[170:173], v[194:197], v[16:19]
	v_mfma_f32_16x16x32_bf16 v[0:3], v[170:173], v[202:205], v[0:3]
	v_mfma_f32_16x16x32_bf16 v[4:7], v[162:165], v[202:205], v[4:7]
	v_mfma_f32_16x16x32_bf16 v[52:55], v[166:169], v[182:185], v[52:55]
	v_mfma_f32_16x16x32_bf16 v[48:51], v[174:177], v[182:185], v[48:51]
	v_mfma_f32_16x16x32_bf16 v[32:35], v[174:177], v[190:193], v[32:35]
	v_mfma_f32_16x16x32_bf16 v[36:39], v[166:169], v[190:193], v[36:39]
	v_mfma_f32_16x16x32_bf16 v[20:23], v[166:169], v[198:201], v[20:23]
	v_mfma_f32_16x16x32_bf16 v[16:19], v[174:177], v[198:201], v[16:19]
	v_mfma_f32_16x16x32_bf16 v[0:3], v[174:177], v[206:209], v[0:3]
	v_mfma_f32_16x16x32_bf16 v[4:7], v[166:169], v[206:209], v[4:7]
	s_setprio 0
	s_barrier
	s_add_u32 s50, s50, 0x100
	s_addc_u32 s51, s51, 0
	s_add_u32 s31, s31, 0x100
	s_addc_u32 s38, s38, 0
	s_cmp_ge_i32 s43, s8
	s_mov_b32 s39, s43
	s_cbranch_scc1 .Lpeel_exit_lbb0_256
.LBB0_256:
	ds_read_b128 v[146:149], v139
	ds_read_b128 v[150:153], v139 offset:1024
	ds_read_b128 v[154:157], v140
	ds_read_b128 v[158:161], v140 offset:1024
	ds_read_b128 v[162:165], v141
	ds_read_b128 v[166:169], v141 offset:1024
	ds_read_b128 v[170:173], v142
	ds_read_b128 v[174:177], v142 offset:1024
	s_add_i32 s43, s39, 2
	s_add_u32 s6, s50, 0xfffc0080
	s_addc_u32 s7, s51, -1
	s_cmp_eq_u32 s30, s39
	s_cselect_b32 s53, s9, s7
	s_cselect_b32 s52, s20, s6
	s_cselect_b32 s67, s21, s38
	s_cselect_b32 s66, s24, s31
	v_mov_b32_e32 v128, v134
	ds_read_b128 v[178:181], v143
	ds_read_b128 v[182:185], v143 offset:1024
	ds_read_b128 v[186:189], v143 offset:2048
	ds_read_b128 v[190:193], v143 offset:3072
	ds_read_b128 v[194:197], v143 offset:4096
	ds_read_b128 v[198:201], v143 offset:5120
	ds_read_b128 v[202:205], v143 offset:6144
	ds_read_b128 v[206:209], v143 offset:7168
	s_add_i32 m0, s87, 0xc000
	s_nop 0
	global_load_lds_dwordx4 v128, s[50:51]
	v_mov_b32_e32 v128, v136
	s_add_i32 m0, s87, 0xe000
	s_nop 0
	global_load_lds_dwordx4 v128, s[50:51]
	s_waitcnt vmcnt(8)
	s_waitcnt lgkmcnt(0)
	s_barrier
; #define PG8_LDA(dst, b, h) do { if constexpr (FP8) { _Pragma("unroll") for (int m = 0; m < 4; ++m) dst##8[m] = PG8_LD8(PG8_SA(b, h), aoff, aoff1, m); } \
;         else { _Pragma("unroll") for (int m = 0; m < 4; ++m) _Pragma("unroll") for (int k = 0; k < 2; ++k) dst[m][k] = *(const LAS bf16x8*)(lds + PG8_SA(b, h) + (k ? aoff1 : aoff) + m * 2048); } } while (0)
; #define PG8_LDB(dst, b, h) do { if constexpr (FP8) { dst##8[0] = PG8_LD8(PG8_SB(b, h), boff, boff1, 0); dst##8[1] = PG8_LD8(PG8_SB(b, h), boff, boff1, 1); } \
;         else { _Pragma("unroll") for (int n = 0; n < 2; ++n) _Pragma("unroll") for (int k = 0; k < 2; ++k) dst[n][k] = *(const LAS bf16x8*)(lds + PG8_SB(b, h) + (k ? boff1 : boff) + n * 2048); } } while (0)
; #define PG8_WAIT_V(n) asm volatile("s_waitcnt vmcnt(" #n ")" ::: "memory")
; #define PG8_WAIT_L(n) asm volatile("s_waitcnt lgkmcnt(" #n ")" ::: "memory")
; #define PG8_BAR __builtin_amdgcn_s_barrier()
; #define PG8_SCHED __builtin_amdgcn_sched_barrier(0)
; #define PG8_S2 do { PG8_STAGE(PG8_SB(0, 0), b2, voffB); PG8_STAGE(PG8_SB(0, 1), b2 + hstepB, voffB); PG8_STAGE(PG8_SA(0, 0), a2, voffA); } while (0)
; #define PG8_S3 PG8_STAGE(PG8_SA(0, 1), a2 + hstepA, voffA)
; template <class Epi, class SchedT, bool ALIGN_EPI, bool SP2, bool FP8 = false>
; __device__ __forceinline__ void gemm_phase(LAS unsigned char* lds, const Gemm g, const SchedT& S, const Epi& E, const int wid) {
;     ...
;             PG8_WAIT_V(8); PG8_WAIT_L(0); PG8_BAR; PG8_MMAP(0, 0, 0); PG8_BAR; PG8_SCHED;
;             PG8_LDA(At, 0, 1); PG8_S2;
;             PG8_WAIT_V(8); PG8_WAIT_L(0); PG8_BAR; PG8_MMAP(1, 0, 1); PG8_BAR; PG8_SCHED;
;             PG8_LDB(B0, 1, 0); PG8_LDB(B1, 1, 1); PG8_SCHED; PG8_LDA(At, 1, 0); PG8_S3;
;             PG8_WAIT_V(8); PG8_WAIT_L(0); PG8_BAR; PG8_MMAP(0, 1, 0); PG8_BAR; PG8_SCHED;
	s_setprio 1
	s_waitcnt lgkmcnt(0)
	v_mfma_f32_16x16x32_bf16 v[124:127], v[146:149], v[178:181], v[124:127]
	v_mfma_f32_16x16x32_bf16 v[120:123], v[154:157], v[178:181], v[120:123]
	v_mfma_f32_16x16x32_bf16 v[104:107], v[154:157], v[186:189], v[104:107]
	v_mfma_f32_16x16x32_bf16 v[108:111], v[146:149], v[186:189], v[108:111]
	v_mfma_f32_16x16x32_bf16 v[92:95], v[146:149], v[194:197], v[92:95]
	v_mfma_f32_16x16x32_bf16 v[88:91], v[154:157], v[194:197], v[88:91]
	v_mfma_f32_16x16x32_bf16 v[72:75], v[154:157], v[202:205], v[72:75]
	v_mfma_f32_16x16x32_bf16 v[76:79], v[146:149], v[202:205], v[76:79]
	v_mfma_f32_16x16x32_bf16 v[124:127], v[150:153], v[182:185], v[124:127]
	v_mfma_f32_16x16x32_bf16 v[120:123], v[158:161], v[182:185], v[120:123]
	v_mfma_f32_16x16x32_bf16 v[104:107], v[158:161], v[190:193], v[104:107]
	v_mfma_f32_16x16x32_bf16 v[108:111], v[150:153], v[190:193], v[108:111]
	v_mfma_f32_16x16x32_bf16 v[92:95], v[150:153], v[198:201], v[92:95]
	v_mfma_f32_16x16x32_bf16 v[88:91], v[158:161], v[198:201], v[88:91]
	v_mfma_f32_16x16x32_bf16 v[72:75], v[158:161], v[206:209], v[72:75]
	v_mfma_f32_16x16x32_bf16 v[76:79], v[150:153], v[206:209], v[76:79]
	s_setprio 0
	s_setprio 1
	v_mfma_f32_16x16x32_bf16 v[116:119], v[162:165], v[178:181], v[116:119]
	v_mfma_f32_16x16x32_bf16 v[112:115], v[170:173], v[178:181], v[112:115]
	v_mfma_f32_16x16x32_bf16 v[96:99], v[170:173], v[186:189], v[96:99]
	v_mfma_f32_16x16x32_bf16 v[100:103], v[162:165], v[186:189], v[100:103]
	v_mfma_f32_16x16x32_bf16 v[84:87], v[162:165], v[194:197], v[84:87]
	v_mfma_f32_16x16x32_bf16 v[80:83], v[170:173], v[194:197], v[80:83]
	v_mfma_f32_16x16x32_bf16 v[56:59], v[170:173], v[202:205], v[56:59]
	v_mfma_f32_16x16x32_bf16 v[60:63], v[162:165], v[202:205], v[60:63]
	v_mfma_f32_16x16x32_bf16 v[116:119], v[166:169], v[182:185], v[116:119]
	v_mfma_f32_16x16x32_bf16 v[112:115], v[174:177], v[182:185], v[112:115]
	v_mfma_f32_16x16x32_bf16 v[96:99], v[174:177], v[190:193], v[96:99]
	v_mfma_f32_16x16x32_bf16 v[100:103], v[166:169], v[190:193], v[100:103]
	v_mfma_f32_16x16x32_bf16 v[84:87], v[166:169], v[198:201], v[84:87]
	v_mfma_f32_16x16x32_bf16 v[80:83], v[174:177], v[198:201], v[80:83]
	v_mfma_f32_16x16x32_bf16 v[56:59], v[174:177], v[206:209], v[56:59]
	v_mfma_f32_16x16x32_bf16 v[60:63], v[166:169], v[206:209], v[60:63]
	s_setprio 0
	s_barrier
	v_mov_b32_e32 v128, v135
	s_add_i32 s6, s94, s86
	ds_read_b128 v[178:181], v143 offset:16384
	ds_read_b128 v[182:185], v143 offset:17408
	ds_read_b128 v[186:189], v143 offset:18432
	ds_read_b128 v[190:193], v143 offset:19456
	ds_read_b128 v[194:197], v143 offset:20480
	ds_read_b128 v[198:201], v143 offset:21504
	ds_read_b128 v[202:205], v143 offset:22528
	ds_read_b128 v[206:209], v143 offset:23552
	s_mov_b32 m0, s6
	s_nop 0
	global_load_lds_dwordx4 v128, s[66:67]
	v_mov_b32_e32 v128, v137
	s_add_i32 m0, s6, 0x2000
	s_add_u32 s60, s66, 0x40000
	global_load_lds_dwordx4 v128, s[66:67]
	s_addc_u32 s61, s67, 0
	v_mov_b32_e32 v128, v135
	s_add_i32 s6, s95, s86
	s_mov_b32 m0, s6
	s_nop 0
	global_load_lds_dwordx4 v128, s[60:61]
	v_mov_b32_e32 v128, v137
	s_add_i32 m0, s6, 0x2000
	s_nop 0
	global_load_lds_dwordx4 v128, s[60:61]
	v_mov_b32_e32 v128, v134
	s_mov_b32 m0, s87
	s_nop 0
	global_load_lds_dwordx4 v128, s[52:53]
	v_mov_b32_e32 v128, v136
	s_mov_b32 m0, s88
	s_nop 0
	global_load_lds_dwordx4 v128, s[52:53]
	s_waitcnt vmcnt(8)
	s_waitcnt lgkmcnt(0)
	s_barrier
	s_setprio 1
	s_waitcnt lgkmcnt(0)
	v_mfma_f32_16x16x32_bf16 v[68:71], v[146:149], v[178:181], v[68:71]
	v_mfma_f32_16x16x32_bf16 v[64:67], v[154:157], v[178:181], v[64:67]
	v_mfma_f32_16x16x32_bf16 v[40:43], v[154:157], v[186:189], v[40:43]
	v_mfma_f32_16x16x32_bf16 v[44:47], v[146:149], v[186:189], v[44:47]
	v_mfma_f32_16x16x32_bf16 v[28:31], v[146:149], v[194:197], v[28:31]
	v_mfma_f32_16x16x32_bf16 v[24:27], v[154:157], v[194:197], v[24:27]
	v_mfma_f32_16x16x32_bf16 v[8:11], v[154:157], v[202:205], v[8:11]
	v_mfma_f32_16x16x32_bf16 v[12:15], v[146:149], v[202:205], v[12:15]
	v_mfma_f32_16x16x32_bf16 v[68:71], v[150:153], v[182:185], v[68:71]
	v_mfma_f32_16x16x32_bf16 v[64:67], v[158:161], v[182:185], v[64:67]
	v_mfma_f32_16x16x32_bf16 v[40:43], v[158:161], v[190:193], v[40:43]
	v_mfma_f32_16x16x32_bf16 v[44:47], v[150:153], v[190:193], v[44:47]
	v_mfma_f32_16x16x32_bf16 v[28:31], v[150:153], v[198:201], v[28:31]
	v_mfma_f32_16x16x32_bf16 v[24:27], v[158:161], v[198:201], v[24:27]
	v_mfma_f32_16x16x32_bf16 v[8:11], v[158:161], v[206:209], v[8:11]
	v_mfma_f32_16x16x32_bf16 v[12:15], v[150:153], v[206:209], v[12:15]
	s_setprio 0
	s_setprio 1
	v_mfma_f32_16x16x32_bf16 v[52:55], v[162:165], v[178:181], v[52:55]
	v_mfma_f32_16x16x32_bf16 v[48:51], v[170:173], v[178:181], v[48:51]
	v_mfma_f32_16x16x32_bf16 v[32:35], v[170:173], v[186:189], v[32:35]
	v_mfma_f32_16x16x32_bf16 v[36:39], v[162:165], v[186:189], v[36:39]
	v_mfma_f32_16x16x32_bf16 v[20:23], v[162:165], v[194:197], v[20:23]
	v_mfma_f32_16x16x32_bf16 v[16:19], v[170:173], v[194:197], v[16:19]
	v_mfma_f32_16x16x32_bf16 v[0:3], v[170:173], v[202:205], v[0:3]
	v_mfma_f32_16x16x32_bf16 v[4:7], v[162:165], v[202:205], v[4:7]
	v_mfma_f32_16x16x32_bf16 v[52:55], v[166:169], v[182:185], v[52:55]
	v_mfma_f32_16x16x32_bf16 v[48:51], v[174:177], v[182:185], v[48:51]
	v_mfma_f32_16x16x32_bf16 v[32:35], v[174:177], v[190:193], v[32:35]
	v_mfma_f32_16x16x32_bf16 v[36:39], v[166:169], v[190:193], v[36:39]
	v_mfma_f32_16x16x32_bf16 v[20:23], v[166:169], v[198:201], v[20:23]
	v_mfma_f32_16x16x32_bf16 v[16:19], v[174:177], v[198:201], v[16:19]
	v_mfma_f32_16x16x32_bf16 v[0:3], v[174:177], v[206:209], v[0:3]
	v_mfma_f32_16x16x32_bf16 v[4:7], v[166:169], v[206:209], v[4:7]
	s_setprio 0
	s_barrier
; #define PG8_LDA(dst, b, h) do { if constexpr (FP8) { _Pragma("unroll") for (int m = 0; m < 4; ++m) dst##8[m] = PG8_LD8(PG8_SA(b, h), aoff, aoff1, m); } \
;         else { _Pragma("unroll") for (int m = 0; m < 4; ++m) _Pragma("unroll") for (int k = 0; k < 2; ++k) dst[m][k] = *(const LAS bf16x8*)(lds + PG8_SA(b, h) + (k ? aoff1 : aoff) + m * 2048); } } while (0)
; #define PG8_LDB(dst, b, h) do { if constexpr (FP8) { dst##8[0] = PG8_LD8(PG8_SB(b, h), boff, boff1, 0); dst##8[1] = PG8_LD8(PG8_SB(b, h), boff, boff1, 1); } \
;         else { _Pragma("unroll") for (int n = 0; n < 2; ++n) _Pragma("unroll") for (int k = 0; k < 2; ++k) dst[n][k] = *(const LAS bf16x8*)(lds + PG8_SB(b, h) + (k ? boff1 : boff) + n * 2048); } } while (0)
; #define PG8_WAIT_V(n) asm volatile("s_waitcnt vmcnt(" #n ")" ::: "memory")
; #define PG8_WAIT_L(n) asm volatile("s_waitcnt lgkmcnt(" #n ")" ::: "memory")
; #define PG8_BAR __builtin_amdgcn_s_barrier()
; #define PG8_SCHED __builtin_amdgcn_sched_barrier(0)
; #define PG8_S3 PG8_STAGE(PG8_SA(0, 1), a2 + hstepA, voffA)
; template <class Epi, class SchedT, bool ALIGN_EPI, bool SP2, bool FP8 = false>
; __device__ __forceinline__ void gemm_phase(LAS unsigned char* lds, const Gemm g, const SchedT& S, const Epi& E, const int wid) {
;     ...
;             PG8_LDB(B0, 1, 0); PG8_LDB(B1, 1, 1); PG8_SCHED; PG8_LDA(At, 1, 0); PG8_S3;
;             PG8_WAIT_V(8); PG8_WAIT_L(0); PG8_BAR; PG8_MMAP(0, 1, 0); PG8_BAR; PG8_SCHED;
	s_add_i32 s6, 0, 0x18000
	v_add_u32_e32 v128, s6, v138
	s_add_i32 s7, 0, 0x1c000
	ds_read_b128 v[146:149], v128
	ds_read_b128 v[150:153], v128 offset:1024
	ds_read_b128 v[154:157], v144
	ds_read_b128 v[158:161], v144 offset:1024
	v_add_u32_e32 v128, s7, v138
	ds_read_b128 v[162:165], v128
	ds_read_b128 v[166:169], v128 offset:1024
	ds_read_b128 v[170:173], v145
	ds_read_b128 v[174:177], v145 offset:1024
	s_add_u32 s60, s52, 0x40000
	v_mov_b32_e32 v128, v134
	s_mov_b32 m0, s89
	ds_read_b128 v[178:181], v143 offset:32768
	ds_read_b128 v[182:185], v143 offset:33792
	ds_read_b128 v[186:189], v143 offset:34816
	ds_read_b128 v[190:193], v143 offset:35840
	ds_read_b128 v[194:197], v143 offset:36864
	ds_read_b128 v[198:201], v143 offset:37888
	ds_read_b128 v[202:205], v143 offset:38912
	ds_read_b128 v[206:209], v143 offset:39936
	s_addc_u32 s61, s53, 0
	s_nop 0
	global_load_lds_dwordx4 v128, s[60:61]
	v_mov_b32_e32 v128, v136
	s_mov_b32 m0, s90
	s_nop 0
	global_load_lds_dwordx4 v128, s[60:61]
	s_waitcnt vmcnt(8)
	s_waitcnt lgkmcnt(0)
	s_barrier
	s_setprio 1
	s_waitcnt lgkmcnt(0)
	v_mfma_f32_16x16x32_bf16 v[124:127], v[146:149], v[178:181], v[124:127]
	v_mfma_f32_16x16x32_bf16 v[120:123], v[154:157], v[178:181], v[120:123]
	v_mfma_f32_16x16x32_bf16 v[104:107], v[154:157], v[186:189], v[104:107]
	v_mfma_f32_16x16x32_bf16 v[108:111], v[146:149], v[186:189], v[108:111]
	v_mfma_f32_16x16x32_bf16 v[92:95], v[146:149], v[194:197], v[92:95]
	v_mfma_f32_16x16x32_bf16 v[88:91], v[154:157], v[194:197], v[88:91]
	v_mfma_f32_16x16x32_bf16 v[72:75], v[154:157], v[202:205], v[72:75]
	v_mfma_f32_16x16x32_bf16 v[76:79], v[146:149], v[202:205], v[76:79]
	v_mfma_f32_16x16x32_bf16 v[124:127], v[150:153], v[182:185], v[124:127]
	v_mfma_f32_16x16x32_bf16 v[120:123], v[158:161], v[182:185], v[120:123]
	v_mfma_f32_16x16x32_bf16 v[104:107], v[158:161], v[190:193], v[104:107]
	v_mfma_f32_16x16x32_bf16 v[108:111], v[150:153], v[190:193], v[108:111]
	v_mfma_f32_16x16x32_bf16 v[92:95], v[150:153], v[198:201], v[92:95]
	v_mfma_f32_16x16x32_bf16 v[88:91], v[158:161], v[198:201], v[88:91]
	v_mfma_f32_16x16x32_bf16 v[72:75], v[158:161], v[206:209], v[72:75]
	v_mfma_f32_16x16x32_bf16 v[76:79], v[150:153], v[206:209], v[76:79]
	s_setprio 0
	s_setprio 1
	v_mfma_f32_16x16x32_bf16 v[116:119], v[162:165], v[178:181], v[116:119]
	v_mfma_f32_16x16x32_bf16 v[112:115], v[170:173], v[178:181], v[112:115]
	v_mfma_f32_16x16x32_bf16 v[96:99], v[170:173], v[186:189], v[96:99]
	v_mfma_f32_16x16x32_bf16 v[100:103], v[162:165], v[186:189], v[100:103]
	v_mfma_f32_16x16x32_bf16 v[84:87], v[162:165], v[194:197], v[84:87]
	v_mfma_f32_16x16x32_bf16 v[80:83], v[170:173], v[194:197], v[80:83]
	v_mfma_f32_16x16x32_bf16 v[56:59], v[170:173], v[202:205], v[56:59]
	v_mfma_f32_16x16x32_bf16 v[60:63], v[162:165], v[202:205], v[60:63]
	v_mfma_f32_16x16x32_bf16 v[116:119], v[166:169], v[182:185], v[116:119]
	v_mfma_f32_16x16x32_bf16 v[112:115], v[174:177], v[182:185], v[112:115]
	v_mfma_f32_16x16x32_bf16 v[96:99], v[174:177], v[190:193], v[96:99]
	v_mfma_f32_16x16x32_bf16 v[100:103], v[166:169], v[190:193], v[100:103]
	v_mfma_f32_16x16x32_bf16 v[84:87], v[166:169], v[198:201], v[84:87]
	v_mfma_f32_16x16x32_bf16 v[80:83], v[174:177], v[198:201], v[80:83]
	v_mfma_f32_16x16x32_bf16 v[56:59], v[174:177], v[206:209], v[56:59]
	v_mfma_f32_16x16x32_bf16 v[60:63], v[166:169], v[206:209], v[60:63]
	s_setprio 0
	s_barrier
; #define PG8_LDA(dst, b, h) do { if constexpr (FP8) { _Pragma("unroll") for (int m = 0; m < 4; ++m) dst##8[m] = PG8_LD8(PG8_SA(b, h), aoff, aoff1, m); } \
;         else { _Pragma("unroll") for (int m = 0; m < 4; ++m) _Pragma("unroll") for (int k = 0; k < 2; ++k) dst[m][k] = *(const LAS bf16x8*)(lds + PG8_SA(b, h) + (k ? aoff1 : aoff) + m * 2048); } } while (0)
; #define PG8_WAIT_V(n) asm volatile("s_waitcnt vmcnt(" #n ")" ::: "memory")
; #define PG8_WAIT_L(n) asm volatile("s_waitcnt lgkmcnt(" #n ")" ::: "memory")
; #define PG8_BAR __builtin_amdgcn_s_barrier()
; #define PG8_SCHED __builtin_amdgcn_sched_barrier(0)
; #define PG8_S4 do { PG8_STAGE(PG8_SB(1, 0), b3, voffB); PG8_STAGE(PG8_SB(1, 1), b3 + hstepB, voffB); PG8_STAGE(PG8_SA(1, 0), a3, voffA); } while (0)
; template <class Epi, class SchedT, bool ALIGN_EPI, bool SP2, bool FP8 = false>
; __device__ __forceinline__ void gemm_phase(LAS unsigned char* lds, const Gemm g, const SchedT& S, const Epi& E, const int wid) {
;     ...
;             PG8_LDA(At, 1, 1); PG8_S4;
;             PG8_WAIT_V(8); PG8_WAIT_L(0); PG8_BAR; PG8_MMAP(1, 1, 1); PG8_BAR; PG8_SCHED;
;     ...
;         if constexpr (ALIGN_EPI) { if (wr == 0) PG8_BAR; }
	v_mov_b32_e32 v128, v135
	ds_read_b128 v[178:181], v143 offset:49152
	ds_read_b128 v[182:185], v143 offset:50176
	ds_read_b128 v[186:189], v143 offset:51200
	ds_read_b128 v[190:193], v143 offset:52224
	ds_read_b128 v[194:197], v143 offset:53248
	ds_read_b128 v[198:201], v143 offset:54272
	ds_read_b128 v[202:205], v143 offset:55296
	ds_read_b128 v[206:209], v143 offset:56320
	s_add_i32 s6, s6, s86
	v_lshl_add_u64 v[210:211], s[66:67], 0, v[128:129]
	v_lshl_add_u64 v[210:211], v[210:211], 0, s[36:37]
	s_mov_b32 m0, s6
	v_mov_b32_e32 v128, v137
	global_load_lds_dwordx4 v[210:211], off
	s_add_i32 m0, s6, 0x2000
	s_add_u32 s60, s66, 0x40080
	v_lshl_add_u64 v[210:211], s[66:67], 0, v[128:129]
	v_lshl_add_u64 v[210:211], v[210:211], 0, s[36:37]
	s_addc_u32 s61, s67, 0
	v_mov_b32_e32 v128, v135
	s_add_i32 s6, s7, s86
	global_load_lds_dwordx4 v[210:211], off
	s_mov_b32 m0, s6
	s_nop 0
	global_load_lds_dwordx4 v128, s[60:61]
	v_mov_b32_e32 v128, v137
	s_add_i32 m0, s6, 0x2000
	s_nop 0
	global_load_lds_dwordx4 v128, s[60:61]
	v_mov_b32_e32 v128, v134
	s_mov_b32 m0, s92
	v_lshl_add_u64 v[210:211], s[52:53], 0, v[128:129]
	v_lshl_add_u64 v[210:211], v[210:211], 0, s[36:37]
	v_mov_b32_e32 v128, v136
	global_load_lds_dwordx4 v[210:211], off
	s_mov_b32 m0, s93
	v_lshl_add_u64 v[210:211], s[52:53], 0, v[128:129]
	v_lshl_add_u64 v[210:211], v[210:211], 0, s[36:37]
	global_load_lds_dwordx4 v[210:211], off
	s_waitcnt vmcnt(8)
	s_waitcnt lgkmcnt(0)
	s_barrier
	s_setprio 1
	s_waitcnt lgkmcnt(0)
	v_mfma_f32_16x16x32_bf16 v[68:71], v[146:149], v[178:181], v[68:71]
	v_mfma_f32_16x16x32_bf16 v[64:67], v[154:157], v[178:181], v[64:67]
	v_mfma_f32_16x16x32_bf16 v[40:43], v[154:157], v[186:189], v[40:43]
	v_mfma_f32_16x16x32_bf16 v[44:47], v[146:149], v[186:189], v[44:47]
	v_mfma_f32_16x16x32_bf16 v[28:31], v[146:149], v[194:197], v[28:31]
	v_mfma_f32_16x16x32_bf16 v[24:27], v[154:157], v[194:197], v[24:27]
	v_mfma_f32_16x16x32_bf16 v[8:11], v[154:157], v[202:205], v[8:11]
	v_mfma_f32_16x16x32_bf16 v[12:15], v[146:149], v[202:205], v[12:15]
	v_mfma_f32_16x16x32_bf16 v[68:71], v[150:153], v[182:185], v[68:71]
	v_mfma_f32_16x16x32_bf16 v[64:67], v[158:161], v[182:185], v[64:67]
	v_mfma_f32_16x16x32_bf16 v[40:43], v[158:161], v[190:193], v[40:43]
	v_mfma_f32_16x16x32_bf16 v[44:47], v[150:153], v[190:193], v[44:47]
	v_mfma_f32_16x16x32_bf16 v[28:31], v[150:153], v[198:201], v[28:31]
	v_mfma_f32_16x16x32_bf16 v[24:27], v[158:161], v[198:201], v[24:27]
	v_mfma_f32_16x16x32_bf16 v[8:11], v[158:161], v[206:209], v[8:11]
	v_mfma_f32_16x16x32_bf16 v[12:15], v[150:153], v[206:209], v[12:15]
	s_setprio 0
	s_setprio 1
	v_mfma_f32_16x16x32_bf16 v[52:55], v[162:165], v[178:181], v[52:55]
	v_mfma_f32_16x16x32_bf16 v[48:51], v[170:173], v[178:181], v[48:51]
	v_mfma_f32_16x16x32_bf16 v[32:35], v[170:173], v[186:189], v[32:35]
	v_mfma_f32_16x16x32_bf16 v[36:39], v[162:165], v[186:189], v[36:39]
	v_mfma_f32_16x16x32_bf16 v[20:23], v[162:165], v[194:197], v[20:23]
	v_mfma_f32_16x16x32_bf16 v[16:19], v[170:173], v[194:197], v[16:19]
	v_mfma_f32_16x16x32_bf16 v[0:3], v[170:173], v[202:205], v[0:3]
	v_mfma_f32_16x16x32_bf16 v[4:7], v[162:165], v[202:205], v[4:7]
	v_mfma_f32_16x16x32_bf16 v[52:55], v[166:169], v[182:185], v[52:55]
	v_mfma_f32_16x16x32_bf16 v[48:51], v[174:177], v[182:185], v[48:51]
	v_mfma_f32_16x16x32_bf16 v[32:35], v[174:177], v[190:193], v[32:35]
	v_mfma_f32_16x16x32_bf16 v[36:39], v[166:169], v[190:193], v[36:39]
	v_mfma_f32_16x16x32_bf16 v[20:23], v[166:169], v[198:201], v[20:23]
	v_mfma_f32_16x16x32_bf16 v[16:19], v[174:177], v[198:201], v[16:19]
	v_mfma_f32_16x16x32_bf16 v[0:3], v[174:177], v[206:209], v[0:3]
	v_mfma_f32_16x16x32_bf16 v[4:7], v[166:169], v[206:209], v[4:7]
	s_setprio 0
	s_barrier
	s_add_u32 s50, s50, 0x100
	s_addc_u32 s51, s51, 0
	s_add_u32 s31, s31, 0x100
	s_addc_u32 s38, s38, 0
	s_cmp_ge_i32 s43, s8
	s_mov_b32 s39, s43
	s_cbranch_scc0 .LBB0_256
.Lpeel_exit_lbb0_256:
	s_and_b64 vcc, exec, s[96:97]
	s_cbranch_vccz .LBB0_259
.LBB0_258:
	s_barrier

; #define PG8_LDA(dst, b, h) do { if constexpr (FP8) { _Pragma("unroll") for (int m = 0; m < 4; ++m) dst##8[m] = PG8_LD8(PG8_SA(b, h), aoff, aoff1, m); } \
;         else { _Pragma("unroll") for (int m = 0; m < 4; ++m) _Pragma("unroll") for (int k = 0; k < 2; ++k) dst[m][k] = *(const LAS bf16x8*)(lds + PG8_SA(b, h) + (k ? aoff1 : aoff) + m * 2048); } } while (0)
; #define PG8_LDB(dst, b, h) do { if constexpr (FP8) { dst##8[0] = PG8_LD8(PG8_SB(b, h), boff, boff1, 0); dst##8[1] = PG8_LD8(PG8_SB(b, h), boff, boff1, 1); } \
;         else { _Pragma("unroll") for (int n = 0; n < 2; ++n) _Pragma("unroll") for (int k = 0; k < 2; ++k) dst[n][k] = *(const LAS bf16x8*)(lds + PG8_SB(b, h) + (k ? boff1 : boff) + n * 2048); } } while (0)
; #define PG8_WAIT_V(n) asm volatile("s_waitcnt vmcnt(" #n ")" ::: "memory")
; #define PG8_WAIT_L(n) asm volatile("s_waitcnt lgkmcnt(" #n ")" ::: "memory")
; #define PG8_BAR __builtin_amdgcn_s_barrier()
; #define PG8_SCHED __builtin_amdgcn_sched_barrier(0)
; #define PG8_S1 PG8_STAGE(PG8_SA(1, 1), a1 + hstepA, voffA)
; template <class Epi, class SchedT, bool ALIGN_EPI, bool SP2, bool FP8 = false>
; __device__ __forceinline__ void gemm_phase(LAS unsigned char* lds, const Gemm g, const SchedT& S, const Epi& E, const int wid) {
;     ...
;         const bool has_next = S.next(ui + 1, nxt);
;         const char* nA = has_next ? (const char*)g.A + (size_t)nxt.pm * tstepA + (size_t)nxt.aoff * 2 : cA; const char* nB = has_next ? (const char*)g.Bt + (size_t)nxt.pn * tstepB + (size_t)nxt.boff * 2 : cB;
;         const int nt = cur.nt;
;         for (int t = 0; t < nt; t += 2) {
;             const bool last = (t == nt - 2);
;             const char* a1 = cA + (size_t)(t + 1) * kstep;
;             const char* a2 = last ? nA : cA + (size_t)(t + 2) * kstep; const char* b2 = last ? nB : cB + (size_t)(t + 2) * kstep;
;             const char* a3 = a2 + kstep; const char* b3 = b2 + kstep;
;             if constexpr (SP2) {
;     ...
;             PG8_LDB(B0, 0, 0); PG8_LDB(B1, 0, 1); PG8_SCHED; PG8_LDA(At, 0, 0); PG8_S1;
;             PG8_WAIT_V(8); PG8_WAIT_L(0); PG8_BAR; PG8_MMAP(0, 0, 0); PG8_BAR; PG8_SCHED;
;             PG8_LDA(At, 0, 1); PG8_S2;
;             PG8_WAIT_V(8); PG8_WAIT_L(0); PG8_BAR; PG8_MMAP(1, 0, 1); PG8_BAR; PG8_SCHED;
.LBB0_538:
	s_add_i32 s20, s71, -2
	s_add_u32 s8, s66, 0x90080
	s_addc_u32 s9, s67, 0
	s_add_u32 s21, s10, 0x100
	s_addc_u32 s24, s11, 0
	s_mov_b32 s10, 0
	ds_read_b128 v[134:137], v215
	ds_read_b128 v[138:141], v215 offset:16
	ds_read_b128 v[142:145], v215 offset:2048
	ds_read_b128 v[146:149], v215 offset:2064
	ds_read_b128 v[150:153], v216
	ds_read_b128 v[154:157], v216 offset:16
	ds_read_b128 v[158:161], v216 offset:2048
	ds_read_b128 v[162:165], v216 offset:2064
	s_add_i32 s30, s10, 2
	s_add_u32 s16, s8, 0xfff70080
	s_addc_u32 s11, s9, -1
	s_cmp_eq_u32 s20, s10
	s_cselect_b32 s10, s52, s16
	s_cselect_b32 s11, s53, s11
	v_mov_b32_e32 v128, v210
	ds_read_b128 v[166:169], v217
	ds_read_b128 v[170:173], v217 offset:16
	ds_read_b128 v[174:177], v217 offset:2048
	ds_read_b128 v[178:181], v217 offset:2064
	ds_read_b128 v[182:185], v217 offset:4096
	ds_read_b128 v[186:189], v217 offset:4112
	ds_read_b128 v[190:193], v217 offset:6144
	ds_read_b128 v[194:197], v217 offset:6160
	s_cselect_b32 s67, s65, s24
	s_cselect_b32 s66, s64, s21
	s_add_i32 m0, s87, 0xc000
	s_nop 0
	global_load_lds_dwordx4 v128, s[8:9]
	v_mov_b32_e32 v128, v212
	s_add_i32 m0, s87, 0xe000
	s_nop 0
	global_load_lds_dwordx4 v128, s[8:9]
	s_waitcnt vmcnt(8)
	s_waitcnt lgkmcnt(0)
	s_barrier
	s_setprio 1
	s_waitcnt lgkmcnt(0)
	v_mfma_scale_f32_16x16x128_f8f6f4 v[124:127], v[134:141], v[166:173], 0, v218, v218 op_sel_hi:[0,0,0]
	v_mfma_scale_f32_16x16x128_f8f6f4 v[120:123], v[142:149], v[166:173], 0, v218, v218 op_sel_hi:[0,0,0]
	v_mfma_scale_f32_16x16x128_f8f6f4 v[116:119], v[134:141], v[174:181], 0, v218, v218 op_sel_hi:[0,0,0]
	v_mfma_scale_f32_16x16x128_f8f6f4 v[112:115], v[142:149], v[174:181], 0, v218, v218 op_sel_hi:[0,0,0]
	v_mfma_scale_f32_16x16x128_f8f6f4 v[108:111], v[134:141], v[182:189], 0, v218, v218 op_sel_hi:[0,0,0]
	v_mfma_scale_f32_16x16x128_f8f6f4 v[104:107], v[142:149], v[182:189], 0, v218, v218 op_sel_hi:[0,0,0]
	v_mfma_scale_f32_16x16x128_f8f6f4 v[100:103], v[134:141], v[190:197], 0, v218, v218 op_sel_hi:[0,0,0]
	v_mfma_scale_f32_16x16x128_f8f6f4 v[96:99], v[142:149], v[190:197], 0, v218, v218 op_sel_hi:[0,0,0]
	v_mfma_scale_f32_16x16x128_f8f6f4 v[198:201], v[150:157], v[166:173], 0, v218, v218 op_sel_hi:[0,0,0]
	v_mfma_scale_f32_16x16x128_f8f6f4 v[166:169], v[158:165], v[166:173], 0, v218, v218 op_sel_hi:[0,0,0]
	v_mfma_scale_f32_16x16x128_f8f6f4 v[170:173], v[150:157], v[174:181], 0, v218, v218 op_sel_hi:[0,0,0]
	v_mfma_scale_f32_16x16x128_f8f6f4 v[174:177], v[158:165], v[174:181], 0, v218, v218 op_sel_hi:[0,0,0]
	v_mfma_scale_f32_16x16x128_f8f6f4 v[178:181], v[150:157], v[182:189], 0, v218, v218 op_sel_hi:[0,0,0]
	v_mfma_scale_f32_16x16x128_f8f6f4 v[182:185], v[158:165], v[182:189], 0, v218, v218 op_sel_hi:[0,0,0]
	v_mfma_scale_f32_16x16x128_f8f6f4 v[186:189], v[150:157], v[190:197], 0, v218, v218 op_sel_hi:[0,0,0]
	v_mfma_scale_f32_16x16x128_f8f6f4 v[190:193], v[158:165], v[190:197], 0, v218, v218 op_sel_hi:[0,0,0]
	s_setprio 0
	s_barrier
	v_mov_b32_e32 v128, v211
	s_add_i32 s16, s94, s86
	s_nop 2
	ds_read_b128 v[64:67], v217 offset:16384
	ds_read_b128 v[68:71], v217 offset:16400
	ds_read_b128 v[72:75], v217 offset:18432
	ds_read_b128 v[76:79], v217 offset:18448
	ds_read_b128 v[80:83], v217 offset:20480
	ds_read_b128 v[84:87], v217 offset:20496
	ds_read_b128 v[88:91], v217 offset:22528
	ds_read_b128 v[92:95], v217 offset:22544
	s_mov_b32 m0, s16
	s_nop 0
	global_load_lds_dwordx4 v128, s[66:67]
	v_mov_b32_e32 v128, v213
	s_add_i32 m0, s16, 0x2000
	s_add_u32 s60, s66, 0x88000
	global_load_lds_dwordx4 v128, s[66:67]
	s_addc_u32 s61, s67, 0
	v_mov_b32_e32 v128, v211
	s_add_i32 s16, s95, s86
	s_mov_b32 m0, s16
	s_nop 0
	global_load_lds_dwordx4 v128, s[60:61]
	v_mov_b32_e32 v128, v213
	s_add_i32 m0, s16, 0x2000
	s_nop 0
	global_load_lds_dwordx4 v128, s[60:61]
	v_mov_b32_e32 v128, v210
	s_mov_b32 m0, s87
	s_nop 0
	global_load_lds_dwordx4 v128, s[10:11]
	v_mov_b32_e32 v128, v212
	s_mov_b32 m0, s88
	s_nop 0
	global_load_lds_dwordx4 v128, s[10:11]
	s_waitcnt vmcnt(8)
	s_waitcnt lgkmcnt(0)
	s_barrier
	s_setprio 1
	s_waitcnt lgkmcnt(0)
	v_mfma_scale_f32_16x16x128_f8f6f4 v[60:63], v[134:141], v[64:71], 0, v218, v218 op_sel_hi:[0,0,0]
	v_mfma_scale_f32_16x16x128_f8f6f4 v[56:59], v[142:149], v[64:71], 0, v218, v218 op_sel_hi:[0,0,0]
	v_mfma_scale_f32_16x16x128_f8f6f4 v[52:55], v[134:141], v[72:79], 0, v218, v218 op_sel_hi:[0,0,0]
	v_mfma_scale_f32_16x16x128_f8f6f4 v[48:51], v[142:149], v[72:79], 0, v218, v218 op_sel_hi:[0,0,0]
	v_mfma_scale_f32_16x16x128_f8f6f4 v[44:47], v[134:141], v[80:87], 0, v218, v218 op_sel_hi:[0,0,0]
	v_mfma_scale_f32_16x16x128_f8f6f4 v[40:43], v[142:149], v[80:87], 0, v218, v218 op_sel_hi:[0,0,0]
	v_mfma_scale_f32_16x16x128_f8f6f4 v[194:197], v[150:157], v[64:71], 0, v218, v218 op_sel_hi:[0,0,0]
	v_mfma_scale_f32_16x16x128_f8f6f4 v[202:205], v[158:165], v[64:71], 0, v218, v218 op_sel_hi:[0,0,0]
	v_mfma_scale_f32_16x16x128_f8f6f4 v[206:209], v[150:157], v[72:79], 0, v218, v218 op_sel_hi:[0,0,0]
	v_mfma_scale_f32_16x16x128_f8f6f4 v[220:223], v[158:165], v[72:79], 0, v218, v218 op_sel_hi:[0,0,0]
	v_mfma_scale_f32_16x16x128_f8f6f4 v[224:227], v[150:157], v[80:87], 0, v218, v218 op_sel_hi:[0,0,0]
	v_mfma_scale_f32_16x16x128_f8f6f4 v[228:231], v[158:165], v[80:87], 0, v218, v218 op_sel_hi:[0,0,0]
	v_mfma_scale_f32_16x16x128_f8f6f4 v[232:235], v[134:141], v[88:95], 0, v218, v218 op_sel_hi:[0,0,0]
	v_mfma_scale_f32_16x16x128_f8f6f4 v[236:239], v[150:157], v[88:95], 0, v218, v218 op_sel_hi:[0,0,0]
	v_mfma_scale_f32_16x16x128_f8f6f4 v[240:243], v[142:149], v[88:95], 0, v218, v218 op_sel_hi:[0,0,0]
	v_mfma_scale_f32_16x16x128_f8f6f4 v[244:247], v[158:165], v[88:95], 0, v218, v218 op_sel_hi:[0,0,0]
	s_setprio 0
	s_barrier
; #define PG8_LDA(dst, b, h) do { if constexpr (FP8) { _Pragma("unroll") for (int m = 0; m < 4; ++m) dst##8[m] = PG8_LD8(PG8_SA(b, h), aoff, aoff1, m); } \
;         else { _Pragma("unroll") for (int m = 0; m < 4; ++m) _Pragma("unroll") for (int k = 0; k < 2; ++k) dst[m][k] = *(const LAS bf16x8*)(lds + PG8_SA(b, h) + (k ? aoff1 : aoff) + m * 2048); } } while (0)
; #define PG8_LDB(dst, b, h) do { if constexpr (FP8) { dst##8[0] = PG8_LD8(PG8_SB(b, h), boff, boff1, 0); dst##8[1] = PG8_LD8(PG8_SB(b, h), boff, boff1, 1); } \
;         else { _Pragma("unroll") for (int n = 0; n < 2; ++n) _Pragma("unroll") for (int k = 0; k < 2; ++k) dst[n][k] = *(const LAS bf16x8*)(lds + PG8_SB(b, h) + (k ? boff1 : boff) + n * 2048); } } while (0)
; #define PG8_WAIT_V(n) asm volatile("s_waitcnt vmcnt(" #n ")" ::: "memory")
; #define PG8_WAIT_L(n) asm volatile("s_waitcnt lgkmcnt(" #n ")" ::: "memory")
; #define PG8_BAR __builtin_amdgcn_s_barrier()
; #define PG8_SCHED __builtin_amdgcn_sched_barrier(0)
; #define PG8_S3 PG8_STAGE(PG8_SA(0, 1), a2 + hstepA, voffA)
; #define PG8_S4 do { PG8_STAGE(PG8_SB(1, 0), b3, voffB); PG8_STAGE(PG8_SB(1, 1), b3 + hstepB, voffB); PG8_STAGE(PG8_SA(1, 0), a3, voffA); } while (0)
; template <class Epi, class SchedT, bool ALIGN_EPI, bool SP2, bool FP8 = false>
; __device__ __forceinline__ void gemm_phase(LAS unsigned char* lds, const Gemm g, const SchedT& S, const Epi& E, const int wid) {
;     ...
;             PG8_LDB(B0, 1, 0); PG8_LDB(B1, 1, 1); PG8_SCHED; PG8_LDA(At, 1, 0); PG8_S3;
;             PG8_WAIT_V(8); PG8_WAIT_L(0); PG8_BAR; PG8_MMAP(0, 1, 0); PG8_BAR; PG8_SCHED;
;             PG8_LDA(At, 1, 1); PG8_S4;
;             PG8_WAIT_V(8); PG8_WAIT_L(0); PG8_BAR; PG8_MMAP(1, 1, 1); PG8_BAR; PG8_SCHED;
	s_add_i32 s16, 0, 0x18000
	v_add_u32_e32 v8, s16, v214
	s_add_i32 s17, 0, 0x1c000
	s_nop 1
	ds_read_b128 v[0:3], v8
	ds_read_b128 v[4:7], v8 offset:16
	ds_read_b128 v[134:137], v8 offset:2048
	ds_read_b128 v[138:141], v8 offset:2064
	v_add_u32_e32 v8, s17, v214
	ds_read_b128 v[142:145], v8
	ds_read_b128 v[146:149], v8 offset:16
	ds_read_b128 v[150:153], v8 offset:2048
	ds_read_b128 v[154:157], v8 offset:2064
	s_add_u32 s60, s10, 0x90000
	v_mov_b32_e32 v64, v210
	s_mov_b32 m0, s89
	ds_read_b128 v[8:11], v217 offset:32768
	ds_read_b128 v[12:15], v217 offset:32784
	ds_read_b128 v[16:19], v217 offset:34816
	ds_read_b128 v[20:23], v217 offset:34832
	ds_read_b128 v[24:27], v217 offset:36864
	ds_read_b128 v[28:31], v217 offset:36880
	ds_read_b128 v[32:35], v217 offset:38912
	ds_read_b128 v[36:39], v217 offset:38928
	s_addc_u32 s61, s11, 0
	s_nop 0
	global_load_lds_dwordx4 v64, s[60:61]
	v_mov_b32_e32 v64, v212
	s_mov_b32 m0, s90
	s_nop 0
	global_load_lds_dwordx4 v64, s[60:61]
	s_waitcnt vmcnt(8)
	s_waitcnt lgkmcnt(0)
	s_barrier
	s_setprio 1
	s_waitcnt lgkmcnt(0)
	v_mfma_scale_f32_16x16x128_f8f6f4 v[124:127], v[0:7], v[8:15], v[124:127], v218, v218 op_sel_hi:[0,0,0]
	v_mfma_scale_f32_16x16x128_f8f6f4 v[92:95], v[142:149], v[8:15], v[198:201], v218, v218 op_sel_hi:[0,0,0]
	v_mfma_scale_f32_16x16x128_f8f6f4 v[120:123], v[134:141], v[8:15], v[120:123], v218, v218 op_sel_hi:[0,0,0]
	v_mfma_scale_f32_16x16x128_f8f6f4 v[88:91], v[150:157], v[8:15], v[166:169], v218, v218 op_sel_hi:[0,0,0]
	v_mfma_scale_f32_16x16x128_f8f6f4 v[116:119], v[0:7], v[16:23], v[116:119], v218, v218 op_sel_hi:[0,0,0]
	v_mfma_scale_f32_16x16x128_f8f6f4 v[84:87], v[142:149], v[16:23], v[170:173], v218, v218 op_sel_hi:[0,0,0]
	v_mfma_scale_f32_16x16x128_f8f6f4 v[112:115], v[134:141], v[16:23], v[112:115], v218, v218 op_sel_hi:[0,0,0]
	v_mfma_scale_f32_16x16x128_f8f6f4 v[80:83], v[150:157], v[16:23], v[174:177], v218, v218 op_sel_hi:[0,0,0]
	v_mfma_scale_f32_16x16x128_f8f6f4 v[108:111], v[0:7], v[24:31], v[108:111], v218, v218 op_sel_hi:[0,0,0]
	v_mfma_scale_f32_16x16x128_f8f6f4 v[76:79], v[142:149], v[24:31], v[178:181], v218, v218 op_sel_hi:[0,0,0]
	v_mfma_scale_f32_16x16x128_f8f6f4 v[104:107], v[134:141], v[24:31], v[104:107], v218, v218 op_sel_hi:[0,0,0]
	v_mfma_scale_f32_16x16x128_f8f6f4 v[72:75], v[150:157], v[24:31], v[182:185], v218, v218 op_sel_hi:[0,0,0]
	v_mfma_scale_f32_16x16x128_f8f6f4 v[100:103], v[0:7], v[32:39], v[100:103], v218, v218 op_sel_hi:[0,0,0]
	v_mfma_scale_f32_16x16x128_f8f6f4 v[68:71], v[142:149], v[32:39], v[186:189], v218, v218 op_sel_hi:[0,0,0]
	v_mfma_scale_f32_16x16x128_f8f6f4 v[96:99], v[134:141], v[32:39], v[96:99], v218, v218 op_sel_hi:[0,0,0]
	v_mfma_scale_f32_16x16x128_f8f6f4 v[64:67], v[150:157], v[32:39], v[190:193], v218, v218 op_sel_hi:[0,0,0]
	s_setprio 0
	s_barrier
	v_mov_b32_e32 v128, v211
	ds_read_b128 v[8:11], v217 offset:49152
	ds_read_b128 v[12:15], v217 offset:49168
	ds_read_b128 v[32:35], v217 offset:51200
	ds_read_b128 v[36:39], v217 offset:51216
	ds_read_b128 v[158:161], v217 offset:53248
	ds_read_b128 v[162:165], v217 offset:53264
	ds_read_b128 v[166:169], v217 offset:55296
	ds_read_b128 v[170:173], v217 offset:55312
	s_add_i32 s16, s16, s86
	v_lshl_add_u64 v[16:17], s[66:67], 0, v[128:129]
	v_lshl_add_u64 v[16:17], v[16:17], 0, s[44:45]
	s_mov_b32 m0, s16
	v_mov_b32_e32 v128, v213
	global_load_lds_dwordx4 v[16:17], off
	s_add_i32 m0, s16, 0x2000
	v_lshl_add_u64 v[16:17], s[66:67], 0, v[128:129]
	v_lshl_add_u64 v[16:17], v[16:17], 0, s[44:45]
	s_add_u32 s60, s66, 0x88080
	global_load_lds_dwordx4 v[16:17], off
	s_addc_u32 s61, s67, 0
	v_mov_b32_e32 v16, v211
	s_add_i32 s16, s17, s86
	s_mov_b32 m0, s16
	v_mov_b32_e32 v128, v210
	global_load_lds_dwordx4 v16, s[60:61]
	v_mov_b32_e32 v16, v213
	s_add_i32 m0, s16, 0x2000
	s_nop 0
	global_load_lds_dwordx4 v16, s[60:61]
	s_mov_b32 m0, s92
	v_lshl_add_u64 v[16:17], s[10:11], 0, v[128:129]
	v_lshl_add_u64 v[16:17], v[16:17], 0, s[44:45]
	v_mov_b32_e32 v128, v212
	global_load_lds_dwordx4 v[16:17], off
	s_mov_b32 m0, s93
	v_lshl_add_u64 v[16:17], s[10:11], 0, v[128:129]
	v_lshl_add_u64 v[16:17], v[16:17], 0, s[44:45]
	global_load_lds_dwordx4 v[16:17], off
	s_waitcnt vmcnt(8)
	s_waitcnt lgkmcnt(0)
	s_barrier
	s_setprio 1
	s_waitcnt lgkmcnt(0)
	v_mfma_scale_f32_16x16x128_f8f6f4 v[60:63], v[0:7], v[8:15], v[60:63], v218, v218 op_sel_hi:[0,0,0]
	v_mfma_scale_f32_16x16x128_f8f6f4 v[28:31], v[142:149], v[8:15], v[194:197], v218, v218 op_sel_hi:[0,0,0]
	v_mfma_scale_f32_16x16x128_f8f6f4 v[56:59], v[134:141], v[8:15], v[56:59], v218, v218 op_sel_hi:[0,0,0]
	v_mfma_scale_f32_16x16x128_f8f6f4 v[24:27], v[150:157], v[8:15], v[202:205], v218, v218 op_sel_hi:[0,0,0]
	v_mfma_scale_f32_16x16x128_f8f6f4 v[52:55], v[0:7], v[32:39], v[52:55], v218, v218 op_sel_hi:[0,0,0]
	v_mfma_scale_f32_16x16x128_f8f6f4 v[20:23], v[142:149], v[32:39], v[206:209], v218, v218 op_sel_hi:[0,0,0]
	v_mfma_scale_f32_16x16x128_f8f6f4 v[48:51], v[134:141], v[32:39], v[48:51], v218, v218 op_sel_hi:[0,0,0]
	v_mfma_scale_f32_16x16x128_f8f6f4 v[16:19], v[150:157], v[32:39], v[220:223], v218, v218 op_sel_hi:[0,0,0]
	v_mfma_scale_f32_16x16x128_f8f6f4 v[44:47], v[0:7], v[158:165], v[44:47], v218, v218 op_sel_hi:[0,0,0]
	v_mfma_scale_f32_16x16x128_f8f6f4 v[12:15], v[142:149], v[158:165], v[224:227], v218, v218 op_sel_hi:[0,0,0]
	v_mfma_scale_f32_16x16x128_f8f6f4 v[40:43], v[134:141], v[158:165], v[40:43], v218, v218 op_sel_hi:[0,0,0]
	v_mfma_scale_f32_16x16x128_f8f6f4 v[8:11], v[150:157], v[158:165], v[228:231], v218, v218 op_sel_hi:[0,0,0]
	v_mfma_scale_f32_16x16x128_f8f6f4 v[36:39], v[0:7], v[166:173], v[232:235], v218, v218 op_sel_hi:[0,0,0]
	v_mfma_scale_f32_16x16x128_f8f6f4 v[4:7], v[142:149], v[166:173], v[236:239], v218, v218 op_sel_hi:[0,0,0]
	v_mfma_scale_f32_16x16x128_f8f6f4 v[32:35], v[134:141], v[166:173], v[240:243], v218, v218 op_sel_hi:[0,0,0]
	v_mfma_scale_f32_16x16x128_f8f6f4 v[0:3], v[150:157], v[166:173], v[244:247], v218, v218 op_sel_hi:[0,0,0]
	s_setprio 0
	s_barrier
	s_add_u32 s8, s8, 0x100
	s_addc_u32 s9, s9, 0
	s_add_u32 s21, s21, 0x100
	s_addc_u32 s24, s24, 0
	s_cmp_ge_i32 s30, s71
	s_mov_b32 s10, s30
	s_cbranch_scc1 .Lpeel_exit_lbb0_539
; #define PG8_LDA(dst, b, h) do { if constexpr (FP8) { _Pragma("unroll") for (int m = 0; m < 4; ++m) dst##8[m] = PG8_LD8(PG8_SA(b, h), aoff, aoff1, m); } \
;         else { _Pragma("unroll") for (int m = 0; m < 4; ++m) _Pragma("unroll") for (int k = 0; k < 2; ++k) dst[m][k] = *(const LAS bf16x8*)(lds + PG8_SA(b, h) + (k ? aoff1 : aoff) + m * 2048); } } while (0)
; #define PG8_LDB(dst, b, h) do { if constexpr (FP8) { dst##8[0] = PG8_LD8(PG8_SB(b, h), boff, boff1, 0); dst##8[1] = PG8_LD8(PG8_SB(b, h), boff, boff1, 1); } \
;         else { _Pragma("unroll") for (int n = 0; n < 2; ++n) _Pragma("unroll") for (int k = 0; k < 2; ++k) dst[n][k] = *(const LAS bf16x8*)(lds + PG8_SB(b, h) + (k ? boff1 : boff) + n * 2048); } } while (0)
; #define PG8_WAIT_V(n) asm volatile("s_waitcnt vmcnt(" #n ")" ::: "memory")
; #define PG8_WAIT_L(n) asm volatile("s_waitcnt lgkmcnt(" #n ")" ::: "memory")
; #define PG8_BAR __builtin_amdgcn_s_barrier()
; #define PG8_SCHED __builtin_amdgcn_sched_barrier(0)
; #define PG8_S1 PG8_STAGE(PG8_SA(1, 1), a1 + hstepA, voffA)
; #define PG8_S2 do { PG8_STAGE(PG8_SB(0, 0), b2, voffB); PG8_STAGE(PG8_SB(0, 1), b2 + hstepB, voffB); PG8_STAGE(PG8_SA(0, 0), a2, voffA); } while (0)
; template <class Epi, class SchedT, bool ALIGN_EPI, bool SP2, bool FP8 = false>
; __device__ __forceinline__ void gemm_phase(LAS unsigned char* lds, const Gemm g, const SchedT& S, const Epi& E, const int wid) {
;     ...
;             PG8_LDB(B0, 0, 0); PG8_LDB(B1, 0, 1); PG8_SCHED; PG8_LDA(At, 0, 0); PG8_S1;
;             PG8_WAIT_V(8); PG8_WAIT_L(0); PG8_BAR; PG8_MMAP(0, 0, 0); PG8_BAR; PG8_SCHED;
;             PG8_LDA(At, 0, 1); PG8_S2;
;             PG8_WAIT_V(8); PG8_WAIT_L(0); PG8_BAR; PG8_MMAP(1, 0, 1); PG8_BAR; PG8_SCHED;
.LBB0_539:
	ds_read_b128 v[134:137], v215
	ds_read_b128 v[138:141], v215 offset:16
	ds_read_b128 v[142:145], v215 offset:2048
	ds_read_b128 v[146:149], v215 offset:2064
	ds_read_b128 v[150:153], v216
	ds_read_b128 v[154:157], v216 offset:16
	ds_read_b128 v[158:161], v216 offset:2048
	ds_read_b128 v[162:165], v216 offset:2064
	s_add_i32 s30, s10, 2
	s_add_u32 s16, s8, 0xfff70080
	s_addc_u32 s11, s9, -1
	s_cmp_eq_u32 s20, s10
	s_cselect_b32 s10, s52, s16
	s_cselect_b32 s11, s53, s11
	v_mov_b32_e32 v128, v210
	ds_read_b128 v[166:169], v217
	ds_read_b128 v[170:173], v217 offset:16
	ds_read_b128 v[174:177], v217 offset:2048
	ds_read_b128 v[178:181], v217 offset:2064
	ds_read_b128 v[182:185], v217 offset:4096
	ds_read_b128 v[186:189], v217 offset:4112
	ds_read_b128 v[190:193], v217 offset:6144
	ds_read_b128 v[194:197], v217 offset:6160
	s_cselect_b32 s67, s65, s24
	s_cselect_b32 s66, s64, s21
	s_add_i32 m0, s87, 0xc000
	s_nop 0
	global_load_lds_dwordx4 v128, s[8:9]
	v_mov_b32_e32 v128, v212
	s_add_i32 m0, s87, 0xe000
	s_nop 0
	global_load_lds_dwordx4 v128, s[8:9]
	s_waitcnt vmcnt(8)
	s_waitcnt lgkmcnt(0)
	s_barrier
	s_setprio 1
	s_waitcnt lgkmcnt(0)
	v_mfma_scale_f32_16x16x128_f8f6f4 v[124:127], v[134:141], v[166:173], v[124:127], v218, v218 op_sel_hi:[0,0,0]
	v_mfma_scale_f32_16x16x128_f8f6f4 v[120:123], v[142:149], v[166:173], v[120:123], v218, v218 op_sel_hi:[0,0,0]
	v_mfma_scale_f32_16x16x128_f8f6f4 v[116:119], v[134:141], v[174:181], v[116:119], v218, v218 op_sel_hi:[0,0,0]
	v_mfma_scale_f32_16x16x128_f8f6f4 v[112:115], v[142:149], v[174:181], v[112:115], v218, v218 op_sel_hi:[0,0,0]
	v_mfma_scale_f32_16x16x128_f8f6f4 v[108:111], v[134:141], v[182:189], v[108:111], v218, v218 op_sel_hi:[0,0,0]
	v_mfma_scale_f32_16x16x128_f8f6f4 v[104:107], v[142:149], v[182:189], v[104:107], v218, v218 op_sel_hi:[0,0,0]
	v_mfma_scale_f32_16x16x128_f8f6f4 v[100:103], v[134:141], v[190:197], v[100:103], v218, v218 op_sel_hi:[0,0,0]
	v_mfma_scale_f32_16x16x128_f8f6f4 v[96:99], v[142:149], v[190:197], v[96:99], v218, v218 op_sel_hi:[0,0,0]
	v_mfma_scale_f32_16x16x128_f8f6f4 v[198:201], v[150:157], v[166:173], v[92:95], v218, v218 op_sel_hi:[0,0,0]
	v_mfma_scale_f32_16x16x128_f8f6f4 v[166:169], v[158:165], v[166:173], v[88:91], v218, v218 op_sel_hi:[0,0,0]
	v_mfma_scale_f32_16x16x128_f8f6f4 v[170:173], v[150:157], v[174:181], v[84:87], v218, v218 op_sel_hi:[0,0,0]
	v_mfma_scale_f32_16x16x128_f8f6f4 v[174:177], v[158:165], v[174:181], v[80:83], v218, v218 op_sel_hi:[0,0,0]
	v_mfma_scale_f32_16x16x128_f8f6f4 v[178:181], v[150:157], v[182:189], v[76:79], v218, v218 op_sel_hi:[0,0,0]
	v_mfma_scale_f32_16x16x128_f8f6f4 v[182:185], v[158:165], v[182:189], v[72:75], v218, v218 op_sel_hi:[0,0,0]
	v_mfma_scale_f32_16x16x128_f8f6f4 v[186:189], v[150:157], v[190:197], v[68:71], v218, v218 op_sel_hi:[0,0,0]
	v_mfma_scale_f32_16x16x128_f8f6f4 v[190:193], v[158:165], v[190:197], v[64:67], v218, v218 op_sel_hi:[0,0,0]
	s_setprio 0
	s_barrier
	v_mov_b32_e32 v128, v211
	s_add_i32 s16, s94, s86
	s_nop 2
	ds_read_b128 v[64:67], v217 offset:16384
	ds_read_b128 v[68:71], v217 offset:16400
	ds_read_b128 v[72:75], v217 offset:18432
	ds_read_b128 v[76:79], v217 offset:18448
	ds_read_b128 v[80:83], v217 offset:20480
	ds_read_b128 v[84:87], v217 offset:20496
	ds_read_b128 v[88:91], v217 offset:22528
	ds_read_b128 v[92:95], v217 offset:22544
	s_mov_b32 m0, s16
	s_nop 0
	global_load_lds_dwordx4 v128, s[66:67]
	v_mov_b32_e32 v128, v213
	s_add_i32 m0, s16, 0x2000
	s_add_u32 s60, s66, 0x88000
	global_load_lds_dwordx4 v128, s[66:67]
	s_addc_u32 s61, s67, 0
	v_mov_b32_e32 v128, v211
	s_add_i32 s16, s95, s86
	s_mov_b32 m0, s16
	s_nop 0
	global_load_lds_dwordx4 v128, s[60:61]
	v_mov_b32_e32 v128, v213
	s_add_i32 m0, s16, 0x2000
	s_nop 0
	global_load_lds_dwordx4 v128, s[60:61]
	v_mov_b32_e32 v128, v210
	s_mov_b32 m0, s87
	s_nop 0
	global_load_lds_dwordx4 v128, s[10:11]
	v_mov_b32_e32 v128, v212
	s_mov_b32 m0, s88
	s_nop 0
	global_load_lds_dwordx4 v128, s[10:11]
	s_waitcnt vmcnt(8)
	s_waitcnt lgkmcnt(0)
	s_barrier
	s_setprio 1
	s_waitcnt lgkmcnt(0)
	v_mfma_scale_f32_16x16x128_f8f6f4 v[60:63], v[134:141], v[64:71], v[60:63], v218, v218 op_sel_hi:[0,0,0]
	v_mfma_scale_f32_16x16x128_f8f6f4 v[56:59], v[142:149], v[64:71], v[56:59], v218, v218 op_sel_hi:[0,0,0]
	v_mfma_scale_f32_16x16x128_f8f6f4 v[52:55], v[134:141], v[72:79], v[52:55], v218, v218 op_sel_hi:[0,0,0]
	v_mfma_scale_f32_16x16x128_f8f6f4 v[48:51], v[142:149], v[72:79], v[48:51], v218, v218 op_sel_hi:[0,0,0]
	v_mfma_scale_f32_16x16x128_f8f6f4 v[44:47], v[134:141], v[80:87], v[44:47], v218, v218 op_sel_hi:[0,0,0]
	v_mfma_scale_f32_16x16x128_f8f6f4 v[40:43], v[142:149], v[80:87], v[40:43], v218, v218 op_sel_hi:[0,0,0]
	v_mfma_scale_f32_16x16x128_f8f6f4 v[194:197], v[150:157], v[64:71], v[28:31], v218, v218 op_sel_hi:[0,0,0]
	v_mfma_scale_f32_16x16x128_f8f6f4 v[202:205], v[158:165], v[64:71], v[24:27], v218, v218 op_sel_hi:[0,0,0]
	v_mfma_scale_f32_16x16x128_f8f6f4 v[206:209], v[150:157], v[72:79], v[20:23], v218, v218 op_sel_hi:[0,0,0]
	v_mfma_scale_f32_16x16x128_f8f6f4 v[220:223], v[158:165], v[72:79], v[16:19], v218, v218 op_sel_hi:[0,0,0]
	v_mfma_scale_f32_16x16x128_f8f6f4 v[224:227], v[150:157], v[80:87], v[12:15], v218, v218 op_sel_hi:[0,0,0]
	v_mfma_scale_f32_16x16x128_f8f6f4 v[228:231], v[158:165], v[80:87], v[8:11], v218, v218 op_sel_hi:[0,0,0]
	v_mfma_scale_f32_16x16x128_f8f6f4 v[232:235], v[134:141], v[88:95], v[36:39], v218, v218 op_sel_hi:[0,0,0]
	v_mfma_scale_f32_16x16x128_f8f6f4 v[236:239], v[150:157], v[88:95], v[4:7], v218, v218 op_sel_hi:[0,0,0]
	v_mfma_scale_f32_16x16x128_f8f6f4 v[240:243], v[142:149], v[88:95], v[32:35], v218, v218 op_sel_hi:[0,0,0]
	v_mfma_scale_f32_16x16x128_f8f6f4 v[244:247], v[158:165], v[88:95], v[0:3], v218, v218 op_sel_hi:[0,0,0]
	s_setprio 0
	s_barrier
; #define PG8_LDA(dst, b, h) do { if constexpr (FP8) { _Pragma("unroll") for (int m = 0; m < 4; ++m) dst##8[m] = PG8_LD8(PG8_SA(b, h), aoff, aoff1, m); } \
;         else { _Pragma("unroll") for (int m = 0; m < 4; ++m) _Pragma("unroll") for (int k = 0; k < 2; ++k) dst[m][k] = *(const LAS bf16x8*)(lds + PG8_SA(b, h) + (k ? aoff1 : aoff) + m * 2048); } } while (0)
; #define PG8_LDB(dst, b, h) do { if constexpr (FP8) { dst##8[0] = PG8_LD8(PG8_SB(b, h), boff, boff1, 0); dst##8[1] = PG8_LD8(PG8_SB(b, h), boff, boff1, 1); } \
;         else { _Pragma("unroll") for (int n = 0; n < 2; ++n) _Pragma("unroll") for (int k = 0; k < 2; ++k) dst[n][k] = *(const LAS bf16x8*)(lds + PG8_SB(b, h) + (k ? boff1 : boff) + n * 2048); } } while (0)
; #define PG8_WAIT_V(n) asm volatile("s_waitcnt vmcnt(" #n ")" ::: "memory")
; #define PG8_WAIT_L(n) asm volatile("s_waitcnt lgkmcnt(" #n ")" ::: "memory")
; #define PG8_BAR __builtin_amdgcn_s_barrier()
; #define PG8_SCHED __builtin_amdgcn_sched_barrier(0)
; #define PG8_S3 PG8_STAGE(PG8_SA(0, 1), a2 + hstepA, voffA)
; #define PG8_S4 do { PG8_STAGE(PG8_SB(1, 0), b3, voffB); PG8_STAGE(PG8_SB(1, 1), b3 + hstepB, voffB); PG8_STAGE(PG8_SA(1, 0), a3, voffA); } while (0)
; template <class Epi, class SchedT, bool ALIGN_EPI, bool SP2, bool FP8 = false>
; __device__ __forceinline__ void gemm_phase(LAS unsigned char* lds, const Gemm g, const SchedT& S, const Epi& E, const int wid) {
;     ...
;             PG8_LDB(B0, 1, 0); PG8_LDB(B1, 1, 1); PG8_SCHED; PG8_LDA(At, 1, 0); PG8_S3;
;             PG8_WAIT_V(8); PG8_WAIT_L(0); PG8_BAR; PG8_MMAP(0, 1, 0); PG8_BAR; PG8_SCHED;
;             PG8_LDA(At, 1, 1); PG8_S4;
;             PG8_WAIT_V(8); PG8_WAIT_L(0); PG8_BAR; PG8_MMAP(1, 1, 1); PG8_BAR; PG8_SCHED;
;     ...
;         if constexpr (ALIGN_EPI) { if (wr == 0) PG8_BAR; }
	s_add_i32 s16, 0, 0x18000
	v_add_u32_e32 v8, s16, v214
	s_add_i32 s17, 0, 0x1c000
	s_nop 1
	ds_read_b128 v[0:3], v8
	ds_read_b128 v[4:7], v8 offset:16
	ds_read_b128 v[134:137], v8 offset:2048
	ds_read_b128 v[138:141], v8 offset:2064
	v_add_u32_e32 v8, s17, v214
	ds_read_b128 v[142:145], v8
	ds_read_b128 v[146:149], v8 offset:16
	ds_read_b128 v[150:153], v8 offset:2048
	ds_read_b128 v[154:157], v8 offset:2064
	s_add_u32 s60, s10, 0x90000
	v_mov_b32_e32 v64, v210
	s_mov_b32 m0, s89
	ds_read_b128 v[8:11], v217 offset:32768
	ds_read_b128 v[12:15], v217 offset:32784
	ds_read_b128 v[16:19], v217 offset:34816
	ds_read_b128 v[20:23], v217 offset:34832
	ds_read_b128 v[24:27], v217 offset:36864
	ds_read_b128 v[28:31], v217 offset:36880
	ds_read_b128 v[32:35], v217 offset:38912
	ds_read_b128 v[36:39], v217 offset:38928
	s_addc_u32 s61, s11, 0
	s_nop 0
	global_load_lds_dwordx4 v64, s[60:61]
	v_mov_b32_e32 v64, v212
	s_mov_b32 m0, s90
	s_nop 0
	global_load_lds_dwordx4 v64, s[60:61]
	s_waitcnt vmcnt(8)
	s_waitcnt lgkmcnt(0)
	s_barrier
	s_setprio 1
	s_waitcnt lgkmcnt(0)
	v_mfma_scale_f32_16x16x128_f8f6f4 v[124:127], v[0:7], v[8:15], v[124:127], v218, v218 op_sel_hi:[0,0,0]
	v_mfma_scale_f32_16x16x128_f8f6f4 v[92:95], v[142:149], v[8:15], v[198:201], v218, v218 op_sel_hi:[0,0,0]
	v_mfma_scale_f32_16x16x128_f8f6f4 v[120:123], v[134:141], v[8:15], v[120:123], v218, v218 op_sel_hi:[0,0,0]
	v_mfma_scale_f32_16x16x128_f8f6f4 v[88:91], v[150:157], v[8:15], v[166:169], v218, v218 op_sel_hi:[0,0,0]
	v_mfma_scale_f32_16x16x128_f8f6f4 v[116:119], v[0:7], v[16:23], v[116:119], v218, v218 op_sel_hi:[0,0,0]
	v_mfma_scale_f32_16x16x128_f8f6f4 v[84:87], v[142:149], v[16:23], v[170:173], v218, v218 op_sel_hi:[0,0,0]
	v_mfma_scale_f32_16x16x128_f8f6f4 v[112:115], v[134:141], v[16:23], v[112:115], v218, v218 op_sel_hi:[0,0,0]
	v_mfma_scale_f32_16x16x128_f8f6f4 v[80:83], v[150:157], v[16:23], v[174:177], v218, v218 op_sel_hi:[0,0,0]
	v_mfma_scale_f32_16x16x128_f8f6f4 v[108:111], v[0:7], v[24:31], v[108:111], v218, v218 op_sel_hi:[0,0,0]
	v_mfma_scale_f32_16x16x128_f8f6f4 v[76:79], v[142:149], v[24:31], v[178:181], v218, v218 op_sel_hi:[0,0,0]
	v_mfma_scale_f32_16x16x128_f8f6f4 v[104:107], v[134:141], v[24:31], v[104:107], v218, v218 op_sel_hi:[0,0,0]
	v_mfma_scale_f32_16x16x128_f8f6f4 v[72:75], v[150:157], v[24:31], v[182:185], v218, v218 op_sel_hi:[0,0,0]
	v_mfma_scale_f32_16x16x128_f8f6f4 v[100:103], v[0:7], v[32:39], v[100:103], v218, v218 op_sel_hi:[0,0,0]
	v_mfma_scale_f32_16x16x128_f8f6f4 v[68:71], v[142:149], v[32:39], v[186:189], v218, v218 op_sel_hi:[0,0,0]
	v_mfma_scale_f32_16x16x128_f8f6f4 v[96:99], v[134:141], v[32:39], v[96:99], v218, v218 op_sel_hi:[0,0,0]
	v_mfma_scale_f32_16x16x128_f8f6f4 v[64:67], v[150:157], v[32:39], v[190:193], v218, v218 op_sel_hi:[0,0,0]
	s_setprio 0
	s_barrier
	v_mov_b32_e32 v128, v211
	ds_read_b128 v[8:11], v217 offset:49152
	ds_read_b128 v[12:15], v217 offset:49168
	ds_read_b128 v[32:35], v217 offset:51200
	ds_read_b128 v[36:39], v217 offset:51216
	ds_read_b128 v[158:161], v217 offset:53248
	ds_read_b128 v[162:165], v217 offset:53264
	ds_read_b128 v[166:169], v217 offset:55296
	ds_read_b128 v[170:173], v217 offset:55312
	s_add_i32 s16, s16, s86
	v_lshl_add_u64 v[16:17], s[66:67], 0, v[128:129]
	v_lshl_add_u64 v[16:17], v[16:17], 0, s[44:45]
	s_mov_b32 m0, s16
	v_mov_b32_e32 v128, v213
	global_load_lds_dwordx4 v[16:17], off
	s_add_i32 m0, s16, 0x2000
	v_lshl_add_u64 v[16:17], s[66:67], 0, v[128:129]
	v_lshl_add_u64 v[16:17], v[16:17], 0, s[44:45]
	s_add_u32 s60, s66, 0x88080
	global_load_lds_dwordx4 v[16:17], off
	s_addc_u32 s61, s67, 0
	v_mov_b32_e32 v16, v211
	s_add_i32 s16, s17, s86
	s_mov_b32 m0, s16
	v_mov_b32_e32 v128, v210
	global_load_lds_dwordx4 v16, s[60:61]
	v_mov_b32_e32 v16, v213
	s_add_i32 m0, s16, 0x2000
	s_nop 0
	global_load_lds_dwordx4 v16, s[60:61]
	s_mov_b32 m0, s92
	v_lshl_add_u64 v[16:17], s[10:11], 0, v[128:129]
	v_lshl_add_u64 v[16:17], v[16:17], 0, s[44:45]
	v_mov_b32_e32 v128, v212
	global_load_lds_dwordx4 v[16:17], off
	s_mov_b32 m0, s93
	v_lshl_add_u64 v[16:17], s[10:11], 0, v[128:129]
	v_lshl_add_u64 v[16:17], v[16:17], 0, s[44:45]
	global_load_lds_dwordx4 v[16:17], off
	s_waitcnt vmcnt(8)
	s_waitcnt lgkmcnt(0)
	s_barrier
	s_setprio 1
	s_waitcnt lgkmcnt(0)
	v_mfma_scale_f32_16x16x128_f8f6f4 v[60:63], v[0:7], v[8:15], v[60:63], v218, v218 op_sel_hi:[0,0,0]
	v_mfma_scale_f32_16x16x128_f8f6f4 v[28:31], v[142:149], v[8:15], v[194:197], v218, v218 op_sel_hi:[0,0,0]
	v_mfma_scale_f32_16x16x128_f8f6f4 v[56:59], v[134:141], v[8:15], v[56:59], v218, v218 op_sel_hi:[0,0,0]
	v_mfma_scale_f32_16x16x128_f8f6f4 v[24:27], v[150:157], v[8:15], v[202:205], v218, v218 op_sel_hi:[0,0,0]
	v_mfma_scale_f32_16x16x128_f8f6f4 v[52:55], v[0:7], v[32:39], v[52:55], v218, v218 op_sel_hi:[0,0,0]
	v_mfma_scale_f32_16x16x128_f8f6f4 v[20:23], v[142:149], v[32:39], v[206:209], v218, v218 op_sel_hi:[0,0,0]
	v_mfma_scale_f32_16x16x128_f8f6f4 v[48:51], v[134:141], v[32:39], v[48:51], v218, v218 op_sel_hi:[0,0,0]
	v_mfma_scale_f32_16x16x128_f8f6f4 v[16:19], v[150:157], v[32:39], v[220:223], v218, v218 op_sel_hi:[0,0,0]
	v_mfma_scale_f32_16x16x128_f8f6f4 v[44:47], v[0:7], v[158:165], v[44:47], v218, v218 op_sel_hi:[0,0,0]
	v_mfma_scale_f32_16x16x128_f8f6f4 v[12:15], v[142:149], v[158:165], v[224:227], v218, v218 op_sel_hi:[0,0,0]
	v_mfma_scale_f32_16x16x128_f8f6f4 v[40:43], v[134:141], v[158:165], v[40:43], v218, v218 op_sel_hi:[0,0,0]
	v_mfma_scale_f32_16x16x128_f8f6f4 v[8:11], v[150:157], v[158:165], v[228:231], v218, v218 op_sel_hi:[0,0,0]
	v_mfma_scale_f32_16x16x128_f8f6f4 v[36:39], v[0:7], v[166:173], v[232:235], v218, v218 op_sel_hi:[0,0,0]
	v_mfma_scale_f32_16x16x128_f8f6f4 v[4:7], v[142:149], v[166:173], v[236:239], v218, v218 op_sel_hi:[0,0,0]
	v_mfma_scale_f32_16x16x128_f8f6f4 v[32:35], v[134:141], v[166:173], v[240:243], v218, v218 op_sel_hi:[0,0,0]
	v_mfma_scale_f32_16x16x128_f8f6f4 v[0:3], v[150:157], v[166:173], v[244:247], v218, v218 op_sel_hi:[0,0,0]
	s_setprio 0
	s_barrier
	s_add_u32 s8, s8, 0x100
	s_addc_u32 s9, s9, 0
	s_add_u32 s21, s21, 0x100
	s_addc_u32 s24, s24, 0
	s_cmp_ge_i32 s30, s71
	s_mov_b32 s10, s30
	s_cbranch_scc0 .LBB0_539
.Lpeel_exit_lbb0_539:
	s_and_b64 vcc, exec, s[96:97]
	s_cbranch_vccz .LBB0_542
.LBB0_541:
	s_barrier

; #define PG8_LDA(dst, b, h) do { if constexpr (FP8) { _Pragma("unroll") for (int m = 0; m < 4; ++m) dst##8[m] = PG8_LD8(PG8_SA(b, h), aoff, aoff1, m); } \
;         else { _Pragma("unroll") for (int m = 0; m < 4; ++m) _Pragma("unroll") for (int k = 0; k < 2; ++k) dst[m][k] = *(const LAS bf16x8*)(lds + PG8_SA(b, h) + (k ? aoff1 : aoff) + m * 2048); } } while (0)
; #define PG8_LDB(dst, b, h) do { if constexpr (FP8) { dst##8[0] = PG8_LD8(PG8_SB(b, h), boff, boff1, 0); dst##8[1] = PG8_LD8(PG8_SB(b, h), boff, boff1, 1); } \
;         else { _Pragma("unroll") for (int n = 0; n < 2; ++n) _Pragma("unroll") for (int k = 0; k < 2; ++k) dst[n][k] = *(const LAS bf16x8*)(lds + PG8_SB(b, h) + (k ? boff1 : boff) + n * 2048); } } while (0)
; #define PG8_WAIT_V(n) asm volatile("s_waitcnt vmcnt(" #n ")" ::: "memory")
; #define PG8_WAIT_L(n) asm volatile("s_waitcnt lgkmcnt(" #n ")" ::: "memory")
; #define PG8_BAR __builtin_amdgcn_s_barrier()
; #define PG8_SCHED __builtin_amdgcn_sched_barrier(0)
; #define PG8_S1 PG8_STAGE(PG8_SA(1, 1), a1 + hstepA, voffA)
; template <class Epi, class SchedT, bool ALIGN_EPI, bool SP2, bool FP8 = false>
; __device__ __forceinline__ void gemm_phase(LAS unsigned char* lds, const Gemm g, const SchedT& S, const Epi& E, const int wid) {
;     ...
;         const bool has_next = S.next(ui + 1, nxt);
;         const char* nA = has_next ? (const char*)g.A + (size_t)nxt.pm * tstepA + (size_t)nxt.aoff * 2 : cA; const char* nB = has_next ? (const char*)g.Bt + (size_t)nxt.pn * tstepB + (size_t)nxt.boff * 2 : cB;
;         const int nt = cur.nt;
;         for (int t = 0; t < nt; t += 2) {
;             const bool last = (t == nt - 2);
;             const char* a1 = cA + (size_t)(t + 1) * kstep;
;             const char* a2 = last ? nA : cA + (size_t)(t + 2) * kstep; const char* b2 = last ? nB : cB + (size_t)(t + 2) * kstep;
;             const char* a3 = a2 + kstep; const char* b3 = b2 + kstep;
;             if constexpr (SP2) {
;     ...
;             PG8_LDB(B0, 0, 0); PG8_LDB(B1, 0, 1); PG8_SCHED; PG8_LDA(At, 0, 0); PG8_S1;
;             PG8_WAIT_V(8); PG8_WAIT_L(0); PG8_BAR; PG8_MMAP(0, 0, 0); PG8_BAR; PG8_SCHED;
;             PG8_LDA(At, 0, 1); PG8_S2;
;             PG8_WAIT_V(8); PG8_WAIT_L(0); PG8_BAR; PG8_MMAP(1, 0, 1); PG8_BAR; PG8_SCHED;
.LBB0_777:
	s_ashr_i32 s47, s46, 31
	s_lshl_b64 s[22:23], s[46:47], 18
	s_add_u32 s48, s36, s22
	s_addc_u32 s49, s37, s23
	s_ashr_i32 s45, s44, 31
	s_lshl_b64 s[22:23], s[44:45], 18
	s_add_u32 s50, s12, s22
	s_addc_u32 s51, s13, s23
	s_cmp_lt_i32 s20, 1
	s_cbranch_scc1 .LBB0_833
	s_and_b64 s[22:23], s[6:7], exec
	s_cselect_b32 s9, s49, s53
	s_cselect_b32 s21, s48, s52
	s_cselect_b32 s22, s51, s65
	s_cselect_b32 s23, s50, s64
	s_add_i32 s24, s20, -2
	s_add_u32 s52, s52, 0x20080
	s_addc_u32 s53, s53, 0
	s_add_u32 s30, s64, 0x100
	s_addc_u32 s31, s65, 0
	s_mov_b32 s47, 0
	s_waitcnt lgkmcnt(0)
	ds_read_b128 v[134:137], v149
	ds_read_b128 v[138:141], v149 offset:16
	ds_read_b128 v[154:157], v149 offset:2048
	ds_read_b128 v[158:161], v149 offset:2064
	ds_read_b128 v[162:165], v150
	ds_read_b128 v[166:169], v150 offset:16
	ds_read_b128 v[170:173], v150 offset:2048
	ds_read_b128 v[174:177], v150 offset:2064
	s_add_i32 s45, s47, 2
	s_add_u32 s16, s52, 0xfffe0080
	s_addc_u32 s17, s53, -1
	s_cmp_eq_u32 s24, s47
	s_cselect_b32 s65, s9, s17
	s_cselect_b32 s64, s21, s16
	v_mov_b32_e32 v128, v146
	ds_read_b128 v[178:181], v151
	ds_read_b128 v[182:185], v151 offset:16
	ds_read_b128 v[186:189], v151 offset:2048
	ds_read_b128 v[190:193], v151 offset:2064
	ds_read_b128 v[194:197], v151 offset:4096
	ds_read_b128 v[198:201], v151 offset:4112
	ds_read_b128 v[202:205], v151 offset:6144
	ds_read_b128 v[206:209], v151 offset:6160
	s_cselect_b32 s67, s22, s31
	s_cselect_b32 s66, s23, s30
	s_add_i32 m0, s87, 0xc000
	s_nop 0
	global_load_lds_dwordx4 v128, s[52:53]
	v_mov_b32_e32 v128, v147
	s_add_i32 m0, s87, 0xe000
	s_nop 0
	global_load_lds_dwordx4 v128, s[52:53]
	s_waitcnt vmcnt(8)
	s_waitcnt lgkmcnt(0)
	s_barrier
	s_setprio 1
	s_waitcnt lgkmcnt(0)
	v_mfma_scale_f32_16x16x128_f8f6f4 v[124:127], v[134:141], v[178:185], 0, v152, v152 op_sel_hi:[0,0,0]
	v_mfma_scale_f32_16x16x128_f8f6f4 v[108:111], v[162:169], v[178:185], 0, v152, v152 op_sel_hi:[0,0,0]
	v_mfma_scale_f32_16x16x128_f8f6f4 v[120:123], v[154:161], v[178:185], 0, v152, v152 op_sel_hi:[0,0,0]
	v_mfma_scale_f32_16x16x128_f8f6f4 v[100:103], v[170:177], v[178:185], 0, v152, v152 op_sel_hi:[0,0,0]
	v_mfma_scale_f32_16x16x128_f8f6f4 v[116:119], v[134:141], v[186:193], 0, v152, v152 op_sel_hi:[0,0,0]
	v_mfma_scale_f32_16x16x128_f8f6f4 v[112:115], v[154:161], v[186:193], 0, v152, v152 op_sel_hi:[0,0,0]
	v_mfma_scale_f32_16x16x128_f8f6f4 v[104:107], v[134:141], v[194:201], 0, v152, v152 op_sel_hi:[0,0,0]
	v_mfma_scale_f32_16x16x128_f8f6f4 v[60:63], v[170:177], v[202:209], 0, v152, v152 op_sel_hi:[0,0,0]
	v_mfma_scale_f32_16x16x128_f8f6f4 v[142:145], v[162:169], v[186:193], 0, v152, v152 op_sel_hi:[0,0,0]
	v_mfma_scale_f32_16x16x128_f8f6f4 v[178:181], v[170:177], v[186:193], 0, v152, v152 op_sel_hi:[0,0,0]
	v_mfma_scale_f32_16x16x128_f8f6f4 v[182:185], v[162:169], v[194:201], 0, v152, v152 op_sel_hi:[0,0,0]
	v_mfma_scale_f32_16x16x128_f8f6f4 v[186:189], v[154:161], v[194:201], 0, v152, v152 op_sel_hi:[0,0,0]
	v_mfma_scale_f32_16x16x128_f8f6f4 v[190:193], v[170:177], v[194:201], 0, v152, v152 op_sel_hi:[0,0,0]
	v_mfma_scale_f32_16x16x128_f8f6f4 v[194:197], v[134:141], v[202:209], 0, v152, v152 op_sel_hi:[0,0,0]
	v_mfma_scale_f32_16x16x128_f8f6f4 v[198:201], v[162:169], v[202:209], 0, v152, v152 op_sel_hi:[0,0,0]
	v_mfma_scale_f32_16x16x128_f8f6f4 v[210:213], v[154:161], v[202:209], 0, v152, v152 op_sel_hi:[0,0,0]
	s_setprio 0
	s_barrier
	v_mov_b32_e32 v128, v146
	s_add_i32 s16, s94, s86
	s_nop 1
	ds_read_b128 v[68:71], v151 offset:16384
	ds_read_b128 v[72:75], v151 offset:16400
	ds_read_b128 v[76:79], v151 offset:18432
	ds_read_b128 v[80:83], v151 offset:18448
	ds_read_b128 v[84:87], v151 offset:20480
	ds_read_b128 v[88:91], v151 offset:20496
	ds_read_b128 v[92:95], v151 offset:22528
	ds_read_b128 v[96:99], v151 offset:22544
	s_mov_b32 m0, s16
	s_nop 0
	global_load_lds_dwordx4 v128, s[66:67]
	v_mov_b32_e32 v128, v147
	s_add_i32 m0, s16, 0x2000
	s_add_u32 s60, s66, 0x20000
	global_load_lds_dwordx4 v128, s[66:67]
	s_addc_u32 s61, s67, 0
	v_mov_b32_e32 v128, v146
	s_add_i32 s16, s95, s86
	s_mov_b32 m0, s16
	s_nop 0
	global_load_lds_dwordx4 v128, s[60:61]
	v_mov_b32_e32 v128, v147
	s_add_i32 m0, s16, 0x2000
	s_nop 0
	global_load_lds_dwordx4 v128, s[60:61]
	v_mov_b32_e32 v128, v146
	s_mov_b32 m0, s87
	s_nop 0
	global_load_lds_dwordx4 v128, s[64:65]
	v_mov_b32_e32 v128, v147
	s_mov_b32 m0, s88
	s_nop 0
	global_load_lds_dwordx4 v128, s[64:65]
	s_waitcnt vmcnt(8)
	s_waitcnt lgkmcnt(0)
	s_barrier
	s_setprio 1
	s_waitcnt lgkmcnt(0)
	v_mfma_scale_f32_16x16x128_f8f6f4 v[64:67], v[134:141], v[68:75], 0, v152, v152 op_sel_hi:[0,0,0]
	v_mfma_scale_f32_16x16x128_f8f6f4 v[44:47], v[162:169], v[68:75], 0, v152, v152 op_sel_hi:[0,0,0]
	v_mfma_scale_f32_16x16x128_f8f6f4 v[56:59], v[154:161], v[68:75], 0, v152, v152 op_sel_hi:[0,0,0]
	v_mfma_scale_f32_16x16x128_f8f6f4 v[52:55], v[134:141], v[76:83], 0, v152, v152 op_sel_hi:[0,0,0]
	v_mfma_scale_f32_16x16x128_f8f6f4 v[48:51], v[154:161], v[76:83], 0, v152, v152 op_sel_hi:[0,0,0]
	v_mfma_scale_f32_16x16x128_f8f6f4 v[40:43], v[134:141], v[84:91], 0, v152, v152 op_sel_hi:[0,0,0]
	v_mfma_scale_f32_16x16x128_f8f6f4 v[202:205], v[170:177], v[68:75], 0, v152, v152 op_sel_hi:[0,0,0]
	v_mfma_scale_f32_16x16x128_f8f6f4 v[206:209], v[162:169], v[76:83], 0, v152, v152 op_sel_hi:[0,0,0]
	v_mfma_scale_f32_16x16x128_f8f6f4 v[214:217], v[170:177], v[76:83], 0, v152, v152 op_sel_hi:[0,0,0]
	v_mfma_scale_f32_16x16x128_f8f6f4 v[218:221], v[162:169], v[84:91], 0, v152, v152 op_sel_hi:[0,0,0]
	v_mfma_scale_f32_16x16x128_f8f6f4 v[222:225], v[154:161], v[84:91], 0, v152, v152 op_sel_hi:[0,0,0]
	v_mfma_scale_f32_16x16x128_f8f6f4 v[226:229], v[170:177], v[84:91], 0, v152, v152 op_sel_hi:[0,0,0]
	v_mfma_scale_f32_16x16x128_f8f6f4 v[230:233], v[134:141], v[92:99], 0, v152, v152 op_sel_hi:[0,0,0]
	v_mfma_scale_f32_16x16x128_f8f6f4 v[234:237], v[162:169], v[92:99], 0, v152, v152 op_sel_hi:[0,0,0]
	v_mfma_scale_f32_16x16x128_f8f6f4 v[238:241], v[154:161], v[92:99], 0, v152, v152 op_sel_hi:[0,0,0]
	v_mfma_scale_f32_16x16x128_f8f6f4 v[242:245], v[170:177], v[92:99], 0, v152, v152 op_sel_hi:[0,0,0]
	s_setprio 0
	s_barrier
; #define PG8_LDA(dst, b, h) do { if constexpr (FP8) { _Pragma("unroll") for (int m = 0; m < 4; ++m) dst##8[m] = PG8_LD8(PG8_SA(b, h), aoff, aoff1, m); } \
;         else { _Pragma("unroll") for (int m = 0; m < 4; ++m) _Pragma("unroll") for (int k = 0; k < 2; ++k) dst[m][k] = *(const LAS bf16x8*)(lds + PG8_SA(b, h) + (k ? aoff1 : aoff) + m * 2048); } } while (0)
; #define PG8_LDB(dst, b, h) do { if constexpr (FP8) { dst##8[0] = PG8_LD8(PG8_SB(b, h), boff, boff1, 0); dst##8[1] = PG8_LD8(PG8_SB(b, h), boff, boff1, 1); } \
;         else { _Pragma("unroll") for (int n = 0; n < 2; ++n) _Pragma("unroll") for (int k = 0; k < 2; ++k) dst[n][k] = *(const LAS bf16x8*)(lds + PG8_SB(b, h) + (k ? boff1 : boff) + n * 2048); } } while (0)
; #define PG8_WAIT_V(n) asm volatile("s_waitcnt vmcnt(" #n ")" ::: "memory")
; #define PG8_WAIT_L(n) asm volatile("s_waitcnt lgkmcnt(" #n ")" ::: "memory")
; #define PG8_BAR __builtin_amdgcn_s_barrier()
; #define PG8_SCHED __builtin_amdgcn_sched_barrier(0)
; #define PG8_S3 PG8_STAGE(PG8_SA(0, 1), a2 + hstepA, voffA)
; #define PG8_S4 do { PG8_STAGE(PG8_SB(1, 0), b3, voffB); PG8_STAGE(PG8_SB(1, 1), b3 + hstepB, voffB); PG8_STAGE(PG8_SA(1, 0), a3, voffA); } while (0)
; template <class Epi, class SchedT, bool ALIGN_EPI, bool SP2, bool FP8 = false>
; __device__ __forceinline__ void gemm_phase(LAS unsigned char* lds, const Gemm g, const SchedT& S, const Epi& E, const int wid) {
;     ...
;             PG8_LDB(B0, 1, 0); PG8_LDB(B1, 1, 1); PG8_SCHED; PG8_LDA(At, 1, 0); PG8_S3;
;             PG8_WAIT_V(8); PG8_WAIT_L(0); PG8_BAR; PG8_MMAP(0, 1, 0); PG8_BAR; PG8_SCHED;
;             PG8_LDA(At, 1, 1); PG8_S4;
;             PG8_WAIT_V(8); PG8_WAIT_L(0); PG8_BAR; PG8_MMAP(1, 1, 1); PG8_BAR; PG8_SCHED;
	s_add_i32 s16, 0, 0x18000
	v_add_u32_e32 v8, s16, v148
	s_add_i32 s17, 0, 0x1c000
	s_nop 1
	ds_read_b128 v[0:3], v8
	ds_read_b128 v[4:7], v8 offset:16
	ds_read_b128 v[134:137], v8 offset:2048
	ds_read_b128 v[138:141], v8 offset:2064
	v_add_u32_e32 v8, s17, v148
	ds_read_b128 v[154:157], v8
	ds_read_b128 v[158:161], v8 offset:16
	ds_read_b128 v[162:165], v8 offset:2048
	ds_read_b128 v[166:169], v8 offset:2064
	s_add_u32 s60, s64, 0x20000
	v_mov_b32_e32 v68, v146
	s_mov_b32 m0, s89
	ds_read_b128 v[8:11], v151 offset:32768
	ds_read_b128 v[12:15], v151 offset:32784
	ds_read_b128 v[16:19], v151 offset:34816
	ds_read_b128 v[20:23], v151 offset:34832
	ds_read_b128 v[24:27], v151 offset:36864
	ds_read_b128 v[28:31], v151 offset:36880
	ds_read_b128 v[32:35], v151 offset:38912
	ds_read_b128 v[36:39], v151 offset:38928
	s_addc_u32 s61, s65, 0
	s_nop 0
	global_load_lds_dwordx4 v68, s[60:61]
	v_mov_b32_e32 v68, v147
	s_mov_b32 m0, s90
	s_nop 0
	global_load_lds_dwordx4 v68, s[60:61]
	s_waitcnt vmcnt(8)
	s_waitcnt lgkmcnt(0)
	s_barrier
	s_setprio 1
	s_waitcnt lgkmcnt(0)
	v_mfma_scale_f32_16x16x128_f8f6f4 v[124:127], v[0:7], v[8:15], v[124:127], v152, v152 op_sel_hi:[0,0,0]
	v_mfma_scale_f32_16x16x128_f8f6f4 v[108:111], v[154:161], v[8:15], v[108:111], v152, v152 op_sel_hi:[0,0,0]
	v_mfma_scale_f32_16x16x128_f8f6f4 v[120:123], v[134:141], v[8:15], v[120:123], v152, v152 op_sel_hi:[0,0,0]
	v_mfma_scale_f32_16x16x128_f8f6f4 v[100:103], v[162:169], v[8:15], v[100:103], v152, v152 op_sel_hi:[0,0,0]
	v_mfma_scale_f32_16x16x128_f8f6f4 v[116:119], v[0:7], v[16:23], v[116:119], v152, v152 op_sel_hi:[0,0,0]
	v_mfma_scale_f32_16x16x128_f8f6f4 v[92:95], v[154:161], v[16:23], v[142:145], v152, v152 op_sel_hi:[0,0,0]
	v_mfma_scale_f32_16x16x128_f8f6f4 v[112:115], v[134:141], v[16:23], v[112:115], v152, v152 op_sel_hi:[0,0,0]
	v_mfma_scale_f32_16x16x128_f8f6f4 v[84:87], v[162:169], v[16:23], v[178:181], v152, v152 op_sel_hi:[0,0,0]
	v_mfma_scale_f32_16x16x128_f8f6f4 v[104:107], v[0:7], v[24:31], v[104:107], v152, v152 op_sel_hi:[0,0,0]
	v_mfma_scale_f32_16x16x128_f8f6f4 v[76:79], v[154:161], v[24:31], v[182:185], v152, v152 op_sel_hi:[0,0,0]
	v_mfma_scale_f32_16x16x128_f8f6f4 v[96:99], v[134:141], v[24:31], v[186:189], v152, v152 op_sel_hi:[0,0,0]
	v_mfma_scale_f32_16x16x128_f8f6f4 v[72:75], v[162:169], v[24:31], v[190:193], v152, v152 op_sel_hi:[0,0,0]
	v_mfma_scale_f32_16x16x128_f8f6f4 v[88:91], v[0:7], v[32:39], v[194:197], v152, v152 op_sel_hi:[0,0,0]
	v_mfma_scale_f32_16x16x128_f8f6f4 v[68:71], v[154:161], v[32:39], v[198:201], v152, v152 op_sel_hi:[0,0,0]
	v_mfma_scale_f32_16x16x128_f8f6f4 v[80:83], v[134:141], v[32:39], v[210:213], v152, v152 op_sel_hi:[0,0,0]
	v_mfma_scale_f32_16x16x128_f8f6f4 v[60:63], v[162:169], v[32:39], v[60:63], v152, v152 op_sel_hi:[0,0,0]
	s_setprio 0
	s_barrier
	v_mov_b32_e32 v128, v146
	ds_read_b128 v[8:11], v151 offset:49152
	ds_read_b128 v[12:15], v151 offset:49168
	ds_read_b128 v[16:19], v151 offset:51200
	ds_read_b128 v[20:23], v151 offset:51216
	ds_read_b128 v[170:173], v151 offset:53248
	ds_read_b128 v[174:177], v151 offset:53264
	ds_read_b128 v[178:181], v151 offset:55296
	ds_read_b128 v[182:185], v151 offset:55312
	s_add_i32 s16, s16, s86
	v_lshl_add_u64 v[24:25], s[66:67], 0, v[128:129]
	v_lshl_add_u64 v[24:25], v[24:25], 0, s[26:27]
	s_mov_b32 m0, s16
	v_mov_b32_e32 v128, v147
	global_load_lds_dwordx4 v[24:25], off
	s_add_i32 m0, s16, 0x2000
	v_lshl_add_u64 v[24:25], s[66:67], 0, v[128:129]
	v_lshl_add_u64 v[24:25], v[24:25], 0, s[26:27]
	s_add_u32 s60, s66, 0x20080
	global_load_lds_dwordx4 v[24:25], off
	s_addc_u32 s61, s67, 0
	v_mov_b32_e32 v24, v146
	s_add_i32 s16, s17, s86
	s_mov_b32 m0, s16
	v_mov_b32_e32 v128, v146
	global_load_lds_dwordx4 v24, s[60:61]
	v_mov_b32_e32 v24, v147
	s_add_i32 m0, s16, 0x2000
	s_nop 0
	global_load_lds_dwordx4 v24, s[60:61]
	s_mov_b32 m0, s92
	v_lshl_add_u64 v[24:25], s[64:65], 0, v[128:129]
	v_lshl_add_u64 v[24:25], v[24:25], 0, s[26:27]
	v_mov_b32_e32 v128, v147
	global_load_lds_dwordx4 v[24:25], off
	s_mov_b32 m0, s93
	v_lshl_add_u64 v[24:25], s[64:65], 0, v[128:129]
	v_lshl_add_u64 v[24:25], v[24:25], 0, s[26:27]
	global_load_lds_dwordx4 v[24:25], off
	s_waitcnt vmcnt(8)
	s_waitcnt lgkmcnt(0)
	s_barrier
	s_setprio 1
	s_waitcnt lgkmcnt(0)
	v_mfma_scale_f32_16x16x128_f8f6f4 v[64:67], v[0:7], v[8:15], v[64:67], v152, v152 op_sel_hi:[0,0,0]
	v_mfma_scale_f32_16x16x128_f8f6f4 v[44:47], v[154:161], v[8:15], v[44:47], v152, v152 op_sel_hi:[0,0,0]
	v_mfma_scale_f32_16x16x128_f8f6f4 v[56:59], v[134:141], v[8:15], v[56:59], v152, v152 op_sel_hi:[0,0,0]
	v_mfma_scale_f32_16x16x128_f8f6f4 v[36:39], v[162:169], v[8:15], v[202:205], v152, v152 op_sel_hi:[0,0,0]
	v_mfma_scale_f32_16x16x128_f8f6f4 v[52:55], v[0:7], v[16:23], v[52:55], v152, v152 op_sel_hi:[0,0,0]
	v_mfma_scale_f32_16x16x128_f8f6f4 v[28:31], v[154:161], v[16:23], v[206:209], v152, v152 op_sel_hi:[0,0,0]
	v_mfma_scale_f32_16x16x128_f8f6f4 v[48:51], v[134:141], v[16:23], v[48:51], v152, v152 op_sel_hi:[0,0,0]
	v_mfma_scale_f32_16x16x128_f8f6f4 v[20:23], v[162:169], v[16:23], v[214:217], v152, v152 op_sel_hi:[0,0,0]
	v_mfma_scale_f32_16x16x128_f8f6f4 v[40:43], v[0:7], v[170:177], v[40:43], v152, v152 op_sel_hi:[0,0,0]
	v_mfma_scale_f32_16x16x128_f8f6f4 v[12:15], v[154:161], v[170:177], v[218:221], v152, v152 op_sel_hi:[0,0,0]
	v_mfma_scale_f32_16x16x128_f8f6f4 v[32:35], v[134:141], v[170:177], v[222:225], v152, v152 op_sel_hi:[0,0,0]
	v_mfma_scale_f32_16x16x128_f8f6f4 v[8:11], v[162:169], v[170:177], v[226:229], v152, v152 op_sel_hi:[0,0,0]
	v_mfma_scale_f32_16x16x128_f8f6f4 v[24:27], v[0:7], v[178:185], v[230:233], v152, v152 op_sel_hi:[0,0,0]
	v_mfma_scale_f32_16x16x128_f8f6f4 v[4:7], v[154:161], v[178:185], v[234:237], v152, v152 op_sel_hi:[0,0,0]
	v_mfma_scale_f32_16x16x128_f8f6f4 v[16:19], v[134:141], v[178:185], v[238:241], v152, v152 op_sel_hi:[0,0,0]
	v_mfma_scale_f32_16x16x128_f8f6f4 v[0:3], v[162:169], v[178:185], v[242:245], v152, v152 op_sel_hi:[0,0,0]
	s_setprio 0
	s_barrier
	s_add_u32 s52, s52, 0x100
	s_addc_u32 s53, s53, 0
	s_add_u32 s30, s30, 0x100
	s_addc_u32 s31, s31, 0
	s_cmp_ge_i32 s45, s20
	s_mov_b32 s47, s45
	s_cbranch_scc1 .Lpeel_exit_lbb0_779

; #define PG8_BAR __builtin_amdgcn_s_barrier()
;     __device__ __forceinline__ void operator()(const f32x4 (&acc)[2][2][4][2], const Unit& u, int wr, int wc, int fr, int fq) const {
;     ...
;         for (int ai = 0; ai < 2; ++ai)
; #pragma unroll
;             for (int m = 0; m < 4; ++m) { const int row = row0 + ai * HALF + m * 16;
;                 const float* xr = (row < TP ? xp + (size_t)row * DM : xs + (size_t)(row - TP) * DM) + col0;
;                 bf16_t* brow = x1b + (size_t)row * DM + col0; float ss = 0.f;
; #pragma unroll
;                 for (int bj = 0; bj < 2; ++bj)
; #pragma unroll
;                     for (int n = 0; n < 2; ++n) { const int co = bj * HALF + n * 16; const f32x4 v = *(const f32x4*)(xr + co) + acc[ai][bj][m][n] * sc;
; template <class Epi, class SchedT, bool ALIGN_EPI, bool SP2, bool FP8 = false>
; __device__ __forceinline__ void gemm_phase(LAS unsigned char* lds, const Gemm g, const SchedT& S, const Epi& E, const int wid) {
;     ...
;         if constexpr (ALIGN_EPI) { if (wr == 0) PG8_BAR; }
.Lpeel_exit_lbb0_779:
	v_pk_mul_f32 v[142:143], v[126:127], s[42:43] op_sel_hi:[1,0]
	v_pk_mul_f32 v[144:145], v[124:125], s[42:43] op_sel_hi:[1,0]
	v_pk_mul_f32 v[136:137], v[122:123], s[42:43] op_sel_hi:[1,0]
	v_pk_mul_f32 v[134:135], v[120:121], s[42:43] op_sel_hi:[1,0]
	v_pk_mul_f32 v[140:141], v[110:111], s[42:43] op_sel_hi:[1,0]
	v_pk_mul_f32 v[138:139], v[108:109], s[42:43] op_sel_hi:[1,0]
	v_pk_mul_f32 v[126:127], v[102:103], s[42:43] op_sel_hi:[1,0]
	v_pk_mul_f32 v[124:125], v[100:101], s[42:43] op_sel_hi:[1,0]
	v_pk_mul_f32 v[122:123], v[118:119], s[42:43] op_sel_hi:[1,0]
	v_pk_mul_f32 v[120:121], v[116:117], s[42:43] op_sel_hi:[1,0]
	v_pk_mul_f32 v[114:115], v[114:115], s[42:43] op_sel_hi:[1,0]
	v_pk_mul_f32 v[112:113], v[112:113], s[42:43] op_sel_hi:[1,0]
	v_pk_mul_f32 v[118:119], v[94:95], s[42:43] op_sel_hi:[1,0]
	v_pk_mul_f32 v[116:117], v[92:93], s[42:43] op_sel_hi:[1,0]
	v_pk_mul_f32 v[110:111], v[86:87], s[42:43] op_sel_hi:[1,0]
	v_pk_mul_f32 v[108:109], v[84:85], s[42:43] op_sel_hi:[1,0]
	v_pk_mul_f32 v[106:107], v[106:107], s[42:43] op_sel_hi:[1,0]
	v_pk_mul_f32 v[104:105], v[104:105], s[42:43] op_sel_hi:[1,0]
	v_pk_mul_f32 v[98:99], v[98:99], s[42:43] op_sel_hi:[1,0]
	v_pk_mul_f32 v[96:97], v[96:97], s[42:43] op_sel_hi:[1,0]
	v_pk_mul_f32 v[102:103], v[78:79], s[42:43] op_sel_hi:[1,0]
	v_pk_mul_f32 v[100:101], v[76:77], s[42:43] op_sel_hi:[1,0]
	v_pk_mul_f32 v[94:95], v[74:75], s[42:43] op_sel_hi:[1,0]
	v_pk_mul_f32 v[92:93], v[72:73], s[42:43] op_sel_hi:[1,0]
	v_pk_mul_f32 v[90:91], v[90:91], s[42:43] op_sel_hi:[1,0]
	v_pk_mul_f32 v[88:89], v[88:89], s[42:43] op_sel_hi:[1,0]
	v_pk_mul_f32 v[82:83], v[82:83], s[42:43] op_sel_hi:[1,0]
	v_pk_mul_f32 v[80:81], v[80:81], s[42:43] op_sel_hi:[1,0]
	v_pk_mul_f32 v[86:87], v[70:71], s[42:43] op_sel_hi:[1,0]
	v_pk_mul_f32 v[84:85], v[68:69], s[42:43] op_sel_hi:[1,0]
	v_pk_mul_f32 v[78:79], v[62:63], s[42:43] op_sel_hi:[1,0]
	v_pk_mul_f32 v[76:77], v[60:61], s[42:43] op_sel_hi:[1,0]
	v_pk_mul_f32 v[74:75], v[66:67], s[42:43] op_sel_hi:[1,0]
	v_pk_mul_f32 v[72:73], v[64:65], s[42:43] op_sel_hi:[1,0]
	v_pk_mul_f32 v[66:67], v[58:59], s[42:43] op_sel_hi:[1,0]
	v_pk_mul_f32 v[64:65], v[56:57], s[42:43] op_sel_hi:[1,0]
	v_pk_mul_f32 v[70:71], v[46:47], s[42:43] op_sel_hi:[1,0]
	v_pk_mul_f32 v[68:69], v[44:45], s[42:43] op_sel_hi:[1,0]
	v_pk_mul_f32 v[62:63], v[38:39], s[42:43] op_sel_hi:[1,0]
	v_pk_mul_f32 v[60:61], v[36:37], s[42:43] op_sel_hi:[1,0]
	v_pk_mul_f32 v[58:59], v[54:55], s[42:43] op_sel_hi:[1,0]
	v_pk_mul_f32 v[56:57], v[52:53], s[42:43] op_sel_hi:[1,0]
	v_pk_mul_f32 v[50:51], v[50:51], s[42:43] op_sel_hi:[1,0]
	v_pk_mul_f32 v[48:49], v[48:49], s[42:43] op_sel_hi:[1,0]
	v_pk_mul_f32 v[54:55], v[30:31], s[42:43] op_sel_hi:[1,0]
	v_pk_mul_f32 v[52:53], v[28:29], s[42:43] op_sel_hi:[1,0]
	v_pk_mul_f32 v[46:47], v[22:23], s[42:43] op_sel_hi:[1,0]
	v_pk_mul_f32 v[44:45], v[20:21], s[42:43] op_sel_hi:[1,0]
	v_pk_mul_f32 v[38:39], v[42:43], s[42:43] op_sel_hi:[1,0]
	v_pk_mul_f32 v[36:37], v[40:41], s[42:43] op_sel_hi:[1,0]
	v_pk_mul_f32 v[30:31], v[34:35], s[42:43] op_sel_hi:[1,0]
	v_pk_mul_f32 v[28:29], v[32:33], s[42:43] op_sel_hi:[1,0]
	v_pk_mul_f32 v[34:35], v[14:15], s[42:43] op_sel_hi:[1,0]
	v_pk_mul_f32 v[32:33], v[12:13], s[42:43] op_sel_hi:[1,0]
	v_pk_mul_f32 v[22:23], v[10:11], s[42:43] op_sel_hi:[1,0]
	v_pk_mul_f32 v[20:21], v[8:9], s[42:43] op_sel_hi:[1,0]
	v_pk_mul_f32 v[14:15], v[26:27], s[42:43] op_sel_hi:[1,0]
	v_pk_mul_f32 v[12:13], v[24:25], s[42:43] op_sel_hi:[1,0]
	v_pk_mul_f32 v[10:11], v[18:19], s[42:43] op_sel_hi:[1,0]
	v_pk_mul_f32 v[8:9], v[16:17], s[42:43] op_sel_hi:[1,0]
	v_pk_mul_f32 v[6:7], v[6:7], s[42:43] op_sel_hi:[1,0]
	v_pk_mul_f32 v[4:5], v[4:5], s[42:43] op_sel_hi:[1,0]
	v_pk_mul_f32 v[2:3], v[2:3], s[42:43] op_sel_hi:[1,0]
	v_pk_mul_f32 v[0:1], v[0:1], s[42:43] op_sel_hi:[1,0]
	s_and_b64 vcc, exec, s[96:97]
	s_cbranch_vccz .LBB0_782

; #define PG8_LDA(dst, b, h) do { if constexpr (FP8) { _Pragma("unroll") for (int m = 0; m < 4; ++m) dst##8[m] = PG8_LD8(PG8_SA(b, h), aoff, aoff1, m); } \
;         else { _Pragma("unroll") for (int m = 0; m < 4; ++m) _Pragma("unroll") for (int k = 0; k < 2; ++k) dst[m][k] = *(const LAS bf16x8*)(lds + PG8_SA(b, h) + (k ? aoff1 : aoff) + m * 2048); } } while (0)
; #define PG8_LDB(dst, b, h) do { if constexpr (FP8) { dst##8[0] = PG8_LD8(PG8_SB(b, h), boff, boff1, 0); dst##8[1] = PG8_LD8(PG8_SB(b, h), boff, boff1, 1); } \
;         else { _Pragma("unroll") for (int n = 0; n < 2; ++n) _Pragma("unroll") for (int k = 0; k < 2; ++k) dst[n][k] = *(const LAS bf16x8*)(lds + PG8_SB(b, h) + (k ? boff1 : boff) + n * 2048); } } while (0)
; #define PG8_WAIT_V(n) asm volatile("s_waitcnt vmcnt(" #n ")" ::: "memory")
; #define PG8_WAIT_L(n) asm volatile("s_waitcnt lgkmcnt(" #n ")" ::: "memory")
; #define PG8_BAR __builtin_amdgcn_s_barrier()
; #define PG8_SCHED __builtin_amdgcn_sched_barrier(0)
; #define PG8_S1 PG8_STAGE(PG8_SA(1, 1), a1 + hstepA, voffA)
; template <class Epi, class SchedT, bool ALIGN_EPI, bool SP2, bool FP8 = false>
; __device__ __forceinline__ void gemm_phase(LAS unsigned char* lds, const Gemm g, const SchedT& S, const Epi& E, const int wid) {
;     ...
;         const bool has_next = S.next(ui + 1, nxt);
;         const char* nA = has_next ? (const char*)g.A + (size_t)nxt.pm * tstepA + (size_t)nxt.aoff * 2 : cA; const char* nB = has_next ? (const char*)g.Bt + (size_t)nxt.pn * tstepB + (size_t)nxt.boff * 2 : cB;
;         const int nt = cur.nt;
;         for (int t = 0; t < nt; t += 2) {
;             const bool last = (t == nt - 2);
;             const char* a1 = cA + (size_t)(t + 1) * kstep;
;             const char* a2 = last ? nA : cA + (size_t)(t + 2) * kstep; const char* b2 = last ? nB : cB + (size_t)(t + 2) * kstep;
;             const char* a3 = a2 + kstep; const char* b3 = b2 + kstep;
;             if constexpr (SP2) {
;     ...
;             PG8_LDB(B0, 0, 0); PG8_LDB(B1, 0, 1); PG8_SCHED; PG8_LDA(At, 0, 0); PG8_S1;
;             PG8_WAIT_V(8); PG8_WAIT_L(0); PG8_BAR; PG8_MMAP(0, 0, 0); PG8_BAR; PG8_SCHED;
;             PG8_LDA(At, 0, 1); PG8_S2;
;             PG8_WAIT_V(8); PG8_WAIT_L(0); PG8_BAR; PG8_MMAP(1, 0, 1); PG8_BAR; PG8_SCHED;
.LBB0_897:
	s_ashr_i32 s27, s26, 31
	s_lshl_b64 s[24:25], s[26:27], 19
	s_add_u32 s40, s2, s24
	s_addc_u32 s41, s3, s25
	s_ashr_i32 s15, s14, 31
	s_lshl_b64 s[24:25], s[14:15], 19
	s_add_u32 s42, s18, s24
	s_addc_u32 s43, s19, s25
	s_cmp_lt_i32 s20, 1
	s_cbranch_scc1 .LBB0_893
	v_cmp_lt_i64_e32 vcc, s[52:53], v[146:147]
	s_and_b64 s[24:25], vcc, exec
	s_cselect_b32 s15, s41, s49
	s_cselect_b32 s21, s40, s48
	s_cselect_b32 s24, s43, s51
	s_cselect_b32 s25, s42, s50
	s_add_i32 s27, s20, -2
	s_add_u32 s48, s48, 0x40080
	s_addc_u32 s49, s49, 0
	s_add_u32 s30, s50, 0x100
	s_addc_u32 s31, s51, 0
	s_mov_b32 s34, 0
	ds_read_b128 v[128:131], v173
	ds_read_b128 v[132:135], v173 offset:1024
	ds_read_b128 v[136:139], v174
	ds_read_b128 v[140:143], v174 offset:1024
	ds_read_b128 v[150:153], v175
	ds_read_b128 v[154:157], v175 offset:1024
	ds_read_b128 v[158:161], v176
	ds_read_b128 v[162:165], v176 offset:1024
	s_add_i32 s35, s34, 2
	s_add_u32 s16, s48, 0xfffc0080
	s_addc_u32 s17, s49, -1
	s_cmp_eq_u32 s27, s34
	s_cselect_b32 s51, s15, s17
	s_cselect_b32 s50, s21, s16
	s_cselect_b32 s53, s24, s31
	s_cselect_b32 s52, s25, s30
	v_mov_b32_e32 v144, v168
	ds_read_b128 v[182:185], v177
	ds_read_b128 v[186:189], v177 offset:1024
	ds_read_b128 v[190:193], v177 offset:2048
	ds_read_b128 v[194:197], v177 offset:3072
	ds_read_b128 v[198:201], v177 offset:4096
	ds_read_b128 v[202:205], v177 offset:5120
	ds_read_b128 v[206:209], v177 offset:6144
	ds_read_b128 v[210:213], v177 offset:7168
	s_add_i32 m0, s87, 0xc000
	s_nop 0
	global_load_lds_dwordx4 v144, s[48:49]
	v_mov_b32_e32 v144, v170
	s_add_i32 m0, s87, 0xe000
	s_nop 0
	global_load_lds_dwordx4 v144, s[48:49]
	s_waitcnt vmcnt(8)
	s_waitcnt lgkmcnt(0)
	s_barrier
	s_setprio 1
	s_waitcnt lgkmcnt(0)
	v_mfma_f32_16x16x32_bf16 v[124:127], v[128:131], v[182:185], 0
	v_mfma_f32_16x16x32_bf16 v[120:123], v[136:139], v[182:185], 0
	v_mfma_f32_16x16x32_bf16 v[104:107], v[136:139], v[190:193], 0
	v_mfma_f32_16x16x32_bf16 v[108:111], v[128:131], v[190:193], 0
	v_mfma_f32_16x16x32_bf16 v[92:95], v[128:131], v[198:201], 0
	v_mfma_f32_16x16x32_bf16 v[88:91], v[136:139], v[198:201], 0
	v_mfma_f32_16x16x32_bf16 v[72:75], v[136:139], v[206:209], 0
	v_mfma_f32_16x16x32_bf16 v[76:79], v[128:131], v[206:209], 0
	s_setprio 0
	s_setprio 1
	v_mfma_f32_16x16x32_bf16 v[124:127], v[132:135], v[186:189], v[124:127]
	v_mfma_f32_16x16x32_bf16 v[120:123], v[140:143], v[186:189], v[120:123]
	v_mfma_f32_16x16x32_bf16 v[104:107], v[140:143], v[194:197], v[104:107]
	v_mfma_f32_16x16x32_bf16 v[108:111], v[132:135], v[194:197], v[108:111]
	v_mfma_f32_16x16x32_bf16 v[92:95], v[132:135], v[202:205], v[92:95]
	v_mfma_f32_16x16x32_bf16 v[88:91], v[140:143], v[202:205], v[88:91]
	v_mfma_f32_16x16x32_bf16 v[72:75], v[140:143], v[210:213], v[72:75]
	v_mfma_f32_16x16x32_bf16 v[76:79], v[132:135], v[210:213], v[76:79]
	s_setprio 0
	s_setprio 1
	v_mfma_f32_16x16x32_bf16 v[116:119], v[150:153], v[182:185], 0
	v_mfma_f32_16x16x32_bf16 v[112:115], v[158:161], v[182:185], 0
	v_mfma_f32_16x16x32_bf16 v[96:99], v[158:161], v[190:193], 0
	v_mfma_f32_16x16x32_bf16 v[100:103], v[150:153], v[190:193], 0
	v_mfma_f32_16x16x32_bf16 v[84:87], v[150:153], v[198:201], 0
	v_mfma_f32_16x16x32_bf16 v[80:83], v[158:161], v[198:201], 0
	v_mfma_f32_16x16x32_bf16 v[64:67], v[158:161], v[206:209], 0
	v_mfma_f32_16x16x32_bf16 v[68:71], v[150:153], v[206:209], 0
	s_setprio 0
	s_setprio 1
	v_mfma_f32_16x16x32_bf16 v[116:119], v[154:157], v[186:189], v[116:119]
	v_mfma_f32_16x16x32_bf16 v[112:115], v[162:165], v[186:189], v[112:115]
	v_mfma_f32_16x16x32_bf16 v[96:99], v[162:165], v[194:197], v[96:99]
	v_mfma_f32_16x16x32_bf16 v[100:103], v[154:157], v[194:197], v[100:103]
	v_mfma_f32_16x16x32_bf16 v[84:87], v[154:157], v[202:205], v[84:87]
	v_mfma_f32_16x16x32_bf16 v[80:83], v[162:165], v[202:205], v[80:83]
	v_mfma_f32_16x16x32_bf16 v[64:67], v[162:165], v[210:213], v[64:67]
	v_mfma_f32_16x16x32_bf16 v[68:71], v[154:157], v[210:213], v[68:71]
	s_setprio 0
	s_barrier
	v_mov_b32_e32 v144, v169
	s_add_i32 s16, s94, s86
	ds_read_b128 v[182:185], v177 offset:16384
	ds_read_b128 v[186:189], v177 offset:17408
	ds_read_b128 v[190:193], v177 offset:18432
	ds_read_b128 v[194:197], v177 offset:19456
	ds_read_b128 v[198:201], v177 offset:20480
	ds_read_b128 v[202:205], v177 offset:21504
	ds_read_b128 v[206:209], v177 offset:22528
	ds_read_b128 v[210:213], v177 offset:23552
	s_mov_b32 m0, s16
	s_nop 0
	global_load_lds_dwordx4 v144, s[52:53]
	v_mov_b32_e32 v144, v171
	s_add_i32 m0, s16, 0x2000
	s_add_u32 s60, s52, 0x40000
	global_load_lds_dwordx4 v144, s[52:53]
	s_addc_u32 s61, s53, 0
	v_mov_b32_e32 v144, v169
	s_add_i32 s16, s95, s86
	s_mov_b32 m0, s16
	s_nop 0
	global_load_lds_dwordx4 v144, s[60:61]
	v_mov_b32_e32 v144, v171
	s_add_i32 m0, s16, 0x2000
	s_nop 0
	global_load_lds_dwordx4 v144, s[60:61]
	v_mov_b32_e32 v144, v168
	s_mov_b32 m0, s87
	s_nop 0
	global_load_lds_dwordx4 v144, s[50:51]
	v_mov_b32_e32 v144, v170
	s_mov_b32 m0, s88
	s_nop 0
	global_load_lds_dwordx4 v144, s[50:51]
	s_waitcnt vmcnt(8)
	s_waitcnt lgkmcnt(0)
	s_barrier
; #define PG8_LDA(dst, b, h) do { if constexpr (FP8) { _Pragma("unroll") for (int m = 0; m < 4; ++m) dst##8[m] = PG8_LD8(PG8_SA(b, h), aoff, aoff1, m); } \
;         else { _Pragma("unroll") for (int m = 0; m < 4; ++m) _Pragma("unroll") for (int k = 0; k < 2; ++k) dst[m][k] = *(const LAS bf16x8*)(lds + PG8_SA(b, h) + (k ? aoff1 : aoff) + m * 2048); } } while (0)
; #define PG8_LDB(dst, b, h) do { if constexpr (FP8) { dst##8[0] = PG8_LD8(PG8_SB(b, h), boff, boff1, 0); dst##8[1] = PG8_LD8(PG8_SB(b, h), boff, boff1, 1); } \
;         else { _Pragma("unroll") for (int n = 0; n < 2; ++n) _Pragma("unroll") for (int k = 0; k < 2; ++k) dst[n][k] = *(const LAS bf16x8*)(lds + PG8_SB(b, h) + (k ? boff1 : boff) + n * 2048); } } while (0)
; #define PG8_WAIT_V(n) asm volatile("s_waitcnt vmcnt(" #n ")" ::: "memory")
; #define PG8_WAIT_L(n) asm volatile("s_waitcnt lgkmcnt(" #n ")" ::: "memory")
; #define PG8_BAR __builtin_amdgcn_s_barrier()
; #define PG8_SCHED __builtin_amdgcn_sched_barrier(0)
; #define PG8_S2 do { PG8_STAGE(PG8_SB(0, 0), b2, voffB); PG8_STAGE(PG8_SB(0, 1), b2 + hstepB, voffB); PG8_STAGE(PG8_SA(0, 0), a2, voffA); } while (0)
; #define PG8_S3 PG8_STAGE(PG8_SA(0, 1), a2 + hstepA, voffA)
; template <class Epi, class SchedT, bool ALIGN_EPI, bool SP2, bool FP8 = false>
; __device__ __forceinline__ void gemm_phase(LAS unsigned char* lds, const Gemm g, const SchedT& S, const Epi& E, const int wid) {
;     ...
;             PG8_LDA(At, 0, 1); PG8_S2;
;             PG8_WAIT_V(8); PG8_WAIT_L(0); PG8_BAR; PG8_MMAP(1, 0, 1); PG8_BAR; PG8_SCHED;
;             PG8_LDB(B0, 1, 0); PG8_LDB(B1, 1, 1); PG8_SCHED; PG8_LDA(At, 1, 0); PG8_S3;
;             PG8_WAIT_V(8); PG8_WAIT_L(0); PG8_BAR; PG8_MMAP(0, 1, 0); PG8_BAR; PG8_SCHED;
	s_setprio 1
	s_waitcnt lgkmcnt(0)
	v_mfma_f32_16x16x32_bf16 v[60:63], v[128:131], v[182:185], 0
	v_mfma_f32_16x16x32_bf16 v[56:59], v[136:139], v[182:185], 0
	v_mfma_f32_16x16x32_bf16 v[40:43], v[136:139], v[190:193], 0
	v_mfma_f32_16x16x32_bf16 v[44:47], v[128:131], v[190:193], 0
	v_mfma_f32_16x16x32_bf16 v[28:31], v[128:131], v[198:201], 0
	v_mfma_f32_16x16x32_bf16 v[24:27], v[136:139], v[198:201], 0
	v_mfma_f32_16x16x32_bf16 v[8:11], v[136:139], v[206:209], 0
	v_mfma_f32_16x16x32_bf16 v[12:15], v[128:131], v[206:209], 0
	s_setprio 0
	s_setprio 1
	v_mfma_f32_16x16x32_bf16 v[60:63], v[132:135], v[186:189], v[60:63]
	v_mfma_f32_16x16x32_bf16 v[56:59], v[140:143], v[186:189], v[56:59]
	v_mfma_f32_16x16x32_bf16 v[40:43], v[140:143], v[194:197], v[40:43]
	v_mfma_f32_16x16x32_bf16 v[44:47], v[132:135], v[194:197], v[44:47]
	v_mfma_f32_16x16x32_bf16 v[28:31], v[132:135], v[202:205], v[28:31]
	v_mfma_f32_16x16x32_bf16 v[24:27], v[140:143], v[202:205], v[24:27]
	v_mfma_f32_16x16x32_bf16 v[8:11], v[140:143], v[210:213], v[8:11]
	v_mfma_f32_16x16x32_bf16 v[12:15], v[132:135], v[210:213], v[12:15]
	s_setprio 0
	s_setprio 1
	v_mfma_f32_16x16x32_bf16 v[52:55], v[150:153], v[182:185], 0
	v_mfma_f32_16x16x32_bf16 v[48:51], v[158:161], v[182:185], 0
	v_mfma_f32_16x16x32_bf16 v[32:35], v[158:161], v[190:193], 0
	v_mfma_f32_16x16x32_bf16 v[36:39], v[150:153], v[190:193], 0
	v_mfma_f32_16x16x32_bf16 v[20:23], v[150:153], v[198:201], 0
	v_mfma_f32_16x16x32_bf16 v[16:19], v[158:161], v[198:201], 0
	v_mfma_f32_16x16x32_bf16 v[0:3], v[158:161], v[206:209], 0
	v_mfma_f32_16x16x32_bf16 v[4:7], v[150:153], v[206:209], 0
	s_setprio 0
	s_setprio 1
	v_mfma_f32_16x16x32_bf16 v[52:55], v[154:157], v[186:189], v[52:55]
	v_mfma_f32_16x16x32_bf16 v[48:51], v[162:165], v[186:189], v[48:51]
	v_mfma_f32_16x16x32_bf16 v[32:35], v[162:165], v[194:197], v[32:35]
	v_mfma_f32_16x16x32_bf16 v[36:39], v[154:157], v[194:197], v[36:39]
	v_mfma_f32_16x16x32_bf16 v[20:23], v[154:157], v[202:205], v[20:23]
	v_mfma_f32_16x16x32_bf16 v[16:19], v[162:165], v[202:205], v[16:19]
	v_mfma_f32_16x16x32_bf16 v[0:3], v[162:165], v[210:213], v[0:3]
	v_mfma_f32_16x16x32_bf16 v[4:7], v[154:157], v[210:213], v[4:7]
	s_setprio 0
	s_barrier
	s_add_i32 s16, 0, 0x18000
	s_add_i32 s17, 0, 0x1c000
	v_add_u32_e32 v132, s16, v172
	v_add_u32_e32 v144, s17, v172
	ds_read_b128 v[128:131], v132
	ds_read_b128 v[132:135], v132 offset:1024
	ds_read_b128 v[136:139], v178
	ds_read_b128 v[140:143], v178 offset:1024
	ds_read_b128 v[150:153], v144
	ds_read_b128 v[154:157], v144 offset:1024
	ds_read_b128 v[158:161], v179
	ds_read_b128 v[162:165], v179 offset:1024
	s_add_u32 s60, s50, 0x40000
	v_mov_b32_e32 v144, v168
	s_mov_b32 m0, s89
	ds_read_b128 v[182:185], v177 offset:32768
	ds_read_b128 v[186:189], v177 offset:33792
	ds_read_b128 v[190:193], v177 offset:34816
	ds_read_b128 v[194:197], v177 offset:35840
	ds_read_b128 v[198:201], v177 offset:36864
	ds_read_b128 v[202:205], v177 offset:37888
	ds_read_b128 v[206:209], v177 offset:38912
	ds_read_b128 v[210:213], v177 offset:39936
	s_addc_u32 s61, s51, 0
	s_nop 0
	global_load_lds_dwordx4 v144, s[60:61]
	v_mov_b32_e32 v144, v170
	s_mov_b32 m0, s90
	s_nop 0
	global_load_lds_dwordx4 v144, s[60:61]
	s_waitcnt vmcnt(8)
	s_waitcnt lgkmcnt(0)
	s_barrier
	s_setprio 1
	s_waitcnt lgkmcnt(0)
	v_mfma_f32_16x16x32_bf16 v[124:127], v[128:131], v[182:185], v[124:127]
	v_mfma_f32_16x16x32_bf16 v[120:123], v[136:139], v[182:185], v[120:123]
	v_mfma_f32_16x16x32_bf16 v[104:107], v[136:139], v[190:193], v[104:107]
	v_mfma_f32_16x16x32_bf16 v[108:111], v[128:131], v[190:193], v[108:111]
	v_mfma_f32_16x16x32_bf16 v[92:95], v[128:131], v[198:201], v[92:95]
	v_mfma_f32_16x16x32_bf16 v[88:91], v[136:139], v[198:201], v[88:91]
	v_mfma_f32_16x16x32_bf16 v[72:75], v[136:139], v[206:209], v[72:75]
	v_mfma_f32_16x16x32_bf16 v[76:79], v[128:131], v[206:209], v[76:79]
	s_setprio 0
	s_setprio 1
	v_mfma_f32_16x16x32_bf16 v[124:127], v[132:135], v[186:189], v[124:127]
	v_mfma_f32_16x16x32_bf16 v[120:123], v[140:143], v[186:189], v[120:123]
	v_mfma_f32_16x16x32_bf16 v[104:107], v[140:143], v[194:197], v[104:107]
	v_mfma_f32_16x16x32_bf16 v[108:111], v[132:135], v[194:197], v[108:111]
	v_mfma_f32_16x16x32_bf16 v[92:95], v[132:135], v[202:205], v[92:95]
	v_mfma_f32_16x16x32_bf16 v[88:91], v[140:143], v[202:205], v[88:91]
	v_mfma_f32_16x16x32_bf16 v[72:75], v[140:143], v[210:213], v[72:75]
	v_mfma_f32_16x16x32_bf16 v[76:79], v[132:135], v[210:213], v[76:79]
	s_setprio 0
	s_setprio 1
	v_mfma_f32_16x16x32_bf16 v[116:119], v[150:153], v[182:185], v[116:119]
	v_mfma_f32_16x16x32_bf16 v[112:115], v[158:161], v[182:185], v[112:115]
	v_mfma_f32_16x16x32_bf16 v[96:99], v[158:161], v[190:193], v[96:99]
	v_mfma_f32_16x16x32_bf16 v[100:103], v[150:153], v[190:193], v[100:103]
	v_mfma_f32_16x16x32_bf16 v[84:87], v[150:153], v[198:201], v[84:87]
	v_mfma_f32_16x16x32_bf16 v[80:83], v[158:161], v[198:201], v[80:83]
	v_mfma_f32_16x16x32_bf16 v[64:67], v[158:161], v[206:209], v[64:67]
	v_mfma_f32_16x16x32_bf16 v[68:71], v[150:153], v[206:209], v[68:71]
	s_setprio 0
	s_setprio 1
	v_mfma_f32_16x16x32_bf16 v[116:119], v[154:157], v[186:189], v[116:119]
	v_mfma_f32_16x16x32_bf16 v[112:115], v[162:165], v[186:189], v[112:115]
	v_mfma_f32_16x16x32_bf16 v[96:99], v[162:165], v[194:197], v[96:99]
	v_mfma_f32_16x16x32_bf16 v[100:103], v[154:157], v[194:197], v[100:103]
	v_mfma_f32_16x16x32_bf16 v[84:87], v[154:157], v[202:205], v[84:87]
	v_mfma_f32_16x16x32_bf16 v[80:83], v[162:165], v[202:205], v[80:83]
	v_mfma_f32_16x16x32_bf16 v[64:67], v[162:165], v[210:213], v[64:67]
	v_mfma_f32_16x16x32_bf16 v[68:71], v[154:157], v[210:213], v[68:71]
	s_setprio 0
	s_barrier
; #define PG8_LDA(dst, b, h) do { if constexpr (FP8) { _Pragma("unroll") for (int m = 0; m < 4; ++m) dst##8[m] = PG8_LD8(PG8_SA(b, h), aoff, aoff1, m); } \
;         else { _Pragma("unroll") for (int m = 0; m < 4; ++m) _Pragma("unroll") for (int k = 0; k < 2; ++k) dst[m][k] = *(const LAS bf16x8*)(lds + PG8_SA(b, h) + (k ? aoff1 : aoff) + m * 2048); } } while (0)
; #define PG8_LDB(dst, b, h) do { if constexpr (FP8) { dst##8[0] = PG8_LD8(PG8_SB(b, h), boff, boff1, 0); dst##8[1] = PG8_LD8(PG8_SB(b, h), boff, boff1, 1); } \
;         else { _Pragma("unroll") for (int n = 0; n < 2; ++n) _Pragma("unroll") for (int k = 0; k < 2; ++k) dst[n][k] = *(const LAS bf16x8*)(lds + PG8_SB(b, h) + (k ? boff1 : boff) + n * 2048); } } while (0)
; #define PG8_WAIT_V(n) asm volatile("s_waitcnt vmcnt(" #n ")" ::: "memory")
; #define PG8_WAIT_L(n) asm volatile("s_waitcnt lgkmcnt(" #n ")" ::: "memory")
; #define PG8_BAR __builtin_amdgcn_s_barrier()
; #define PG8_SCHED __builtin_amdgcn_sched_barrier(0)
; #define PG8_S1 PG8_STAGE(PG8_SA(1, 1), a1 + hstepA, voffA)
; #define PG8_S4 do { PG8_STAGE(PG8_SB(1, 0), b3, voffB); PG8_STAGE(PG8_SB(1, 1), b3 + hstepB, voffB); PG8_STAGE(PG8_SA(1, 0), a3, voffA); } while (0)
; template <class Epi, class SchedT, bool ALIGN_EPI, bool SP2, bool FP8 = false>
; __device__ __forceinline__ void gemm_phase(LAS unsigned char* lds, const Gemm g, const SchedT& S, const Epi& E, const int wid) {
;     ...
;             PG8_LDB(B0, 0, 0); PG8_LDB(B1, 0, 1); PG8_SCHED; PG8_LDA(At, 0, 0); PG8_S1;
;             PG8_WAIT_V(8); PG8_WAIT_L(0); PG8_BAR; PG8_MMAP(0, 0, 0); PG8_BAR; PG8_SCHED;
;     ...
;             PG8_LDA(At, 1, 1); PG8_S4;
;             PG8_WAIT_V(8); PG8_WAIT_L(0); PG8_BAR; PG8_MMAP(1, 1, 1); PG8_BAR; PG8_SCHED;
	v_mov_b32_e32 v144, v169
	ds_read_b128 v[182:185], v177 offset:49152
	ds_read_b128 v[186:189], v177 offset:50176
	ds_read_b128 v[190:193], v177 offset:51200
	ds_read_b128 v[194:197], v177 offset:52224
	ds_read_b128 v[198:201], v177 offset:53248
	ds_read_b128 v[202:205], v177 offset:54272
	ds_read_b128 v[206:209], v177 offset:55296
	ds_read_b128 v[210:213], v177 offset:56320
	s_add_i32 s16, s16, s86
	v_lshl_add_u64 v[166:167], s[52:53], 0, v[144:145]
	v_lshl_add_u64 v[166:167], v[166:167], 0, s[6:7]
	s_mov_b32 m0, s16
	v_mov_b32_e32 v144, v171
	global_load_lds_dwordx4 v[166:167], off
	s_add_i32 m0, s16, 0x2000
	s_nop 0
	v_lshl_add_u64 v[166:167], s[52:53], 0, v[144:145]
	s_add_u32 s52, s52, 0x40080
	v_lshl_add_u64 v[166:167], v[166:167], 0, s[6:7]
	s_addc_u32 s53, s53, 0
	v_mov_b32_e32 v144, v169
	s_add_i32 s16, s17, s86
	global_load_lds_dwordx4 v[166:167], off
	s_mov_b32 m0, s16
	s_nop 0
	global_load_lds_dwordx4 v144, s[52:53]
	v_mov_b32_e32 v144, v171
	s_add_i32 m0, s16, 0x2000
	s_nop 0
	global_load_lds_dwordx4 v144, s[52:53]
	v_mov_b32_e32 v144, v168
	s_mov_b32 m0, s92
	v_lshl_add_u64 v[166:167], s[50:51], 0, v[144:145]
	v_lshl_add_u64 v[166:167], v[166:167], 0, s[6:7]
	v_mov_b32_e32 v144, v170
	global_load_lds_dwordx4 v[166:167], off
	s_mov_b32 m0, s93
	v_lshl_add_u64 v[166:167], s[50:51], 0, v[144:145]
	v_lshl_add_u64 v[166:167], v[166:167], 0, s[6:7]
	global_load_lds_dwordx4 v[166:167], off
	s_waitcnt vmcnt(8)
	s_waitcnt lgkmcnt(0)
	s_barrier
	s_setprio 1
	s_waitcnt lgkmcnt(0)
	v_mfma_f32_16x16x32_bf16 v[60:63], v[128:131], v[182:185], v[60:63]
	v_mfma_f32_16x16x32_bf16 v[56:59], v[136:139], v[182:185], v[56:59]
	v_mfma_f32_16x16x32_bf16 v[40:43], v[136:139], v[190:193], v[40:43]
	v_mfma_f32_16x16x32_bf16 v[44:47], v[128:131], v[190:193], v[44:47]
	v_mfma_f32_16x16x32_bf16 v[28:31], v[128:131], v[198:201], v[28:31]
	v_mfma_f32_16x16x32_bf16 v[24:27], v[136:139], v[198:201], v[24:27]
	v_mfma_f32_16x16x32_bf16 v[8:11], v[136:139], v[206:209], v[8:11]
	v_mfma_f32_16x16x32_bf16 v[12:15], v[128:131], v[206:209], v[12:15]
	s_setprio 0
	s_setprio 1
	v_mfma_f32_16x16x32_bf16 v[60:63], v[132:135], v[186:189], v[60:63]
	v_mfma_f32_16x16x32_bf16 v[56:59], v[140:143], v[186:189], v[56:59]
	v_mfma_f32_16x16x32_bf16 v[40:43], v[140:143], v[194:197], v[40:43]
	v_mfma_f32_16x16x32_bf16 v[44:47], v[132:135], v[194:197], v[44:47]
	v_mfma_f32_16x16x32_bf16 v[28:31], v[132:135], v[202:205], v[28:31]
	v_mfma_f32_16x16x32_bf16 v[24:27], v[140:143], v[202:205], v[24:27]
	v_mfma_f32_16x16x32_bf16 v[8:11], v[140:143], v[210:213], v[8:11]
	v_mfma_f32_16x16x32_bf16 v[12:15], v[132:135], v[210:213], v[12:15]
	s_setprio 0
	s_setprio 1
	v_mfma_f32_16x16x32_bf16 v[52:55], v[150:153], v[182:185], v[52:55]
	v_mfma_f32_16x16x32_bf16 v[48:51], v[158:161], v[182:185], v[48:51]
	v_mfma_f32_16x16x32_bf16 v[32:35], v[158:161], v[190:193], v[32:35]
	v_mfma_f32_16x16x32_bf16 v[36:39], v[150:153], v[190:193], v[36:39]
	v_mfma_f32_16x16x32_bf16 v[20:23], v[150:153], v[198:201], v[20:23]
	v_mfma_f32_16x16x32_bf16 v[16:19], v[158:161], v[198:201], v[16:19]
	v_mfma_f32_16x16x32_bf16 v[0:3], v[158:161], v[206:209], v[0:3]
	v_mfma_f32_16x16x32_bf16 v[4:7], v[150:153], v[206:209], v[4:7]
	s_setprio 0
	s_setprio 1
	v_mfma_f32_16x16x32_bf16 v[52:55], v[154:157], v[186:189], v[52:55]
	v_mfma_f32_16x16x32_bf16 v[48:51], v[162:165], v[186:189], v[48:51]
	v_mfma_f32_16x16x32_bf16 v[32:35], v[162:165], v[194:197], v[32:35]
	v_mfma_f32_16x16x32_bf16 v[36:39], v[154:157], v[194:197], v[36:39]
	v_mfma_f32_16x16x32_bf16 v[20:23], v[154:157], v[202:205], v[20:23]
	v_mfma_f32_16x16x32_bf16 v[16:19], v[162:165], v[202:205], v[16:19]
	v_mfma_f32_16x16x32_bf16 v[0:3], v[162:165], v[210:213], v[0:3]
	v_mfma_f32_16x16x32_bf16 v[4:7], v[154:157], v[210:213], v[4:7]
	s_setprio 0
	s_barrier
	s_add_u32 s48, s48, 0x100
	s_addc_u32 s49, s49, 0
	s_add_u32 s30, s30, 0x100
	s_addc_u32 s31, s31, 0
	s_cmp_ge_i32 s35, s20
	s_mov_b32 s34, s35
	s_cbranch_scc1 .Lpeel_exit_lbb0_899
.LBB0_899:
	ds_read_b128 v[128:131], v173
	ds_read_b128 v[132:135], v173 offset:1024
	ds_read_b128 v[136:139], v174
	ds_read_b128 v[140:143], v174 offset:1024
	ds_read_b128 v[150:153], v175
	ds_read_b128 v[154:157], v175 offset:1024
	ds_read_b128 v[158:161], v176
	ds_read_b128 v[162:165], v176 offset:1024
	s_add_i32 s35, s34, 2
	s_add_u32 s16, s48, 0xfffc0080
	s_addc_u32 s17, s49, -1
	s_cmp_eq_u32 s27, s34
	s_cselect_b32 s51, s15, s17
	s_cselect_b32 s50, s21, s16
	s_cselect_b32 s53, s24, s31
	s_cselect_b32 s52, s25, s30
	v_mov_b32_e32 v144, v168
	ds_read_b128 v[182:185], v177
	ds_read_b128 v[186:189], v177 offset:1024
	ds_read_b128 v[190:193], v177 offset:2048
	ds_read_b128 v[194:197], v177 offset:3072
	ds_read_b128 v[198:201], v177 offset:4096
	ds_read_b128 v[202:205], v177 offset:5120
	ds_read_b128 v[206:209], v177 offset:6144
	ds_read_b128 v[210:213], v177 offset:7168
	s_add_i32 m0, s87, 0xc000
	s_nop 0
	global_load_lds_dwordx4 v144, s[48:49]
	v_mov_b32_e32 v144, v170
	s_add_i32 m0, s87, 0xe000
	s_nop 0
	global_load_lds_dwordx4 v144, s[48:49]
	s_waitcnt vmcnt(8)
	s_waitcnt lgkmcnt(0)
	s_barrier
; #define PG8_LDA(dst, b, h) do { if constexpr (FP8) { _Pragma("unroll") for (int m = 0; m < 4; ++m) dst##8[m] = PG8_LD8(PG8_SA(b, h), aoff, aoff1, m); } \
;         else { _Pragma("unroll") for (int m = 0; m < 4; ++m) _Pragma("unroll") for (int k = 0; k < 2; ++k) dst[m][k] = *(const LAS bf16x8*)(lds + PG8_SA(b, h) + (k ? aoff1 : aoff) + m * 2048); } } while (0)
; #define PG8_LDB(dst, b, h) do { if constexpr (FP8) { dst##8[0] = PG8_LD8(PG8_SB(b, h), boff, boff1, 0); dst##8[1] = PG8_LD8(PG8_SB(b, h), boff, boff1, 1); } \
;         else { _Pragma("unroll") for (int n = 0; n < 2; ++n) _Pragma("unroll") for (int k = 0; k < 2; ++k) dst[n][k] = *(const LAS bf16x8*)(lds + PG8_SB(b, h) + (k ? boff1 : boff) + n * 2048); } } while (0)
; #define PG8_WAIT_V(n) asm volatile("s_waitcnt vmcnt(" #n ")" ::: "memory")
; #define PG8_WAIT_L(n) asm volatile("s_waitcnt lgkmcnt(" #n ")" ::: "memory")
; #define PG8_BAR __builtin_amdgcn_s_barrier()
; #define PG8_SCHED __builtin_amdgcn_sched_barrier(0)
; #define PG8_S2 do { PG8_STAGE(PG8_SB(0, 0), b2, voffB); PG8_STAGE(PG8_SB(0, 1), b2 + hstepB, voffB); PG8_STAGE(PG8_SA(0, 0), a2, voffA); } while (0)
; #define PG8_S3 PG8_STAGE(PG8_SA(0, 1), a2 + hstepA, voffA)
; template <class Epi, class SchedT, bool ALIGN_EPI, bool SP2, bool FP8 = false>
; __device__ __forceinline__ void gemm_phase(LAS unsigned char* lds, const Gemm g, const SchedT& S, const Epi& E, const int wid) {
;     ...
;             PG8_WAIT_V(8); PG8_WAIT_L(0); PG8_BAR; PG8_MMAP(0, 0, 0); PG8_BAR; PG8_SCHED;
;             PG8_LDA(At, 0, 1); PG8_S2;
;             PG8_WAIT_V(8); PG8_WAIT_L(0); PG8_BAR; PG8_MMAP(1, 0, 1); PG8_BAR; PG8_SCHED;
;             PG8_LDB(B0, 1, 0); PG8_LDB(B1, 1, 1); PG8_SCHED; PG8_LDA(At, 1, 0); PG8_S3;
;             PG8_WAIT_V(8); PG8_WAIT_L(0); PG8_BAR; PG8_MMAP(0, 1, 0); PG8_BAR; PG8_SCHED;
	s_setprio 1
	s_waitcnt lgkmcnt(0)
	v_mfma_f32_16x16x32_bf16 v[124:127], v[128:131], v[182:185], v[124:127]
	v_mfma_f32_16x16x32_bf16 v[120:123], v[136:139], v[182:185], v[120:123]
	v_mfma_f32_16x16x32_bf16 v[104:107], v[136:139], v[190:193], v[104:107]
	v_mfma_f32_16x16x32_bf16 v[108:111], v[128:131], v[190:193], v[108:111]
	v_mfma_f32_16x16x32_bf16 v[92:95], v[128:131], v[198:201], v[92:95]
	v_mfma_f32_16x16x32_bf16 v[88:91], v[136:139], v[198:201], v[88:91]
	v_mfma_f32_16x16x32_bf16 v[72:75], v[136:139], v[206:209], v[72:75]
	v_mfma_f32_16x16x32_bf16 v[76:79], v[128:131], v[206:209], v[76:79]
	s_setprio 0
	s_setprio 1
	v_mfma_f32_16x16x32_bf16 v[124:127], v[132:135], v[186:189], v[124:127]
	v_mfma_f32_16x16x32_bf16 v[120:123], v[140:143], v[186:189], v[120:123]
	v_mfma_f32_16x16x32_bf16 v[104:107], v[140:143], v[194:197], v[104:107]
	v_mfma_f32_16x16x32_bf16 v[108:111], v[132:135], v[194:197], v[108:111]
	v_mfma_f32_16x16x32_bf16 v[92:95], v[132:135], v[202:205], v[92:95]
	v_mfma_f32_16x16x32_bf16 v[88:91], v[140:143], v[202:205], v[88:91]
	v_mfma_f32_16x16x32_bf16 v[72:75], v[140:143], v[210:213], v[72:75]
	v_mfma_f32_16x16x32_bf16 v[76:79], v[132:135], v[210:213], v[76:79]
	s_setprio 0
	s_setprio 1
	v_mfma_f32_16x16x32_bf16 v[116:119], v[150:153], v[182:185], v[116:119]
	v_mfma_f32_16x16x32_bf16 v[112:115], v[158:161], v[182:185], v[112:115]
	v_mfma_f32_16x16x32_bf16 v[96:99], v[158:161], v[190:193], v[96:99]
	v_mfma_f32_16x16x32_bf16 v[100:103], v[150:153], v[190:193], v[100:103]
	v_mfma_f32_16x16x32_bf16 v[84:87], v[150:153], v[198:201], v[84:87]
	v_mfma_f32_16x16x32_bf16 v[80:83], v[158:161], v[198:201], v[80:83]
	v_mfma_f32_16x16x32_bf16 v[64:67], v[158:161], v[206:209], v[64:67]
	v_mfma_f32_16x16x32_bf16 v[68:71], v[150:153], v[206:209], v[68:71]
	s_setprio 0
	s_setprio 1
	v_mfma_f32_16x16x32_bf16 v[116:119], v[154:157], v[186:189], v[116:119]
	v_mfma_f32_16x16x32_bf16 v[112:115], v[162:165], v[186:189], v[112:115]
	v_mfma_f32_16x16x32_bf16 v[96:99], v[162:165], v[194:197], v[96:99]
	v_mfma_f32_16x16x32_bf16 v[100:103], v[154:157], v[194:197], v[100:103]
	v_mfma_f32_16x16x32_bf16 v[84:87], v[154:157], v[202:205], v[84:87]
	v_mfma_f32_16x16x32_bf16 v[80:83], v[162:165], v[202:205], v[80:83]
	v_mfma_f32_16x16x32_bf16 v[64:67], v[162:165], v[210:213], v[64:67]
	v_mfma_f32_16x16x32_bf16 v[68:71], v[154:157], v[210:213], v[68:71]
	s_setprio 0
	s_barrier
	v_mov_b32_e32 v144, v169
	s_add_i32 s16, s94, s86
	ds_read_b128 v[182:185], v177 offset:16384
	ds_read_b128 v[186:189], v177 offset:17408
	ds_read_b128 v[190:193], v177 offset:18432
	ds_read_b128 v[194:197], v177 offset:19456
	ds_read_b128 v[198:201], v177 offset:20480
	ds_read_b128 v[202:205], v177 offset:21504
	ds_read_b128 v[206:209], v177 offset:22528
	ds_read_b128 v[210:213], v177 offset:23552
	s_mov_b32 m0, s16
	s_nop 0
	global_load_lds_dwordx4 v144, s[52:53]
	v_mov_b32_e32 v144, v171
	s_add_i32 m0, s16, 0x2000
	s_add_u32 s60, s52, 0x40000
	global_load_lds_dwordx4 v144, s[52:53]
	s_addc_u32 s61, s53, 0
	v_mov_b32_e32 v144, v169
	s_add_i32 s16, s95, s86
	s_mov_b32 m0, s16
	s_nop 0
	global_load_lds_dwordx4 v144, s[60:61]
	v_mov_b32_e32 v144, v171
	s_add_i32 m0, s16, 0x2000
	s_nop 0
	global_load_lds_dwordx4 v144, s[60:61]
	v_mov_b32_e32 v144, v168
	s_mov_b32 m0, s87
	s_nop 0
	global_load_lds_dwordx4 v144, s[50:51]
	v_mov_b32_e32 v144, v170
	s_mov_b32 m0, s88
	s_nop 0
	global_load_lds_dwordx4 v144, s[50:51]
	s_waitcnt vmcnt(8)
	s_waitcnt lgkmcnt(0)
	s_barrier
	s_setprio 1
	s_waitcnt lgkmcnt(0)
	v_mfma_f32_16x16x32_bf16 v[60:63], v[128:131], v[182:185], v[60:63]
	v_mfma_f32_16x16x32_bf16 v[56:59], v[136:139], v[182:185], v[56:59]
	v_mfma_f32_16x16x32_bf16 v[40:43], v[136:139], v[190:193], v[40:43]
	v_mfma_f32_16x16x32_bf16 v[44:47], v[128:131], v[190:193], v[44:47]
	v_mfma_f32_16x16x32_bf16 v[28:31], v[128:131], v[198:201], v[28:31]
	v_mfma_f32_16x16x32_bf16 v[24:27], v[136:139], v[198:201], v[24:27]
	v_mfma_f32_16x16x32_bf16 v[8:11], v[136:139], v[206:209], v[8:11]
	v_mfma_f32_16x16x32_bf16 v[12:15], v[128:131], v[206:209], v[12:15]
	s_setprio 0
	s_setprio 1
	v_mfma_f32_16x16x32_bf16 v[60:63], v[132:135], v[186:189], v[60:63]
	v_mfma_f32_16x16x32_bf16 v[56:59], v[140:143], v[186:189], v[56:59]
	v_mfma_f32_16x16x32_bf16 v[40:43], v[140:143], v[194:197], v[40:43]
	v_mfma_f32_16x16x32_bf16 v[44:47], v[132:135], v[194:197], v[44:47]
	v_mfma_f32_16x16x32_bf16 v[28:31], v[132:135], v[202:205], v[28:31]
	v_mfma_f32_16x16x32_bf16 v[24:27], v[140:143], v[202:205], v[24:27]
	v_mfma_f32_16x16x32_bf16 v[8:11], v[140:143], v[210:213], v[8:11]
	v_mfma_f32_16x16x32_bf16 v[12:15], v[132:135], v[210:213], v[12:15]
	s_setprio 0
	s_setprio 1
	v_mfma_f32_16x16x32_bf16 v[52:55], v[150:153], v[182:185], v[52:55]
	v_mfma_f32_16x16x32_bf16 v[48:51], v[158:161], v[182:185], v[48:51]
	v_mfma_f32_16x16x32_bf16 v[32:35], v[158:161], v[190:193], v[32:35]
	v_mfma_f32_16x16x32_bf16 v[36:39], v[150:153], v[190:193], v[36:39]
	v_mfma_f32_16x16x32_bf16 v[20:23], v[150:153], v[198:201], v[20:23]
	v_mfma_f32_16x16x32_bf16 v[16:19], v[158:161], v[198:201], v[16:19]
	v_mfma_f32_16x16x32_bf16 v[0:3], v[158:161], v[206:209], v[0:3]
	v_mfma_f32_16x16x32_bf16 v[4:7], v[150:153], v[206:209], v[4:7]
	s_setprio 0
	s_setprio 1
	v_mfma_f32_16x16x32_bf16 v[52:55], v[154:157], v[186:189], v[52:55]
	v_mfma_f32_16x16x32_bf16 v[48:51], v[162:165], v[186:189], v[48:51]
	v_mfma_f32_16x16x32_bf16 v[32:35], v[162:165], v[194:197], v[32:35]
	v_mfma_f32_16x16x32_bf16 v[36:39], v[154:157], v[194:197], v[36:39]
	v_mfma_f32_16x16x32_bf16 v[20:23], v[154:157], v[202:205], v[20:23]
	v_mfma_f32_16x16x32_bf16 v[16:19], v[162:165], v[202:205], v[16:19]
	v_mfma_f32_16x16x32_bf16 v[0:3], v[162:165], v[210:213], v[0:3]
	v_mfma_f32_16x16x32_bf16 v[4:7], v[154:157], v[210:213], v[4:7]
	s_setprio 0
	s_barrier
; #define PG8_LDA(dst, b, h) do { if constexpr (FP8) { _Pragma("unroll") for (int m = 0; m < 4; ++m) dst##8[m] = PG8_LD8(PG8_SA(b, h), aoff, aoff1, m); } \
;         else { _Pragma("unroll") for (int m = 0; m < 4; ++m) _Pragma("unroll") for (int k = 0; k < 2; ++k) dst[m][k] = *(const LAS bf16x8*)(lds + PG8_SA(b, h) + (k ? aoff1 : aoff) + m * 2048); } } while (0)
; #define PG8_LDB(dst, b, h) do { if constexpr (FP8) { dst##8[0] = PG8_LD8(PG8_SB(b, h), boff, boff1, 0); dst##8[1] = PG8_LD8(PG8_SB(b, h), boff, boff1, 1); } \
;         else { _Pragma("unroll") for (int n = 0; n < 2; ++n) _Pragma("unroll") for (int k = 0; k < 2; ++k) dst[n][k] = *(const LAS bf16x8*)(lds + PG8_SB(b, h) + (k ? boff1 : boff) + n * 2048); } } while (0)
; #define PG8_WAIT_V(n) asm volatile("s_waitcnt vmcnt(" #n ")" ::: "memory")
; #define PG8_WAIT_L(n) asm volatile("s_waitcnt lgkmcnt(" #n ")" ::: "memory")
; #define PG8_BAR __builtin_amdgcn_s_barrier()
; #define PG8_SCHED __builtin_amdgcn_sched_barrier(0)
; #define PG8_S3 PG8_STAGE(PG8_SA(0, 1), a2 + hstepA, voffA)
; template <class Epi, class SchedT, bool ALIGN_EPI, bool SP2, bool FP8 = false>
; __device__ __forceinline__ void gemm_phase(LAS unsigned char* lds, const Gemm g, const SchedT& S, const Epi& E, const int wid) {
;     ...
;             PG8_LDB(B0, 1, 0); PG8_LDB(B1, 1, 1); PG8_SCHED; PG8_LDA(At, 1, 0); PG8_S3;
;             PG8_WAIT_V(8); PG8_WAIT_L(0); PG8_BAR; PG8_MMAP(0, 1, 0); PG8_BAR; PG8_SCHED;
	s_add_i32 s16, 0, 0x18000
	s_add_i32 s17, 0, 0x1c000
	v_add_u32_e32 v132, s16, v172
	v_add_u32_e32 v144, s17, v172
	ds_read_b128 v[128:131], v132
	ds_read_b128 v[132:135], v132 offset:1024
	ds_read_b128 v[136:139], v178
	ds_read_b128 v[140:143], v178 offset:1024
	ds_read_b128 v[150:153], v144
	ds_read_b128 v[154:157], v144 offset:1024
	ds_read_b128 v[158:161], v179
	ds_read_b128 v[162:165], v179 offset:1024
	s_add_u32 s60, s50, 0x40000
	v_mov_b32_e32 v144, v168
	s_mov_b32 m0, s89
	ds_read_b128 v[182:185], v177 offset:32768
	ds_read_b128 v[186:189], v177 offset:33792
	ds_read_b128 v[190:193], v177 offset:34816
	ds_read_b128 v[194:197], v177 offset:35840
	ds_read_b128 v[198:201], v177 offset:36864
	ds_read_b128 v[202:205], v177 offset:37888
	ds_read_b128 v[206:209], v177 offset:38912
	ds_read_b128 v[210:213], v177 offset:39936
	s_addc_u32 s61, s51, 0
	s_nop 0
	global_load_lds_dwordx4 v144, s[60:61]
	v_mov_b32_e32 v144, v170
	s_mov_b32 m0, s90
	s_nop 0
	global_load_lds_dwordx4 v144, s[60:61]
	s_waitcnt vmcnt(8)
	s_waitcnt lgkmcnt(0)
	s_barrier
	s_setprio 1
	s_waitcnt lgkmcnt(0)
	v_mfma_f32_16x16x32_bf16 v[124:127], v[128:131], v[182:185], v[124:127]
	v_mfma_f32_16x16x32_bf16 v[120:123], v[136:139], v[182:185], v[120:123]
	v_mfma_f32_16x16x32_bf16 v[104:107], v[136:139], v[190:193], v[104:107]
	v_mfma_f32_16x16x32_bf16 v[108:111], v[128:131], v[190:193], v[108:111]
	v_mfma_f32_16x16x32_bf16 v[92:95], v[128:131], v[198:201], v[92:95]
	v_mfma_f32_16x16x32_bf16 v[88:91], v[136:139], v[198:201], v[88:91]
	v_mfma_f32_16x16x32_bf16 v[72:75], v[136:139], v[206:209], v[72:75]
	v_mfma_f32_16x16x32_bf16 v[76:79], v[128:131], v[206:209], v[76:79]
	s_setprio 0
	s_setprio 1
	v_mfma_f32_16x16x32_bf16 v[124:127], v[132:135], v[186:189], v[124:127]
	v_mfma_f32_16x16x32_bf16 v[120:123], v[140:143], v[186:189], v[120:123]
	v_mfma_f32_16x16x32_bf16 v[104:107], v[140:143], v[194:197], v[104:107]
	v_mfma_f32_16x16x32_bf16 v[108:111], v[132:135], v[194:197], v[108:111]
	v_mfma_f32_16x16x32_bf16 v[92:95], v[132:135], v[202:205], v[92:95]
	v_mfma_f32_16x16x32_bf16 v[88:91], v[140:143], v[202:205], v[88:91]
	v_mfma_f32_16x16x32_bf16 v[72:75], v[140:143], v[210:213], v[72:75]
	v_mfma_f32_16x16x32_bf16 v[76:79], v[132:135], v[210:213], v[76:79]
	s_setprio 0
	s_setprio 1
	v_mfma_f32_16x16x32_bf16 v[116:119], v[150:153], v[182:185], v[116:119]
	v_mfma_f32_16x16x32_bf16 v[112:115], v[158:161], v[182:185], v[112:115]
	v_mfma_f32_16x16x32_bf16 v[96:99], v[158:161], v[190:193], v[96:99]
	v_mfma_f32_16x16x32_bf16 v[100:103], v[150:153], v[190:193], v[100:103]
	v_mfma_f32_16x16x32_bf16 v[84:87], v[150:153], v[198:201], v[84:87]
	v_mfma_f32_16x16x32_bf16 v[80:83], v[158:161], v[198:201], v[80:83]
	v_mfma_f32_16x16x32_bf16 v[64:67], v[158:161], v[206:209], v[64:67]
	v_mfma_f32_16x16x32_bf16 v[68:71], v[150:153], v[206:209], v[68:71]
	s_setprio 0
	s_setprio 1
	v_mfma_f32_16x16x32_bf16 v[116:119], v[154:157], v[186:189], v[116:119]
	v_mfma_f32_16x16x32_bf16 v[112:115], v[162:165], v[186:189], v[112:115]
	v_mfma_f32_16x16x32_bf16 v[96:99], v[162:165], v[194:197], v[96:99]
	v_mfma_f32_16x16x32_bf16 v[100:103], v[154:157], v[194:197], v[100:103]
	v_mfma_f32_16x16x32_bf16 v[84:87], v[154:157], v[202:205], v[84:87]
	v_mfma_f32_16x16x32_bf16 v[80:83], v[162:165], v[202:205], v[80:83]
	v_mfma_f32_16x16x32_bf16 v[64:67], v[162:165], v[210:213], v[64:67]
	v_mfma_f32_16x16x32_bf16 v[68:71], v[154:157], v[210:213], v[68:71]
	s_setprio 0
	s_barrier
; #define PG8_LDA(dst, b, h) do { if constexpr (FP8) { _Pragma("unroll") for (int m = 0; m < 4; ++m) dst##8[m] = PG8_LD8(PG8_SA(b, h), aoff, aoff1, m); } \
;         else { _Pragma("unroll") for (int m = 0; m < 4; ++m) _Pragma("unroll") for (int k = 0; k < 2; ++k) dst[m][k] = *(const LAS bf16x8*)(lds + PG8_SA(b, h) + (k ? aoff1 : aoff) + m * 2048); } } while (0)
; #define PG8_WAIT_V(n) asm volatile("s_waitcnt vmcnt(" #n ")" ::: "memory")
; #define PG8_WAIT_L(n) asm volatile("s_waitcnt lgkmcnt(" #n ")" ::: "memory")
; #define PG8_BAR __builtin_amdgcn_s_barrier()
; #define PG8_SCHED __builtin_amdgcn_sched_barrier(0)
; #define PG8_S4 do { PG8_STAGE(PG8_SB(1, 0), b3, voffB); PG8_STAGE(PG8_SB(1, 1), b3 + hstepB, voffB); PG8_STAGE(PG8_SA(1, 0), a3, voffA); } while (0)
; template <class Epi, class SchedT, bool ALIGN_EPI, bool SP2, bool FP8 = false>
; __device__ __forceinline__ void gemm_phase(LAS unsigned char* lds, const Gemm g, const SchedT& S, const Epi& E, const int wid) {
;     ...
;             PG8_LDA(At, 1, 1); PG8_S4;
;             PG8_WAIT_V(8); PG8_WAIT_L(0); PG8_BAR; PG8_MMAP(1, 1, 1); PG8_BAR; PG8_SCHED;
;     ...
;         if (!has_next) break;
	v_mov_b32_e32 v144, v169
	ds_read_b128 v[182:185], v177 offset:49152
	ds_read_b128 v[186:189], v177 offset:50176
	ds_read_b128 v[190:193], v177 offset:51200
	ds_read_b128 v[194:197], v177 offset:52224
	ds_read_b128 v[198:201], v177 offset:53248
	ds_read_b128 v[202:205], v177 offset:54272
	ds_read_b128 v[206:209], v177 offset:55296
	ds_read_b128 v[210:213], v177 offset:56320
	s_add_i32 s16, s16, s86
	v_lshl_add_u64 v[166:167], s[52:53], 0, v[144:145]
	v_lshl_add_u64 v[166:167], v[166:167], 0, s[6:7]
	s_mov_b32 m0, s16
	v_mov_b32_e32 v144, v171
	global_load_lds_dwordx4 v[166:167], off
	s_add_i32 m0, s16, 0x2000
	s_nop 0
	v_lshl_add_u64 v[166:167], s[52:53], 0, v[144:145]
	s_add_u32 s52, s52, 0x40080
	v_lshl_add_u64 v[166:167], v[166:167], 0, s[6:7]
	s_addc_u32 s53, s53, 0
	v_mov_b32_e32 v144, v169
	s_add_i32 s16, s17, s86
	global_load_lds_dwordx4 v[166:167], off
	s_mov_b32 m0, s16
	s_nop 0
	global_load_lds_dwordx4 v144, s[52:53]
	v_mov_b32_e32 v144, v171
	s_add_i32 m0, s16, 0x2000
	s_nop 0
	global_load_lds_dwordx4 v144, s[52:53]
	v_mov_b32_e32 v144, v168
	s_mov_b32 m0, s92
	v_lshl_add_u64 v[166:167], s[50:51], 0, v[144:145]
	v_lshl_add_u64 v[166:167], v[166:167], 0, s[6:7]
	v_mov_b32_e32 v144, v170
	global_load_lds_dwordx4 v[166:167], off
	s_mov_b32 m0, s93
	v_lshl_add_u64 v[166:167], s[50:51], 0, v[144:145]
	v_lshl_add_u64 v[166:167], v[166:167], 0, s[6:7]
	global_load_lds_dwordx4 v[166:167], off
	s_waitcnt vmcnt(8)
	s_waitcnt lgkmcnt(0)
	s_barrier
	s_setprio 1
	s_waitcnt lgkmcnt(0)
	v_mfma_f32_16x16x32_bf16 v[60:63], v[128:131], v[182:185], v[60:63]
	v_mfma_f32_16x16x32_bf16 v[56:59], v[136:139], v[182:185], v[56:59]
	v_mfma_f32_16x16x32_bf16 v[40:43], v[136:139], v[190:193], v[40:43]
	v_mfma_f32_16x16x32_bf16 v[44:47], v[128:131], v[190:193], v[44:47]
	v_mfma_f32_16x16x32_bf16 v[28:31], v[128:131], v[198:201], v[28:31]
	v_mfma_f32_16x16x32_bf16 v[24:27], v[136:139], v[198:201], v[24:27]
	v_mfma_f32_16x16x32_bf16 v[8:11], v[136:139], v[206:209], v[8:11]
	v_mfma_f32_16x16x32_bf16 v[12:15], v[128:131], v[206:209], v[12:15]
	s_setprio 0
	s_setprio 1
	v_mfma_f32_16x16x32_bf16 v[60:63], v[132:135], v[186:189], v[60:63]
	v_mfma_f32_16x16x32_bf16 v[56:59], v[140:143], v[186:189], v[56:59]
	v_mfma_f32_16x16x32_bf16 v[40:43], v[140:143], v[194:197], v[40:43]
	v_mfma_f32_16x16x32_bf16 v[44:47], v[132:135], v[194:197], v[44:47]
	v_mfma_f32_16x16x32_bf16 v[28:31], v[132:135], v[202:205], v[28:31]
	v_mfma_f32_16x16x32_bf16 v[24:27], v[140:143], v[202:205], v[24:27]
	v_mfma_f32_16x16x32_bf16 v[8:11], v[140:143], v[210:213], v[8:11]
	v_mfma_f32_16x16x32_bf16 v[12:15], v[132:135], v[210:213], v[12:15]
	s_setprio 0
	s_setprio 1
	v_mfma_f32_16x16x32_bf16 v[52:55], v[150:153], v[182:185], v[52:55]
	v_mfma_f32_16x16x32_bf16 v[48:51], v[158:161], v[182:185], v[48:51]
	v_mfma_f32_16x16x32_bf16 v[32:35], v[158:161], v[190:193], v[32:35]
	v_mfma_f32_16x16x32_bf16 v[36:39], v[150:153], v[190:193], v[36:39]
	v_mfma_f32_16x16x32_bf16 v[20:23], v[150:153], v[198:201], v[20:23]
	v_mfma_f32_16x16x32_bf16 v[16:19], v[158:161], v[198:201], v[16:19]
	v_mfma_f32_16x16x32_bf16 v[0:3], v[158:161], v[206:209], v[0:3]
	v_mfma_f32_16x16x32_bf16 v[4:7], v[150:153], v[206:209], v[4:7]
	s_setprio 0
	s_setprio 1
	v_mfma_f32_16x16x32_bf16 v[52:55], v[154:157], v[186:189], v[52:55]
	v_mfma_f32_16x16x32_bf16 v[48:51], v[162:165], v[186:189], v[48:51]
	v_mfma_f32_16x16x32_bf16 v[32:35], v[162:165], v[194:197], v[32:35]
	v_mfma_f32_16x16x32_bf16 v[36:39], v[154:157], v[194:197], v[36:39]
	v_mfma_f32_16x16x32_bf16 v[20:23], v[154:157], v[202:205], v[20:23]
	v_mfma_f32_16x16x32_bf16 v[16:19], v[162:165], v[202:205], v[16:19]
	v_mfma_f32_16x16x32_bf16 v[0:3], v[162:165], v[210:213], v[0:3]
	v_mfma_f32_16x16x32_bf16 v[4:7], v[154:157], v[210:213], v[4:7]
	s_setprio 0
	s_barrier
	s_add_u32 s48, s48, 0x100
	s_addc_u32 s49, s49, 0
	s_add_u32 s30, s30, 0x100
	s_addc_u32 s31, s31, 0
	s_cmp_ge_i32 s35, s20
	s_mov_b32 s34, s35
	s_cbranch_scc0 .LBB0_899
.Lpeel_exit_lbb0_899:
	s_branch .LBB0_894

; #define PG8_LDA(dst, b, h) do { if constexpr (FP8) { _Pragma("unroll") for (int m = 0; m < 4; ++m) dst##8[m] = PG8_LD8(PG8_SA(b, h), aoff, aoff1, m); } \
;         else { _Pragma("unroll") for (int m = 0; m < 4; ++m) _Pragma("unroll") for (int k = 0; k < 2; ++k) dst[m][k] = *(const LAS bf16x8*)(lds + PG8_SA(b, h) + (k ? aoff1 : aoff) + m * 2048); } } while (0)
; #define PG8_LDB(dst, b, h) do { if constexpr (FP8) { dst##8[0] = PG8_LD8(PG8_SB(b, h), boff, boff1, 0); dst##8[1] = PG8_LD8(PG8_SB(b, h), boff, boff1, 1); } \
;         else { _Pragma("unroll") for (int n = 0; n < 2; ++n) _Pragma("unroll") for (int k = 0; k < 2; ++k) dst[n][k] = *(const LAS bf16x8*)(lds + PG8_SB(b, h) + (k ? boff1 : boff) + n * 2048); } } while (0)
; #define PG8_WAIT_V(n) asm volatile("s_waitcnt vmcnt(" #n ")" ::: "memory")
; #define PG8_WAIT_L(n) asm volatile("s_waitcnt lgkmcnt(" #n ")" ::: "memory")
; #define PG8_BAR __builtin_amdgcn_s_barrier()
; #define PG8_SCHED __builtin_amdgcn_sched_barrier(0)
; #define PG8_S1 PG8_STAGE(PG8_SA(1, 1), a1 + hstepA, voffA)
; template <class Epi, class SchedT, bool ALIGN_EPI, bool SP2, bool FP8 = false>
; __device__ __forceinline__ void gemm_phase(LAS unsigned char* lds, const Gemm g, const SchedT& S, const Epi& E, const int wid) {
;     ...
;         const bool has_next = S.next(ui + 1, nxt);
;         const char* nA = has_next ? (const char*)g.A + (size_t)nxt.pm * tstepA + (size_t)nxt.aoff * 2 : cA; const char* nB = has_next ? (const char*)g.Bt + (size_t)nxt.pn * tstepB + (size_t)nxt.boff * 2 : cB;
;         const int nt = cur.nt;
;         for (int t = 0; t < nt; t += 2) {
;             const bool last = (t == nt - 2);
;             const char* a1 = cA + (size_t)(t + 1) * kstep;
;             const char* a2 = last ? nA : cA + (size_t)(t + 2) * kstep; const char* b2 = last ? nB : cB + (size_t)(t + 2) * kstep;
;             const char* a3 = a2 + kstep; const char* b3 = b2 + kstep;
;             if constexpr (SP2) {
;     ...
;             PG8_LDB(B0, 0, 0); PG8_LDB(B1, 0, 1); PG8_SCHED; PG8_LDA(At, 0, 0); PG8_S1;
;             PG8_WAIT_V(8); PG8_WAIT_L(0); PG8_BAR; PG8_MMAP(0, 0, 0); PG8_BAR; PG8_SCHED;
;             PG8_LDA(At, 0, 1); PG8_S2;
;             PG8_WAIT_V(8); PG8_WAIT_L(0); PG8_BAR; PG8_MMAP(1, 0, 1); PG8_BAR; PG8_SCHED;
.LBB0_968:
	s_ashr_i32 s15, s14, 31
	s_lshl_b64 s[20:21], s[14:15], 21
	s_add_u32 s20, s36, s20
	s_addc_u32 s21, s37, s21
	s_ashr_i32 s13, s12, 31
	s_lshl_b64 s[22:23], s[12:13], 21
	s_add_u32 s22, s52, s22
	s_addc_u32 s23, s53, s23
	s_cmp_lt_i32 s30, 1
	s_cbranch_scc1 .LBB0_997
	s_and_b64 s[38:39], s[4:5], exec
	s_cselect_b32 s13, s21, s25
	s_cselect_b32 s15, s20, s24
	s_cselect_b32 s27, s23, s35
	s_cselect_b32 s31, s22, s34
	s_add_i32 s45, s30, -2
	s_add_u32 s24, s24, 0x100080
	s_addc_u32 s25, s25, 0
	s_add_u32 s46, s34, 0x100
	s_addc_u32 s47, s35, 0
	s_mov_b32 s34, 0
	ds_read_b128 v[134:137], v175
	ds_read_b128 v[138:141], v175 offset:1024
	ds_read_b128 v[142:145], v176
	ds_read_b128 v[146:149], v176 offset:1024
	ds_read_b128 v[150:153], v177
	ds_read_b128 v[154:157], v177 offset:1024
	ds_read_b128 v[158:161], v178
	ds_read_b128 v[162:165], v178 offset:1024
	s_add_i32 s48, s34, 2
	s_add_u32 s16, s24, 0xfff00080
	s_addc_u32 s17, s25, -1
	s_cmp_eq_u32 s45, s34
	s_cselect_b32 s34, s15, s16
	s_cselect_b32 s35, s13, s17
	s_cselect_b32 s39, s27, s47
	s_cselect_b32 s38, s31, s46
	v_mov_b32_e32 v128, v172
	ds_read_b128 v[166:169], v179
	ds_read_b128 v[184:187], v179 offset:1024
	ds_read_b128 v[188:191], v179 offset:2048
	ds_read_b128 v[192:195], v179 offset:3072
	ds_read_b128 v[196:199], v179 offset:4096
	ds_read_b128 v[200:203], v179 offset:5120
	ds_read_b128 v[204:207], v179 offset:6144
	ds_read_b128 v[208:211], v179 offset:7168
	s_add_i32 m0, s87, 0xc000
	s_nop 0
	global_load_lds_dwordx4 v128, s[24:25]
	v_mov_b32_e32 v128, v173
	s_add_i32 m0, s87, 0xe000
	s_nop 0
	global_load_lds_dwordx4 v128, s[24:25]
	s_waitcnt vmcnt(8)
	s_waitcnt lgkmcnt(0)
	s_barrier
	s_setprio 1
	s_waitcnt lgkmcnt(0)
	v_mfma_f32_16x16x32_bf16 v[124:127], v[134:137], v[166:169], 0
	v_mfma_f32_16x16x32_bf16 v[120:123], v[142:145], v[166:169], 0
	v_mfma_f32_16x16x32_bf16 v[104:107], v[142:145], v[188:191], 0
	v_mfma_f32_16x16x32_bf16 v[108:111], v[134:137], v[188:191], 0
	v_mfma_f32_16x16x32_bf16 v[92:95], v[134:137], v[196:199], 0
	v_mfma_f32_16x16x32_bf16 v[88:91], v[142:145], v[196:199], 0
	v_mfma_f32_16x16x32_bf16 v[72:75], v[142:145], v[204:207], 0
	v_mfma_f32_16x16x32_bf16 v[76:79], v[134:137], v[204:207], 0
	s_setprio 0
	s_setprio 1
	v_mfma_f32_16x16x32_bf16 v[124:127], v[138:141], v[184:187], v[124:127]
	v_mfma_f32_16x16x32_bf16 v[120:123], v[146:149], v[184:187], v[120:123]
	v_mfma_f32_16x16x32_bf16 v[104:107], v[146:149], v[192:195], v[104:107]
	v_mfma_f32_16x16x32_bf16 v[108:111], v[138:141], v[192:195], v[108:111]
	v_mfma_f32_16x16x32_bf16 v[92:95], v[138:141], v[200:203], v[92:95]
	v_mfma_f32_16x16x32_bf16 v[88:91], v[146:149], v[200:203], v[88:91]
	v_mfma_f32_16x16x32_bf16 v[72:75], v[146:149], v[208:211], v[72:75]
	v_mfma_f32_16x16x32_bf16 v[76:79], v[138:141], v[208:211], v[76:79]
	s_setprio 0
	s_setprio 1
	v_mfma_f32_16x16x32_bf16 v[116:119], v[150:153], v[166:169], 0
	v_mfma_f32_16x16x32_bf16 v[112:115], v[158:161], v[166:169], 0
	v_mfma_f32_16x16x32_bf16 v[96:99], v[158:161], v[188:191], 0
	v_mfma_f32_16x16x32_bf16 v[100:103], v[150:153], v[188:191], 0
	v_mfma_f32_16x16x32_bf16 v[84:87], v[150:153], v[196:199], 0
	v_mfma_f32_16x16x32_bf16 v[80:83], v[158:161], v[196:199], 0
	v_mfma_f32_16x16x32_bf16 v[64:67], v[158:161], v[204:207], 0
	v_mfma_f32_16x16x32_bf16 v[68:71], v[150:153], v[204:207], 0
	s_setprio 0
	s_setprio 1
	v_mfma_f32_16x16x32_bf16 v[116:119], v[154:157], v[184:187], v[116:119]
	v_mfma_f32_16x16x32_bf16 v[112:115], v[162:165], v[184:187], v[112:115]
	v_mfma_f32_16x16x32_bf16 v[96:99], v[162:165], v[192:195], v[96:99]
	v_mfma_f32_16x16x32_bf16 v[100:103], v[154:157], v[192:195], v[100:103]
	v_mfma_f32_16x16x32_bf16 v[84:87], v[154:157], v[200:203], v[84:87]
	v_mfma_f32_16x16x32_bf16 v[80:83], v[162:165], v[200:203], v[80:83]
	v_mfma_f32_16x16x32_bf16 v[64:67], v[162:165], v[208:211], v[64:67]
	v_mfma_f32_16x16x32_bf16 v[68:71], v[154:157], v[208:211], v[68:71]
	s_setprio 0
	s_barrier
	v_mov_b32_e32 v128, v172
	s_add_i32 s16, s94, s86
	ds_read_b128 v[166:169], v179 offset:16384
	ds_read_b128 v[184:187], v179 offset:17408
	ds_read_b128 v[188:191], v179 offset:18432
	ds_read_b128 v[192:195], v179 offset:19456
	ds_read_b128 v[196:199], v179 offset:20480
	ds_read_b128 v[200:203], v179 offset:21504
	ds_read_b128 v[204:207], v179 offset:22528
	ds_read_b128 v[208:211], v179 offset:23552
	s_mov_b32 m0, s16
	s_nop 0
	global_load_lds_dwordx4 v128, s[38:39]
	v_mov_b32_e32 v128, v173
	s_add_i32 m0, s16, 0x2000
	s_add_u32 s50, s38, 0x100000
	global_load_lds_dwordx4 v128, s[38:39]
	s_addc_u32 s51, s39, 0
	v_mov_b32_e32 v128, v172
	s_add_i32 s16, s95, s86
	s_mov_b32 m0, s16
	s_nop 0
	global_load_lds_dwordx4 v128, s[50:51]
	v_mov_b32_e32 v128, v173
	s_add_i32 m0, s16, 0x2000
	s_nop 0
	global_load_lds_dwordx4 v128, s[50:51]
	v_mov_b32_e32 v128, v172
	s_mov_b32 m0, s87
	s_nop 0
	global_load_lds_dwordx4 v128, s[34:35]
	v_mov_b32_e32 v128, v173
	s_mov_b32 m0, s88
	s_nop 0
	global_load_lds_dwordx4 v128, s[34:35]
	s_waitcnt vmcnt(8)
	s_waitcnt lgkmcnt(0)
	s_barrier
; #define PG8_LDA(dst, b, h) do { if constexpr (FP8) { _Pragma("unroll") for (int m = 0; m < 4; ++m) dst##8[m] = PG8_LD8(PG8_SA(b, h), aoff, aoff1, m); } \
;         else { _Pragma("unroll") for (int m = 0; m < 4; ++m) _Pragma("unroll") for (int k = 0; k < 2; ++k) dst[m][k] = *(const LAS bf16x8*)(lds + PG8_SA(b, h) + (k ? aoff1 : aoff) + m * 2048); } } while (0)
; #define PG8_LDB(dst, b, h) do { if constexpr (FP8) { dst##8[0] = PG8_LD8(PG8_SB(b, h), boff, boff1, 0); dst##8[1] = PG8_LD8(PG8_SB(b, h), boff, boff1, 1); } \
;         else { _Pragma("unroll") for (int n = 0; n < 2; ++n) _Pragma("unroll") for (int k = 0; k < 2; ++k) dst[n][k] = *(const LAS bf16x8*)(lds + PG8_SB(b, h) + (k ? boff1 : boff) + n * 2048); } } while (0)
; #define PG8_WAIT_V(n) asm volatile("s_waitcnt vmcnt(" #n ")" ::: "memory")
; #define PG8_WAIT_L(n) asm volatile("s_waitcnt lgkmcnt(" #n ")" ::: "memory")
; #define PG8_BAR __builtin_amdgcn_s_barrier()
; #define PG8_SCHED __builtin_amdgcn_sched_barrier(0)
; #define PG8_S2 do { PG8_STAGE(PG8_SB(0, 0), b2, voffB); PG8_STAGE(PG8_SB(0, 1), b2 + hstepB, voffB); PG8_STAGE(PG8_SA(0, 0), a2, voffA); } while (0)
; #define PG8_S3 PG8_STAGE(PG8_SA(0, 1), a2 + hstepA, voffA)
; template <class Epi, class SchedT, bool ALIGN_EPI, bool SP2, bool FP8 = false>
; __device__ __forceinline__ void gemm_phase(LAS unsigned char* lds, const Gemm g, const SchedT& S, const Epi& E, const int wid) {
;     ...
;             PG8_LDA(At, 0, 1); PG8_S2;
;             PG8_WAIT_V(8); PG8_WAIT_L(0); PG8_BAR; PG8_MMAP(1, 0, 1); PG8_BAR; PG8_SCHED;
;             PG8_LDB(B0, 1, 0); PG8_LDB(B1, 1, 1); PG8_SCHED; PG8_LDA(At, 1, 0); PG8_S3;
;             PG8_WAIT_V(8); PG8_WAIT_L(0); PG8_BAR; PG8_MMAP(0, 1, 0); PG8_BAR; PG8_SCHED;
	s_setprio 1
	s_waitcnt lgkmcnt(0)
	v_mfma_f32_16x16x32_bf16 v[60:63], v[134:137], v[166:169], 0
	v_mfma_f32_16x16x32_bf16 v[56:59], v[142:145], v[166:169], 0
	v_mfma_f32_16x16x32_bf16 v[40:43], v[142:145], v[188:191], 0
	v_mfma_f32_16x16x32_bf16 v[44:47], v[134:137], v[188:191], 0
	v_mfma_f32_16x16x32_bf16 v[28:31], v[134:137], v[196:199], 0
	v_mfma_f32_16x16x32_bf16 v[24:27], v[142:145], v[196:199], 0
	v_mfma_f32_16x16x32_bf16 v[8:11], v[142:145], v[204:207], 0
	v_mfma_f32_16x16x32_bf16 v[12:15], v[134:137], v[204:207], 0
	s_setprio 0
	s_setprio 1
	v_mfma_f32_16x16x32_bf16 v[60:63], v[138:141], v[184:187], v[60:63]
	v_mfma_f32_16x16x32_bf16 v[56:59], v[146:149], v[184:187], v[56:59]
	v_mfma_f32_16x16x32_bf16 v[40:43], v[146:149], v[192:195], v[40:43]
	v_mfma_f32_16x16x32_bf16 v[44:47], v[138:141], v[192:195], v[44:47]
	v_mfma_f32_16x16x32_bf16 v[28:31], v[138:141], v[200:203], v[28:31]
	v_mfma_f32_16x16x32_bf16 v[24:27], v[146:149], v[200:203], v[24:27]
	v_mfma_f32_16x16x32_bf16 v[8:11], v[146:149], v[208:211], v[8:11]
	v_mfma_f32_16x16x32_bf16 v[12:15], v[138:141], v[208:211], v[12:15]
	s_setprio 0
	s_setprio 1
	v_mfma_f32_16x16x32_bf16 v[52:55], v[150:153], v[166:169], 0
	v_mfma_f32_16x16x32_bf16 v[48:51], v[158:161], v[166:169], 0
	v_mfma_f32_16x16x32_bf16 v[32:35], v[158:161], v[188:191], 0
	v_mfma_f32_16x16x32_bf16 v[36:39], v[150:153], v[188:191], 0
	v_mfma_f32_16x16x32_bf16 v[20:23], v[150:153], v[196:199], 0
	v_mfma_f32_16x16x32_bf16 v[16:19], v[158:161], v[196:199], 0
	v_mfma_f32_16x16x32_bf16 v[0:3], v[158:161], v[204:207], 0
	v_mfma_f32_16x16x32_bf16 v[4:7], v[150:153], v[204:207], 0
	s_setprio 0
	s_setprio 1
	v_mfma_f32_16x16x32_bf16 v[52:55], v[154:157], v[184:187], v[52:55]
	v_mfma_f32_16x16x32_bf16 v[48:51], v[162:165], v[184:187], v[48:51]
	v_mfma_f32_16x16x32_bf16 v[32:35], v[162:165], v[192:195], v[32:35]
	v_mfma_f32_16x16x32_bf16 v[36:39], v[154:157], v[192:195], v[36:39]
	v_mfma_f32_16x16x32_bf16 v[20:23], v[154:157], v[200:203], v[20:23]
	v_mfma_f32_16x16x32_bf16 v[16:19], v[162:165], v[200:203], v[16:19]
	v_mfma_f32_16x16x32_bf16 v[0:3], v[162:165], v[208:211], v[0:3]
	v_mfma_f32_16x16x32_bf16 v[4:7], v[154:157], v[208:211], v[4:7]
	s_setprio 0
	s_barrier
	s_add_i32 s16, 0, 0x18000
	v_add_u32_e32 v128, s16, v174
	s_add_i32 s17, 0, 0x1c000
	ds_read_b128 v[134:137], v128
	ds_read_b128 v[138:141], v128 offset:1024
	ds_read_b128 v[142:145], v180
	ds_read_b128 v[146:149], v180 offset:1024
	v_add_u32_e32 v128, s17, v174
	ds_read_b128 v[150:153], v128
	ds_read_b128 v[154:157], v128 offset:1024
	ds_read_b128 v[158:161], v181
	ds_read_b128 v[162:165], v181 offset:1024
	s_add_u32 s50, s34, 0x100000
	v_mov_b32_e32 v128, v172
	s_mov_b32 m0, s89
	ds_read_b128 v[166:169], v179 offset:32768
	ds_read_b128 v[184:187], v179 offset:33792
	ds_read_b128 v[188:191], v179 offset:34816
	ds_read_b128 v[192:195], v179 offset:35840
	ds_read_b128 v[196:199], v179 offset:36864
	ds_read_b128 v[200:203], v179 offset:37888
	ds_read_b128 v[204:207], v179 offset:38912
	ds_read_b128 v[208:211], v179 offset:39936
	s_addc_u32 s51, s35, 0
	s_nop 0
	global_load_lds_dwordx4 v128, s[50:51]
	v_mov_b32_e32 v128, v173
	s_mov_b32 m0, s90
	s_nop 0
	global_load_lds_dwordx4 v128, s[50:51]
	s_waitcnt vmcnt(8)
	s_waitcnt lgkmcnt(0)
	s_barrier
	s_setprio 1
	s_waitcnt lgkmcnt(0)
	v_mfma_f32_16x16x32_bf16 v[124:127], v[134:137], v[166:169], v[124:127]
	v_mfma_f32_16x16x32_bf16 v[120:123], v[142:145], v[166:169], v[120:123]
	v_mfma_f32_16x16x32_bf16 v[104:107], v[142:145], v[188:191], v[104:107]
	v_mfma_f32_16x16x32_bf16 v[108:111], v[134:137], v[188:191], v[108:111]
	v_mfma_f32_16x16x32_bf16 v[92:95], v[134:137], v[196:199], v[92:95]
	v_mfma_f32_16x16x32_bf16 v[88:91], v[142:145], v[196:199], v[88:91]
	v_mfma_f32_16x16x32_bf16 v[72:75], v[142:145], v[204:207], v[72:75]
	v_mfma_f32_16x16x32_bf16 v[76:79], v[134:137], v[204:207], v[76:79]
	s_setprio 0
	s_setprio 1
	v_mfma_f32_16x16x32_bf16 v[124:127], v[138:141], v[184:187], v[124:127]
	v_mfma_f32_16x16x32_bf16 v[120:123], v[146:149], v[184:187], v[120:123]
	v_mfma_f32_16x16x32_bf16 v[104:107], v[146:149], v[192:195], v[104:107]
	v_mfma_f32_16x16x32_bf16 v[108:111], v[138:141], v[192:195], v[108:111]
	v_mfma_f32_16x16x32_bf16 v[92:95], v[138:141], v[200:203], v[92:95]
	v_mfma_f32_16x16x32_bf16 v[88:91], v[146:149], v[200:203], v[88:91]
	v_mfma_f32_16x16x32_bf16 v[72:75], v[146:149], v[208:211], v[72:75]
	v_mfma_f32_16x16x32_bf16 v[76:79], v[138:141], v[208:211], v[76:79]
	s_setprio 0
	s_setprio 1
	v_mfma_f32_16x16x32_bf16 v[116:119], v[150:153], v[166:169], v[116:119]
	v_mfma_f32_16x16x32_bf16 v[112:115], v[158:161], v[166:169], v[112:115]
	v_mfma_f32_16x16x32_bf16 v[96:99], v[158:161], v[188:191], v[96:99]
	v_mfma_f32_16x16x32_bf16 v[100:103], v[150:153], v[188:191], v[100:103]
	v_mfma_f32_16x16x32_bf16 v[84:87], v[150:153], v[196:199], v[84:87]
	v_mfma_f32_16x16x32_bf16 v[80:83], v[158:161], v[196:199], v[80:83]
	v_mfma_f32_16x16x32_bf16 v[64:67], v[158:161], v[204:207], v[64:67]
	v_mfma_f32_16x16x32_bf16 v[68:71], v[150:153], v[204:207], v[68:71]
	s_setprio 0
	s_setprio 1
	v_mfma_f32_16x16x32_bf16 v[116:119], v[154:157], v[184:187], v[116:119]
	v_mfma_f32_16x16x32_bf16 v[112:115], v[162:165], v[184:187], v[112:115]
	v_mfma_f32_16x16x32_bf16 v[96:99], v[162:165], v[192:195], v[96:99]
	v_mfma_f32_16x16x32_bf16 v[100:103], v[154:157], v[192:195], v[100:103]
	v_mfma_f32_16x16x32_bf16 v[84:87], v[154:157], v[200:203], v[84:87]
	v_mfma_f32_16x16x32_bf16 v[80:83], v[162:165], v[200:203], v[80:83]
	v_mfma_f32_16x16x32_bf16 v[64:67], v[162:165], v[208:211], v[64:67]
	v_mfma_f32_16x16x32_bf16 v[68:71], v[154:157], v[208:211], v[68:71]
	s_setprio 0
	s_barrier
; #define PG8_LDA(dst, b, h) do { if constexpr (FP8) { _Pragma("unroll") for (int m = 0; m < 4; ++m) dst##8[m] = PG8_LD8(PG8_SA(b, h), aoff, aoff1, m); } \
;         else { _Pragma("unroll") for (int m = 0; m < 4; ++m) _Pragma("unroll") for (int k = 0; k < 2; ++k) dst[m][k] = *(const LAS bf16x8*)(lds + PG8_SA(b, h) + (k ? aoff1 : aoff) + m * 2048); } } while (0)
; #define PG8_LDB(dst, b, h) do { if constexpr (FP8) { dst##8[0] = PG8_LD8(PG8_SB(b, h), boff, boff1, 0); dst##8[1] = PG8_LD8(PG8_SB(b, h), boff, boff1, 1); } \
;         else { _Pragma("unroll") for (int n = 0; n < 2; ++n) _Pragma("unroll") for (int k = 0; k < 2; ++k) dst[n][k] = *(const LAS bf16x8*)(lds + PG8_SB(b, h) + (k ? boff1 : boff) + n * 2048); } } while (0)
; #define PG8_WAIT_V(n) asm volatile("s_waitcnt vmcnt(" #n ")" ::: "memory")
; #define PG8_WAIT_L(n) asm volatile("s_waitcnt lgkmcnt(" #n ")" ::: "memory")
; #define PG8_BAR __builtin_amdgcn_s_barrier()
; #define PG8_SCHED __builtin_amdgcn_sched_barrier(0)
; #define PG8_S1 PG8_STAGE(PG8_SA(1, 1), a1 + hstepA, voffA)
; #define PG8_S4 do { PG8_STAGE(PG8_SB(1, 0), b3, voffB); PG8_STAGE(PG8_SB(1, 1), b3 + hstepB, voffB); PG8_STAGE(PG8_SA(1, 0), a3, voffA); } while (0)
; template <class Epi, class SchedT, bool ALIGN_EPI, bool SP2, bool FP8 = false>
; __device__ __forceinline__ void gemm_phase(LAS unsigned char* lds, const Gemm g, const SchedT& S, const Epi& E, const int wid) {
;     ...
;             PG8_LDB(B0, 0, 0); PG8_LDB(B1, 0, 1); PG8_SCHED; PG8_LDA(At, 0, 0); PG8_S1;
;             PG8_WAIT_V(8); PG8_WAIT_L(0); PG8_BAR; PG8_MMAP(0, 0, 0); PG8_BAR; PG8_SCHED;
;     ...
;             PG8_LDA(At, 1, 1); PG8_S4;
;             PG8_WAIT_V(8); PG8_WAIT_L(0); PG8_BAR; PG8_MMAP(1, 1, 1); PG8_BAR; PG8_SCHED;
	v_mov_b32_e32 v128, v172
	ds_read_b128 v[166:169], v179 offset:49152
	ds_read_b128 v[184:187], v179 offset:50176
	ds_read_b128 v[188:191], v179 offset:51200
	ds_read_b128 v[192:195], v179 offset:52224
	ds_read_b128 v[196:199], v179 offset:53248
	ds_read_b128 v[200:203], v179 offset:54272
	ds_read_b128 v[204:207], v179 offset:55296
	ds_read_b128 v[208:211], v179 offset:56320
	s_add_i32 s16, s16, s86
	v_lshl_add_u64 v[170:171], s[38:39], 0, v[128:129]
	v_lshl_add_u64 v[170:171], v[170:171], 0, s[8:9]
	s_mov_b32 m0, s16
	v_mov_b32_e32 v128, v173
	global_load_lds_dwordx4 v[170:171], off
	s_add_i32 m0, s16, 0x2000
	s_nop 0
	v_lshl_add_u64 v[170:171], s[38:39], 0, v[128:129]
	s_add_u32 s38, s38, 0x100080
	v_lshl_add_u64 v[170:171], v[170:171], 0, s[8:9]
	s_addc_u32 s39, s39, 0
	v_mov_b32_e32 v128, v172
	s_add_i32 s16, s17, s86
	global_load_lds_dwordx4 v[170:171], off
	s_mov_b32 m0, s16
	s_nop 0
	global_load_lds_dwordx4 v128, s[38:39]
	v_mov_b32_e32 v128, v173
	s_add_i32 m0, s16, 0x2000
	s_nop 0
	global_load_lds_dwordx4 v128, s[38:39]
	v_mov_b32_e32 v128, v172
	s_mov_b32 m0, s92
	v_lshl_add_u64 v[170:171], s[34:35], 0, v[128:129]
	v_lshl_add_u64 v[170:171], v[170:171], 0, s[8:9]
	v_mov_b32_e32 v128, v173
	global_load_lds_dwordx4 v[170:171], off
	s_mov_b32 m0, s93
	v_lshl_add_u64 v[170:171], s[34:35], 0, v[128:129]
	v_lshl_add_u64 v[170:171], v[170:171], 0, s[8:9]
	global_load_lds_dwordx4 v[170:171], off
	s_waitcnt vmcnt(8)
	s_waitcnt lgkmcnt(0)
	s_barrier
	s_setprio 1
	s_waitcnt lgkmcnt(0)
	v_mfma_f32_16x16x32_bf16 v[60:63], v[134:137], v[166:169], v[60:63]
	v_mfma_f32_16x16x32_bf16 v[56:59], v[142:145], v[166:169], v[56:59]
	v_mfma_f32_16x16x32_bf16 v[40:43], v[142:145], v[188:191], v[40:43]
	v_mfma_f32_16x16x32_bf16 v[44:47], v[134:137], v[188:191], v[44:47]
	v_mfma_f32_16x16x32_bf16 v[28:31], v[134:137], v[196:199], v[28:31]
	v_mfma_f32_16x16x32_bf16 v[24:27], v[142:145], v[196:199], v[24:27]
	v_mfma_f32_16x16x32_bf16 v[8:11], v[142:145], v[204:207], v[8:11]
	v_mfma_f32_16x16x32_bf16 v[12:15], v[134:137], v[204:207], v[12:15]
	s_setprio 0
	s_setprio 1
	v_mfma_f32_16x16x32_bf16 v[60:63], v[138:141], v[184:187], v[60:63]
	v_mfma_f32_16x16x32_bf16 v[56:59], v[146:149], v[184:187], v[56:59]
	v_mfma_f32_16x16x32_bf16 v[40:43], v[146:149], v[192:195], v[40:43]
	v_mfma_f32_16x16x32_bf16 v[44:47], v[138:141], v[192:195], v[44:47]
	v_mfma_f32_16x16x32_bf16 v[28:31], v[138:141], v[200:203], v[28:31]
	v_mfma_f32_16x16x32_bf16 v[24:27], v[146:149], v[200:203], v[24:27]
	v_mfma_f32_16x16x32_bf16 v[8:11], v[146:149], v[208:211], v[8:11]
	v_mfma_f32_16x16x32_bf16 v[12:15], v[138:141], v[208:211], v[12:15]
	s_setprio 0
	s_setprio 1
	v_mfma_f32_16x16x32_bf16 v[52:55], v[150:153], v[166:169], v[52:55]
	v_mfma_f32_16x16x32_bf16 v[48:51], v[158:161], v[166:169], v[48:51]
	v_mfma_f32_16x16x32_bf16 v[32:35], v[158:161], v[188:191], v[32:35]
	v_mfma_f32_16x16x32_bf16 v[36:39], v[150:153], v[188:191], v[36:39]
	v_mfma_f32_16x16x32_bf16 v[20:23], v[150:153], v[196:199], v[20:23]
	v_mfma_f32_16x16x32_bf16 v[16:19], v[158:161], v[196:199], v[16:19]
	v_mfma_f32_16x16x32_bf16 v[0:3], v[158:161], v[204:207], v[0:3]
	v_mfma_f32_16x16x32_bf16 v[4:7], v[150:153], v[204:207], v[4:7]
	s_setprio 0
	s_setprio 1
	v_mfma_f32_16x16x32_bf16 v[52:55], v[154:157], v[184:187], v[52:55]
	v_mfma_f32_16x16x32_bf16 v[48:51], v[162:165], v[184:187], v[48:51]
	v_mfma_f32_16x16x32_bf16 v[32:35], v[162:165], v[192:195], v[32:35]
	v_mfma_f32_16x16x32_bf16 v[36:39], v[154:157], v[192:195], v[36:39]
	v_mfma_f32_16x16x32_bf16 v[20:23], v[154:157], v[200:203], v[20:23]
	v_mfma_f32_16x16x32_bf16 v[16:19], v[162:165], v[200:203], v[16:19]
	v_mfma_f32_16x16x32_bf16 v[0:3], v[162:165], v[208:211], v[0:3]
	v_mfma_f32_16x16x32_bf16 v[4:7], v[154:157], v[208:211], v[4:7]
	s_setprio 0
	s_barrier
	s_add_u32 s24, s24, 0x100
	s_addc_u32 s25, s25, 0
	s_add_u32 s46, s46, 0x100
	s_addc_u32 s47, s47, 0
	s_cmp_ge_i32 s48, s30
	s_mov_b32 s34, s48
	s_cbranch_scc1 .Lpeel_exit_lbb0_970
.LBB0_970:
	ds_read_b128 v[134:137], v175
	ds_read_b128 v[138:141], v175 offset:1024
	ds_read_b128 v[142:145], v176
	ds_read_b128 v[146:149], v176 offset:1024
	ds_read_b128 v[150:153], v177
	ds_read_b128 v[154:157], v177 offset:1024
	ds_read_b128 v[158:161], v178
	ds_read_b128 v[162:165], v178 offset:1024
	s_add_i32 s48, s34, 2
	s_add_u32 s16, s24, 0xfff00080
	s_addc_u32 s17, s25, -1
	s_cmp_eq_u32 s45, s34
	s_cselect_b32 s34, s15, s16
	s_cselect_b32 s35, s13, s17
	s_cselect_b32 s39, s27, s47
	s_cselect_b32 s38, s31, s46
	v_mov_b32_e32 v128, v172
	ds_read_b128 v[166:169], v179
	ds_read_b128 v[184:187], v179 offset:1024
	ds_read_b128 v[188:191], v179 offset:2048
	ds_read_b128 v[192:195], v179 offset:3072
	ds_read_b128 v[196:199], v179 offset:4096
	ds_read_b128 v[200:203], v179 offset:5120
	ds_read_b128 v[204:207], v179 offset:6144
	ds_read_b128 v[208:211], v179 offset:7168
	s_add_i32 m0, s87, 0xc000
	s_nop 0
	global_load_lds_dwordx4 v128, s[24:25]
	v_mov_b32_e32 v128, v173
	s_add_i32 m0, s87, 0xe000
	s_nop 0
	global_load_lds_dwordx4 v128, s[24:25]
	s_waitcnt vmcnt(8)
	s_waitcnt lgkmcnt(0)
	s_barrier
; #define PG8_LDA(dst, b, h) do { if constexpr (FP8) { _Pragma("unroll") for (int m = 0; m < 4; ++m) dst##8[m] = PG8_LD8(PG8_SA(b, h), aoff, aoff1, m); } \
;         else { _Pragma("unroll") for (int m = 0; m < 4; ++m) _Pragma("unroll") for (int k = 0; k < 2; ++k) dst[m][k] = *(const LAS bf16x8*)(lds + PG8_SA(b, h) + (k ? aoff1 : aoff) + m * 2048); } } while (0)
; #define PG8_WAIT_V(n) asm volatile("s_waitcnt vmcnt(" #n ")" ::: "memory")
; #define PG8_WAIT_L(n) asm volatile("s_waitcnt lgkmcnt(" #n ")" ::: "memory")
; #define PG8_BAR __builtin_amdgcn_s_barrier()
; #define PG8_SCHED __builtin_amdgcn_sched_barrier(0)
; #define PG8_S2 do { PG8_STAGE(PG8_SB(0, 0), b2, voffB); PG8_STAGE(PG8_SB(0, 1), b2 + hstepB, voffB); PG8_STAGE(PG8_SA(0, 0), a2, voffA); } while (0)
; template <class Epi, class SchedT, bool ALIGN_EPI, bool SP2, bool FP8 = false>
; __device__ __forceinline__ void gemm_phase(LAS unsigned char* lds, const Gemm g, const SchedT& S, const Epi& E, const int wid) {
;     ...
;             PG8_WAIT_V(8); PG8_WAIT_L(0); PG8_BAR; PG8_MMAP(0, 0, 0); PG8_BAR; PG8_SCHED;
;             PG8_LDA(At, 0, 1); PG8_S2;
;             PG8_WAIT_V(8); PG8_WAIT_L(0); PG8_BAR; PG8_MMAP(1, 0, 1); PG8_BAR; PG8_SCHED;
	s_setprio 1
	s_waitcnt lgkmcnt(0)
	v_mfma_f32_16x16x32_bf16 v[124:127], v[134:137], v[166:169], v[124:127]
	v_mfma_f32_16x16x32_bf16 v[120:123], v[142:145], v[166:169], v[120:123]
	v_mfma_f32_16x16x32_bf16 v[104:107], v[142:145], v[188:191], v[104:107]
	v_mfma_f32_16x16x32_bf16 v[108:111], v[134:137], v[188:191], v[108:111]
	v_mfma_f32_16x16x32_bf16 v[92:95], v[134:137], v[196:199], v[92:95]
	v_mfma_f32_16x16x32_bf16 v[88:91], v[142:145], v[196:199], v[88:91]
	v_mfma_f32_16x16x32_bf16 v[72:75], v[142:145], v[204:207], v[72:75]
	v_mfma_f32_16x16x32_bf16 v[76:79], v[134:137], v[204:207], v[76:79]
	s_setprio 0
	s_setprio 1
	v_mfma_f32_16x16x32_bf16 v[124:127], v[138:141], v[184:187], v[124:127]
	v_mfma_f32_16x16x32_bf16 v[120:123], v[146:149], v[184:187], v[120:123]
	v_mfma_f32_16x16x32_bf16 v[104:107], v[146:149], v[192:195], v[104:107]
	v_mfma_f32_16x16x32_bf16 v[108:111], v[138:141], v[192:195], v[108:111]
	v_mfma_f32_16x16x32_bf16 v[92:95], v[138:141], v[200:203], v[92:95]
	v_mfma_f32_16x16x32_bf16 v[88:91], v[146:149], v[200:203], v[88:91]
	v_mfma_f32_16x16x32_bf16 v[72:75], v[146:149], v[208:211], v[72:75]
	v_mfma_f32_16x16x32_bf16 v[76:79], v[138:141], v[208:211], v[76:79]
	s_setprio 0
	s_setprio 1
	v_mfma_f32_16x16x32_bf16 v[116:119], v[150:153], v[166:169], v[116:119]
	v_mfma_f32_16x16x32_bf16 v[112:115], v[158:161], v[166:169], v[112:115]
	v_mfma_f32_16x16x32_bf16 v[96:99], v[158:161], v[188:191], v[96:99]
	v_mfma_f32_16x16x32_bf16 v[100:103], v[150:153], v[188:191], v[100:103]
	v_mfma_f32_16x16x32_bf16 v[84:87], v[150:153], v[196:199], v[84:87]
	v_mfma_f32_16x16x32_bf16 v[80:83], v[158:161], v[196:199], v[80:83]
	v_mfma_f32_16x16x32_bf16 v[64:67], v[158:161], v[204:207], v[64:67]
	v_mfma_f32_16x16x32_bf16 v[68:71], v[150:153], v[204:207], v[68:71]
	s_setprio 0
	s_setprio 1
	v_mfma_f32_16x16x32_bf16 v[116:119], v[154:157], v[184:187], v[116:119]
	v_mfma_f32_16x16x32_bf16 v[112:115], v[162:165], v[184:187], v[112:115]
	v_mfma_f32_16x16x32_bf16 v[96:99], v[162:165], v[192:195], v[96:99]
	v_mfma_f32_16x16x32_bf16 v[100:103], v[154:157], v[192:195], v[100:103]
	v_mfma_f32_16x16x32_bf16 v[84:87], v[154:157], v[200:203], v[84:87]
	v_mfma_f32_16x16x32_bf16 v[80:83], v[162:165], v[200:203], v[80:83]
	v_mfma_f32_16x16x32_bf16 v[64:67], v[162:165], v[208:211], v[64:67]
	v_mfma_f32_16x16x32_bf16 v[68:71], v[154:157], v[208:211], v[68:71]
	s_setprio 0
	s_barrier
	v_mov_b32_e32 v128, v172
	s_add_i32 s16, s94, s86
	ds_read_b128 v[166:169], v179 offset:16384
	ds_read_b128 v[184:187], v179 offset:17408
	ds_read_b128 v[188:191], v179 offset:18432
	ds_read_b128 v[192:195], v179 offset:19456
	ds_read_b128 v[196:199], v179 offset:20480
	ds_read_b128 v[200:203], v179 offset:21504
	ds_read_b128 v[204:207], v179 offset:22528
	ds_read_b128 v[208:211], v179 offset:23552
	s_mov_b32 m0, s16
	s_nop 0
	global_load_lds_dwordx4 v128, s[38:39]
	v_mov_b32_e32 v128, v173
	s_add_i32 m0, s16, 0x2000
	s_add_u32 s50, s38, 0x100000
	global_load_lds_dwordx4 v128, s[38:39]
	s_addc_u32 s51, s39, 0
	v_mov_b32_e32 v128, v172
	s_add_i32 s16, s95, s86
	s_mov_b32 m0, s16
	s_nop 0
	global_load_lds_dwordx4 v128, s[50:51]
	v_mov_b32_e32 v128, v173
	s_add_i32 m0, s16, 0x2000
	s_nop 0
	global_load_lds_dwordx4 v128, s[50:51]
	v_mov_b32_e32 v128, v172
	s_mov_b32 m0, s87
	s_nop 0
	global_load_lds_dwordx4 v128, s[34:35]
	v_mov_b32_e32 v128, v173
	s_mov_b32 m0, s88
	s_nop 0
	global_load_lds_dwordx4 v128, s[34:35]
	s_waitcnt vmcnt(8)
	s_waitcnt lgkmcnt(0)
	s_barrier
	s_setprio 1
	s_waitcnt lgkmcnt(0)
	v_mfma_f32_16x16x32_bf16 v[60:63], v[134:137], v[166:169], v[60:63]
	v_mfma_f32_16x16x32_bf16 v[56:59], v[142:145], v[166:169], v[56:59]
	v_mfma_f32_16x16x32_bf16 v[40:43], v[142:145], v[188:191], v[40:43]
	v_mfma_f32_16x16x32_bf16 v[44:47], v[134:137], v[188:191], v[44:47]
	v_mfma_f32_16x16x32_bf16 v[28:31], v[134:137], v[196:199], v[28:31]
	v_mfma_f32_16x16x32_bf16 v[24:27], v[142:145], v[196:199], v[24:27]
	v_mfma_f32_16x16x32_bf16 v[8:11], v[142:145], v[204:207], v[8:11]
	v_mfma_f32_16x16x32_bf16 v[12:15], v[134:137], v[204:207], v[12:15]
	s_setprio 0
	s_setprio 1
	v_mfma_f32_16x16x32_bf16 v[60:63], v[138:141], v[184:187], v[60:63]
	v_mfma_f32_16x16x32_bf16 v[56:59], v[146:149], v[184:187], v[56:59]
	v_mfma_f32_16x16x32_bf16 v[40:43], v[146:149], v[192:195], v[40:43]
	v_mfma_f32_16x16x32_bf16 v[44:47], v[138:141], v[192:195], v[44:47]
	v_mfma_f32_16x16x32_bf16 v[28:31], v[138:141], v[200:203], v[28:31]
	v_mfma_f32_16x16x32_bf16 v[24:27], v[146:149], v[200:203], v[24:27]
	v_mfma_f32_16x16x32_bf16 v[8:11], v[146:149], v[208:211], v[8:11]
	v_mfma_f32_16x16x32_bf16 v[12:15], v[138:141], v[208:211], v[12:15]
	s_setprio 0
	s_setprio 1
	v_mfma_f32_16x16x32_bf16 v[52:55], v[150:153], v[166:169], v[52:55]
	v_mfma_f32_16x16x32_bf16 v[48:51], v[158:161], v[166:169], v[48:51]
	v_mfma_f32_16x16x32_bf16 v[32:35], v[158:161], v[188:191], v[32:35]
	v_mfma_f32_16x16x32_bf16 v[36:39], v[150:153], v[188:191], v[36:39]
	v_mfma_f32_16x16x32_bf16 v[20:23], v[150:153], v[196:199], v[20:23]
	v_mfma_f32_16x16x32_bf16 v[16:19], v[158:161], v[196:199], v[16:19]
	v_mfma_f32_16x16x32_bf16 v[0:3], v[158:161], v[204:207], v[0:3]
	v_mfma_f32_16x16x32_bf16 v[4:7], v[150:153], v[204:207], v[4:7]
	s_setprio 0
	s_setprio 1
	v_mfma_f32_16x16x32_bf16 v[52:55], v[154:157], v[184:187], v[52:55]
	v_mfma_f32_16x16x32_bf16 v[48:51], v[162:165], v[184:187], v[48:51]
	v_mfma_f32_16x16x32_bf16 v[32:35], v[162:165], v[192:195], v[32:35]
	v_mfma_f32_16x16x32_bf16 v[36:39], v[154:157], v[192:195], v[36:39]
	v_mfma_f32_16x16x32_bf16 v[20:23], v[154:157], v[200:203], v[20:23]
	v_mfma_f32_16x16x32_bf16 v[16:19], v[162:165], v[200:203], v[16:19]
	v_mfma_f32_16x16x32_bf16 v[0:3], v[162:165], v[208:211], v[0:3]
	v_mfma_f32_16x16x32_bf16 v[4:7], v[154:157], v[208:211], v[4:7]
	s_setprio 0
	s_barrier
; #define PG8_LDA(dst, b, h) do { if constexpr (FP8) { _Pragma("unroll") for (int m = 0; m < 4; ++m) dst##8[m] = PG8_LD8(PG8_SA(b, h), aoff, aoff1, m); } \
;         else { _Pragma("unroll") for (int m = 0; m < 4; ++m) _Pragma("unroll") for (int k = 0; k < 2; ++k) dst[m][k] = *(const LAS bf16x8*)(lds + PG8_SA(b, h) + (k ? aoff1 : aoff) + m * 2048); } } while (0)
; #define PG8_LDB(dst, b, h) do { if constexpr (FP8) { dst##8[0] = PG8_LD8(PG8_SB(b, h), boff, boff1, 0); dst##8[1] = PG8_LD8(PG8_SB(b, h), boff, boff1, 1); } \
;         else { _Pragma("unroll") for (int n = 0; n < 2; ++n) _Pragma("unroll") for (int k = 0; k < 2; ++k) dst[n][k] = *(const LAS bf16x8*)(lds + PG8_SB(b, h) + (k ? boff1 : boff) + n * 2048); } } while (0)
; #define PG8_WAIT_V(n) asm volatile("s_waitcnt vmcnt(" #n ")" ::: "memory")
; #define PG8_WAIT_L(n) asm volatile("s_waitcnt lgkmcnt(" #n ")" ::: "memory")
; #define PG8_BAR __builtin_amdgcn_s_barrier()
; #define PG8_SCHED __builtin_amdgcn_sched_barrier(0)
; #define PG8_S3 PG8_STAGE(PG8_SA(0, 1), a2 + hstepA, voffA)
; template <class Epi, class SchedT, bool ALIGN_EPI, bool SP2, bool FP8 = false>
; __device__ __forceinline__ void gemm_phase(LAS unsigned char* lds, const Gemm g, const SchedT& S, const Epi& E, const int wid) {
;     ...
;             PG8_LDB(B0, 1, 0); PG8_LDB(B1, 1, 1); PG8_SCHED; PG8_LDA(At, 1, 0); PG8_S3;
;             PG8_WAIT_V(8); PG8_WAIT_L(0); PG8_BAR; PG8_MMAP(0, 1, 0); PG8_BAR; PG8_SCHED;
	s_add_i32 s16, 0, 0x18000
	v_add_u32_e32 v128, s16, v174
	s_add_i32 s17, 0, 0x1c000
	ds_read_b128 v[134:137], v128
	ds_read_b128 v[138:141], v128 offset:1024
	ds_read_b128 v[142:145], v180
	ds_read_b128 v[146:149], v180 offset:1024
	v_add_u32_e32 v128, s17, v174
	ds_read_b128 v[150:153], v128
	ds_read_b128 v[154:157], v128 offset:1024
	ds_read_b128 v[158:161], v181
	ds_read_b128 v[162:165], v181 offset:1024
	s_add_u32 s50, s34, 0x100000
	v_mov_b32_e32 v128, v172
	s_mov_b32 m0, s89
	ds_read_b128 v[166:169], v179 offset:32768
	ds_read_b128 v[184:187], v179 offset:33792
	ds_read_b128 v[188:191], v179 offset:34816
	ds_read_b128 v[192:195], v179 offset:35840
	ds_read_b128 v[196:199], v179 offset:36864
	ds_read_b128 v[200:203], v179 offset:37888
	ds_read_b128 v[204:207], v179 offset:38912
	ds_read_b128 v[208:211], v179 offset:39936
	s_addc_u32 s51, s35, 0
	s_nop 0
	global_load_lds_dwordx4 v128, s[50:51]
	v_mov_b32_e32 v128, v173
	s_mov_b32 m0, s90
	s_nop 0
	global_load_lds_dwordx4 v128, s[50:51]
	s_waitcnt vmcnt(8)
	s_waitcnt lgkmcnt(0)
	s_barrier
	s_setprio 1
	s_waitcnt lgkmcnt(0)
	v_mfma_f32_16x16x32_bf16 v[124:127], v[134:137], v[166:169], v[124:127]
	v_mfma_f32_16x16x32_bf16 v[120:123], v[142:145], v[166:169], v[120:123]
	v_mfma_f32_16x16x32_bf16 v[104:107], v[142:145], v[188:191], v[104:107]
	v_mfma_f32_16x16x32_bf16 v[108:111], v[134:137], v[188:191], v[108:111]
	v_mfma_f32_16x16x32_bf16 v[92:95], v[134:137], v[196:199], v[92:95]
	v_mfma_f32_16x16x32_bf16 v[88:91], v[142:145], v[196:199], v[88:91]
	v_mfma_f32_16x16x32_bf16 v[72:75], v[142:145], v[204:207], v[72:75]
	v_mfma_f32_16x16x32_bf16 v[76:79], v[134:137], v[204:207], v[76:79]
	s_setprio 0
	s_setprio 1
	v_mfma_f32_16x16x32_bf16 v[124:127], v[138:141], v[184:187], v[124:127]
	v_mfma_f32_16x16x32_bf16 v[120:123], v[146:149], v[184:187], v[120:123]
	v_mfma_f32_16x16x32_bf16 v[104:107], v[146:149], v[192:195], v[104:107]
	v_mfma_f32_16x16x32_bf16 v[108:111], v[138:141], v[192:195], v[108:111]
	v_mfma_f32_16x16x32_bf16 v[92:95], v[138:141], v[200:203], v[92:95]
	v_mfma_f32_16x16x32_bf16 v[88:91], v[146:149], v[200:203], v[88:91]
	v_mfma_f32_16x16x32_bf16 v[72:75], v[146:149], v[208:211], v[72:75]
	v_mfma_f32_16x16x32_bf16 v[76:79], v[138:141], v[208:211], v[76:79]
	s_setprio 0
	s_setprio 1
	v_mfma_f32_16x16x32_bf16 v[116:119], v[150:153], v[166:169], v[116:119]
	v_mfma_f32_16x16x32_bf16 v[112:115], v[158:161], v[166:169], v[112:115]
	v_mfma_f32_16x16x32_bf16 v[96:99], v[158:161], v[188:191], v[96:99]
	v_mfma_f32_16x16x32_bf16 v[100:103], v[150:153], v[188:191], v[100:103]
	v_mfma_f32_16x16x32_bf16 v[84:87], v[150:153], v[196:199], v[84:87]
	v_mfma_f32_16x16x32_bf16 v[80:83], v[158:161], v[196:199], v[80:83]
	v_mfma_f32_16x16x32_bf16 v[64:67], v[158:161], v[204:207], v[64:67]
	v_mfma_f32_16x16x32_bf16 v[68:71], v[150:153], v[204:207], v[68:71]
	s_setprio 0
	s_setprio 1
	v_mfma_f32_16x16x32_bf16 v[116:119], v[154:157], v[184:187], v[116:119]
	v_mfma_f32_16x16x32_bf16 v[112:115], v[162:165], v[184:187], v[112:115]
	v_mfma_f32_16x16x32_bf16 v[96:99], v[162:165], v[192:195], v[96:99]
	v_mfma_f32_16x16x32_bf16 v[100:103], v[154:157], v[192:195], v[100:103]
	v_mfma_f32_16x16x32_bf16 v[84:87], v[154:157], v[200:203], v[84:87]
	v_mfma_f32_16x16x32_bf16 v[80:83], v[162:165], v[200:203], v[80:83]
	v_mfma_f32_16x16x32_bf16 v[64:67], v[162:165], v[208:211], v[64:67]
	v_mfma_f32_16x16x32_bf16 v[68:71], v[154:157], v[208:211], v[68:71]
	s_setprio 0
	s_barrier
; #define PG8_STAGE(bufoff, gbase, voff) do { _Pragma("unroll") for (int _i = 0; _i < 2; ++_i) { unsigned vo_ = (voff)[_i]; asm volatile("" : "+v"(vo_));     \
;         __builtin_amdgcn_global_load_lds((const unsigned*)((const char*)(gbase) + vo_), (LAS unsigned*)(lds + (bufoff) + ldsw + _i * 8192), 16, 0, 0); } } while (0)
; #define PG8_LDA(dst, b, h) do { if constexpr (FP8) { _Pragma("unroll") for (int m = 0; m < 4; ++m) dst##8[m] = PG8_LD8(PG8_SA(b, h), aoff, aoff1, m); } \
;         else { _Pragma("unroll") for (int m = 0; m < 4; ++m) _Pragma("unroll") for (int k = 0; k < 2; ++k) dst[m][k] = *(const LAS bf16x8*)(lds + PG8_SA(b, h) + (k ? aoff1 : aoff) + m * 2048); } } while (0)
; template <class Epi, class SchedT, bool ALIGN_EPI, bool SP2, bool FP8 = false>
; __device__ __forceinline__ void gemm_phase(LAS unsigned char* lds, const Gemm g, const SchedT& S, const Epi& E, const int wid) {
;     ...
;             PG8_LDA(At, 1, 1); PG8_S4;
;             PG8_WAIT_V(8); PG8_WAIT_L(0); PG8_BAR; PG8_MMAP(1, 1, 1); PG8_BAR; PG8_SCHED;
;             } else {
;             PG8_LDB(B0, 0, 0); PG8_SCHED; PG8_LDA(At, 0, 0); PG8_STAGE(PG8_SA(1, 1), a1 + hstepA, voffA);
;             PG8_WAIT_L(8); PG8_BAR; PG8_WAIT_L(0); PG8_MMA(0, 0, At, B0); PG8_BAR; PG8_SCHED;
;             PG8_LDB(B1, 0, 1); PG8_STAGE(PG8_SB(0, 0), b2, voffB);
;             PG8_BAR; PG8_WAIT_L(0); PG8_MMA(0, 1, At, B1); PG8_BAR;
;             PG8_LDA(At, 0, 1); PG8_STAGE(PG8_SA(0, 0), a2, voffA);
;             PG8_BAR; PG8_WAIT_L(0); PG8_MMA(1, 0, At, B0); PG8_BAR; PG8_SCHED;
;             PG8_STAGE(PG8_SB(0, 1), b2 + hstepB, voffB);
;             PG8_WAIT_V(6); PG8_BAR; PG8_MMA(1, 1, At, B1); PG8_BAR;
;             PG8_LDB(B0, 1, 0); PG8_SCHED; PG8_LDA(At, 1, 0); PG8_STAGE(PG8_SA(0, 1), a2 + hstepA, voffA);
;             PG8_WAIT_L(8); PG8_BAR; PG8_WAIT_L(0); PG8_MMA(0, 0, At, B0); PG8_BAR; PG8_SCHED;
;             PG8_LDB(B1, 1, 1); PG8_STAGE(PG8_SB(1, 0), b3, voffB);
;             PG8_BAR; PG8_WAIT_L(0); PG8_MMA(0, 1, At, B1); PG8_BAR;
;             PG8_LDA(At, 1, 1); PG8_STAGE(PG8_SA(1, 0), a3, voffA);
;             PG8_BAR; PG8_WAIT_L(0); PG8_MMA(1, 0, At, B0); PG8_BAR; PG8_SCHED;
;             PG8_STAGE(PG8_SB(1, 1), b3 + hstepB, voffB);
;             PG8_WAIT_V(6); PG8_BAR; PG8_MMA(1, 1, At, B1); PG8_BAR;
;             }
;         }
;         if constexpr (ALIGN_EPI) { if (wr == 0) PG8_BAR; }
	v_mov_b32_e32 v128, v172
	ds_read_b128 v[166:169], v179 offset:49152
	ds_read_b128 v[184:187], v179 offset:50176
	ds_read_b128 v[188:191], v179 offset:51200
	ds_read_b128 v[192:195], v179 offset:52224
	ds_read_b128 v[196:199], v179 offset:53248
	ds_read_b128 v[200:203], v179 offset:54272
	ds_read_b128 v[204:207], v179 offset:55296
	ds_read_b128 v[208:211], v179 offset:56320
	s_add_i32 s16, s16, s86
	v_lshl_add_u64 v[170:171], s[38:39], 0, v[128:129]
	v_lshl_add_u64 v[170:171], v[170:171], 0, s[8:9]
	s_mov_b32 m0, s16
	v_mov_b32_e32 v128, v173
	global_load_lds_dwordx4 v[170:171], off
	s_add_i32 m0, s16, 0x2000
	s_nop 0
	v_lshl_add_u64 v[170:171], s[38:39], 0, v[128:129]
	s_add_u32 s38, s38, 0x100080
	v_lshl_add_u64 v[170:171], v[170:171], 0, s[8:9]
	s_addc_u32 s39, s39, 0
	v_mov_b32_e32 v128, v172
	s_add_i32 s16, s17, s86
	global_load_lds_dwordx4 v[170:171], off
	s_mov_b32 m0, s16
	s_nop 0
	global_load_lds_dwordx4 v128, s[38:39]
	v_mov_b32_e32 v128, v173
	s_add_i32 m0, s16, 0x2000
	s_nop 0
	global_load_lds_dwordx4 v128, s[38:39]
	v_mov_b32_e32 v128, v172
	s_mov_b32 m0, s92
	v_lshl_add_u64 v[170:171], s[34:35], 0, v[128:129]
	v_lshl_add_u64 v[170:171], v[170:171], 0, s[8:9]
	v_mov_b32_e32 v128, v173
	global_load_lds_dwordx4 v[170:171], off
	s_mov_b32 m0, s93
	v_lshl_add_u64 v[170:171], s[34:35], 0, v[128:129]
	v_lshl_add_u64 v[170:171], v[170:171], 0, s[8:9]
	global_load_lds_dwordx4 v[170:171], off
	s_waitcnt vmcnt(8)
	s_waitcnt lgkmcnt(0)
	s_barrier
	s_setprio 1
	s_waitcnt lgkmcnt(0)
	v_mfma_f32_16x16x32_bf16 v[60:63], v[134:137], v[166:169], v[60:63]
	v_mfma_f32_16x16x32_bf16 v[56:59], v[142:145], v[166:169], v[56:59]
	v_mfma_f32_16x16x32_bf16 v[40:43], v[142:145], v[188:191], v[40:43]
	v_mfma_f32_16x16x32_bf16 v[44:47], v[134:137], v[188:191], v[44:47]
	v_mfma_f32_16x16x32_bf16 v[28:31], v[134:137], v[196:199], v[28:31]
	v_mfma_f32_16x16x32_bf16 v[24:27], v[142:145], v[196:199], v[24:27]
	v_mfma_f32_16x16x32_bf16 v[8:11], v[142:145], v[204:207], v[8:11]
	v_mfma_f32_16x16x32_bf16 v[12:15], v[134:137], v[204:207], v[12:15]
	s_setprio 0
	s_setprio 1
	v_mfma_f32_16x16x32_bf16 v[60:63], v[138:141], v[184:187], v[60:63]
	v_mfma_f32_16x16x32_bf16 v[56:59], v[146:149], v[184:187], v[56:59]
	v_mfma_f32_16x16x32_bf16 v[40:43], v[146:149], v[192:195], v[40:43]
	v_mfma_f32_16x16x32_bf16 v[44:47], v[138:141], v[192:195], v[44:47]
	v_mfma_f32_16x16x32_bf16 v[28:31], v[138:141], v[200:203], v[28:31]
	v_mfma_f32_16x16x32_bf16 v[24:27], v[146:149], v[200:203], v[24:27]
	v_mfma_f32_16x16x32_bf16 v[8:11], v[146:149], v[208:211], v[8:11]
	v_mfma_f32_16x16x32_bf16 v[12:15], v[138:141], v[208:211], v[12:15]
	s_setprio 0
	s_setprio 1
	v_mfma_f32_16x16x32_bf16 v[52:55], v[150:153], v[166:169], v[52:55]
	v_mfma_f32_16x16x32_bf16 v[48:51], v[158:161], v[166:169], v[48:51]
	v_mfma_f32_16x16x32_bf16 v[32:35], v[158:161], v[188:191], v[32:35]
	v_mfma_f32_16x16x32_bf16 v[36:39], v[150:153], v[188:191], v[36:39]
	v_mfma_f32_16x16x32_bf16 v[20:23], v[150:153], v[196:199], v[20:23]
	v_mfma_f32_16x16x32_bf16 v[16:19], v[158:161], v[196:199], v[16:19]
	v_mfma_f32_16x16x32_bf16 v[0:3], v[158:161], v[204:207], v[0:3]
	v_mfma_f32_16x16x32_bf16 v[4:7], v[150:153], v[204:207], v[4:7]
	s_setprio 0
	s_setprio 1
	v_mfma_f32_16x16x32_bf16 v[52:55], v[154:157], v[184:187], v[52:55]
	v_mfma_f32_16x16x32_bf16 v[48:51], v[162:165], v[184:187], v[48:51]
	v_mfma_f32_16x16x32_bf16 v[32:35], v[162:165], v[192:195], v[32:35]
	v_mfma_f32_16x16x32_bf16 v[36:39], v[154:157], v[192:195], v[36:39]
	v_mfma_f32_16x16x32_bf16 v[20:23], v[154:157], v[200:203], v[20:23]
	v_mfma_f32_16x16x32_bf16 v[16:19], v[162:165], v[200:203], v[16:19]
	v_mfma_f32_16x16x32_bf16 v[0:3], v[162:165], v[208:211], v[0:3]
	v_mfma_f32_16x16x32_bf16 v[4:7], v[154:157], v[208:211], v[4:7]
	s_setprio 0
	s_barrier
	s_add_u32 s24, s24, 0x100
	s_addc_u32 s25, s25, 0
	s_add_u32 s46, s46, 0x100
	s_addc_u32 s47, s47, 0
	s_cmp_ge_i32 s48, s30
	s_mov_b32 s34, s48
	s_cbranch_scc0 .LBB0_970
.Lpeel_exit_lbb0_970:
	s_and_b64 vcc, exec, s[96:97]
	s_cbranch_vccz .LBB0_973
.LBB0_972:
	s_barrier
